# VALU instruction selection: 100 adjacent v_mov_b32 pairs in the mixer items merged into v_pk_mov_b32 (same code size)
# speedup vs baseline: 1.0071x; 1.0071x over previous
.LBB0_252:
	s_and_b64 vcc, exec, s[6:7]
	s_cbranch_vccz .LBB0_245
	v_readlane_b32 s6, v255, 40
	s_add_i32 s20, s2, s6
	s_mul_hi_i32 s7, s2, 0x4400
	s_mul_i32 s6, s2, 0x4400
	s_add_i32 s70, s2, 0x200
	s_lshl_b64 s[8:9], s[6:7], 1
	s_add_u32 s54, s85, s8
	s_addc_u32 s55, s39, s9
	s_lshl_b64 s[6:7], s[6:7], 2
	v_readlane_b32 s8, v255, 43
	s_add_u32 s71, s8, s6
	v_readlane_b32 s6, v255, 44
	s_addc_u32 s34, s6, s7
	s_lshl_b64 s[6:7], s[2:3], 1
	v_readlane_b32 s8, v255, 45
	s_add_u32 s6, s8, s6
	v_readlane_b32 s8, v255, 46
	s_waitcnt vmcnt(0)
	v_mov_b32_e32 v36, v208
	s_addc_u32 s7, s8, s7
	v_readlane_b32 s16, v255, 29
	v_readfirstlane_b32 s8, v36
	s_ashr_i32 s12, s8, 6
	s_load_dwordx4 s[8:11], s[0:1], 0x50
	s_mul_i32 s13, s16, 0x4800
	v_cvt_f32_i32_e32 v0, s2
	v_mov_b32_e32 v2, 0xc0447cbd
	v_lshlrev_b32_e32 v44, 3, v36
	s_waitcnt lgkmcnt(0)
	s_add_u32 s13, s8, s13
	s_mul_hi_i32 s8, s16, 0x4800
	s_addc_u32 s14, s9, s8
	s_mul_i32 s8, s16, 0x1800
	s_add_u32 s10, s10, s8
	s_mul_hi_i32 s8, s16, 0x1800
	s_addc_u32 s11, s11, s8
	s_lshl_b64 s[8:9], s[2:3], 2
	s_add_u32 s74, s13, s8
	s_addc_u32 s75, s14, s9
	s_add_u32 s78, s10, s8
	v_fmamk_f32 v37, v0, 0xbcc4df2d, v2
	v_mov_b32_e32 v2, 0x1000
	s_addc_u32 s79, s11, s9
	global_load_dword v38, v1, s[74:75]
	global_load_dword v40, v2, s[74:75] offset:2048
	global_load_dword v41, v211, s[74:75]
	global_load_dword v42, v1, s[78:79]
	s_load_dwordx2 s[82:83], s[0:1], 0x98
	v_or_b32_e32 v140, 1, v44
	v_or_b32_e32 v142, 2, v44
	v_or_b32_e32 v144, 3, v44
	v_or_b32_e32 v146, 4, v44
	v_or_b32_e32 v148, 5, v44
	v_or_b32_e32 v150, 6, v44
	v_or_b32_e32 v152, 7, v44
	v_and_b32_e32 v0, 63, v36
	v_lshlrev_b32_e32 v136, 2, v36
	v_cvt_f32_i32_e32 v138, v44
	v_cvt_f32_i32_e32 v141, v140
	v_cvt_f32_i32_e32 v143, v142
	v_cvt_f32_i32_e32 v145, v144
	v_cvt_f32_i32_e32 v147, v146
	v_cvt_f32_i32_e32 v149, v148
	v_cvt_f32_i32_e32 v151, v150
	v_cvt_f32_i32_e32 v153, v152
	v_and_b32_e32 v2, -8, v136
	v_cmp_eq_u32_e64 s[42:43], 0, v0
	s_lshl_b32 s3, s12, 2
	v_lshlrev_b32_e32 v0, 6, v36
	v_mov_b32_e32 v6, v1
	v_mov_b32_e32 v7, v1
	v_ashrrev_i32_e32 v45, 31, v44
	s_add_i32 s3, s3, 0
	v_add3_u32 v139, 0, v2, v0
	v_add3_u32 v154, s35, v2, v0
	v_mov_b32_e32 v0, v1
	v_pk_mov_b32 v[2:3], v[0:1], v[0:1] op_sel:[1,1]
	v_pk_mov_b32 v[4:5], v[0:1], v[0:1] op_sel:[1,1]
	v_mov_b64_e32 v[14:15], v[6:7]
	v_mov_b64_e32 v[22:23], v[6:7]
	v_lshl_add_u64 v[46:47], v[44:45], 2, s[94:95]
	s_mov_b32 s14, 0
	s_add_i32 s3, s3, 0x22000
	v_cmp_lt_i32_e64 s[44:45], 0, v36
	v_mov_b32_e32 v48, v44
	v_mov_b32_e32 v49, v1
	v_add_u32_e32 v137, 8, v44
	v_cmp_lt_i32_e64 s[46:47], -1, v36
	s_mov_b64 s[8:9], -1
	v_mov_b64_e32 v[12:13], v[4:5]
	v_mov_b64_e32 v[10:11], v[2:3]
	v_mov_b64_e32 v[8:9], v[0:1]
	v_mov_b64_e32 v[20:21], v[4:5]
	v_mov_b64_e32 v[18:19], v[2:3]
	v_mov_b64_e32 v[16:17], v[0:1]
	v_readlane_b32 s17, v255, 30
	s_waitcnt vmcnt(0)
	v_mov_b32_e32 v52, v40
	v_mov_b32_e32 v50, v41
	v_mov_b32_e32 v51, v41
	v_mov_b32_e32 v53, v40
	v_mov_b32_e32 v43, v42
	v_mov_b32_e32 v39, v38
	s_branch .LBB0_255

.LBB0_275:
	s_or_b64 exec, exec, s[10:11]
	s_add_i32 s77, 0, 0x22000
	v_mov_b32_e32 v0, s77
	s_waitcnt lgkmcnt(0)
	s_barrier
	ds_read_b128 v[28:31], v0
	v_mov_b32_e32 v0, s92
	ds_read_b128 v[32:35], v0
	s_waitcnt vmcnt(1)
	v_mov_b32_e32 v59, v58
	v_mov_b32_e32 v57, v56
	s_waitcnt lgkmcnt(1)
	v_add_f32_e32 v0, 0, v28
	v_add_f32_e32 v0, v0, v29
	v_add_f32_e32 v0, v0, v30
	v_add_f32_e32 v0, v0, v31
	s_waitcnt lgkmcnt(0)
	v_add_f32_e32 v0, v0, v32
	v_add_f32_e32 v0, v0, v33
	v_add_f32_e32 v0, v0, v34
	v_add_f32_e32 v0, v0, v35
	v_add_f32_e32 v0, 0x358637bd, v0
	v_mul_f32_e32 v28, 0x4f800000, v0
	v_cmp_gt_f32_e32 vcc, s23, v0
	s_waitcnt vmcnt(0)
	v_mov_b32_e32 v61, v60
	s_mov_b64 s[18:19], -1
	v_cndmask_b32_e32 v0, v0, v28, vcc
	v_sqrt_f32_e32 v28, v0
	s_nop 0
	v_add_u32_e32 v29, -1, v28
	v_fma_f32 v30, -v29, v28, v0
	v_cmp_ge_f32_e64 s[50:51], 0, v30
	v_add_u32_e32 v30, 1, v28
	s_nop 0
	v_cndmask_b32_e64 v29, v28, v29, s[50:51]
	v_fma_f32 v28, -v30, v28, v0
	v_cmp_lt_f32_e64 s[50:51], 0, v28
	s_nop 1
	v_cndmask_b32_e64 v28, v29, v30, s[50:51]
	v_mul_f32_e32 v29, 0x37800000, v28
	v_cndmask_b32_e32 v28, v28, v29, vcc
	v_cmp_class_f32_e32 vcc, v0, v210
	v_cmp_gt_i32_e64 s[50:51], s52, v137
	s_nop 0
	v_cndmask_b32_e32 v0, v28, v0, vcc
	v_div_scale_f32 v28, s[10:11], v0, v0, 1.0
	v_rcp_f32_e32 v29, v28
	s_mul_hi_i32 s10, s16, 0x8800
	s_mul_i32 s16, s16, 0x8800
	s_add_u32 s40, s85, s16
	v_fma_f32 v30, -v28, v29, 1.0
	v_fmac_f32_e32 v29, v30, v29
	v_div_scale_f32 v30, vcc, 1.0, v0, 1.0
	v_mul_f32_e32 v31, v30, v29
	v_fma_f32 v32, -v28, v31, v30
	v_fmac_f32_e32 v31, v32, v29
	v_fma_f32 v28, -v28, v31, v30
	v_div_fmas_f32 v28, v28, v29, v31
	v_div_fixup_f32 v0, v28, v0, 1.0
	v_mov_b32_e32 v29, v208
	v_mul_f32_e32 v28, v7, v0
	s_addc_u32 s41, s39, s10
	v_and_b32_e32 v0, 0xff, v29
	v_lshlrev_b32_e32 v30, 4, v29
	v_and_or_b32 v0, v30, s93, v0
	v_ashrrev_i32_e32 v30, 4, v0
	v_lshlrev_b32_e32 v30, 3, v30
	v_lshlrev_b32_e32 v0, 3, v0
	v_add3_u32 v55, 0, v30, v0
	ds_read_b64 v[32:33], v55
	ds_read_b64 v[34:35], v55 offset:2176
	ds_read_b64 v[62:63], v55 offset:4352
	ds_read_b64 v[64:65], v55 offset:6528
	ds_read_b64 v[66:67], v55 offset:8704
	ds_read_b64 v[68:69], v55 offset:10880
	ds_read_b64 v[70:71], v55 offset:13056
	ds_read_b64 v[72:73], v55 offset:15232
	ds_read_b64 v[74:75], v55 offset:17408
	ds_read_b64 v[76:77], v55 offset:19584
	ds_read_b64 v[78:79], v55 offset:21760
	ds_read_b64 v[80:81], v55 offset:23936
	ds_read_b64 v[82:83], v55 offset:26112
	ds_read_b64 v[84:85], v55 offset:28288
	ds_read_b64 v[86:87], v55 offset:30464
	ds_read_b64 v[88:89], v55 offset:32640
	s_waitcnt lgkmcnt(5)
	v_pk_add_f32 v[96:97], v[62:63], v[78:79]
	v_pk_add_f32 v[62:63], v[62:63], v[78:79] neg_lo:[0,1] neg_hi:[0,1]
	s_waitcnt lgkmcnt(2)
	v_pk_add_f32 v[106:107], v[68:69], v[84:85]
	s_waitcnt lgkmcnt(1)
	v_pk_add_f32 v[98:99], v[70:71], v[86:87]
	v_pk_add_f32 v[70:71], v[70:71], v[86:87] neg_lo:[0,1] neg_hi:[0,1]
	v_pk_add_f32 v[68:69], v[68:69], v[84:85] neg_lo:[0,1] neg_hi:[0,1]
	v_xor_b32_e32 v79, 0x80000000, v70
	v_mov_b32_e32 v78, v71
	v_pk_add_f32 v[104:105], v[34:35], v[76:77]
	v_pk_add_f32 v[70:71], v[62:63], v[78:79]
	v_pk_add_f32 v[34:35], v[34:35], v[76:77] neg_lo:[0,1] neg_hi:[0,1]
	v_xor_b32_e32 v77, 0x80000000, v68
	v_mov_b32_e32 v76, v69
	v_pk_add_f32 v[92:93], v[66:67], v[82:83]
	v_pk_add_f32 v[66:67], v[66:67], v[82:83] neg_lo:[0,1] neg_hi:[0,1]
	v_pk_mul_f32 v[82:83], v[70:71], s[24:25] op_sel_hi:[1,0]
	v_pk_add_f32 v[68:69], v[34:35], v[76:77]
	v_pk_fma_f32 v[86:87], v[70:71], s[24:25], v[82:83] op_sel:[0,0,1] op_sel_hi:[1,0,0]
	v_pk_fma_f32 v[70:71], v[70:71], s[24:25], v[82:83] op_sel_hi:[1,0,0] neg_lo:[0,0,1] neg_hi:[0,0,1]
	v_pk_mul_f32 v[82:83], v[68:69], s[30:31] op_sel_hi:[1,0]
	v_pk_add_f32 v[90:91], v[32:33], v[74:75]
	v_pk_fma_f32 v[84:85], v[68:69], s[22:23], v[82:83] op_sel:[0,0,1] op_sel_hi:[1,0,0]
	v_pk_fma_f32 v[68:69], v[68:69], s[22:23], v[82:83] op_sel:[0,0,1] op_sel_hi:[1,0,0] neg_lo:[0,0,1] neg_hi:[0,0,1]
	v_pk_add_f32 v[94:95], v[90:91], v[92:93]
	v_pk_add_f32 v[100:101], v[96:97], v[98:99]
	s_waitcnt lgkmcnt(0)
	v_pk_add_f32 v[112:113], v[72:73], v[88:89]
	v_mov_b32_e32 v85, v69
	v_pk_add_f32 v[68:69], v[72:73], v[88:89] neg_lo:[0,1] neg_hi:[0,1]
	v_pk_add_f32 v[88:89], v[90:91], v[92:93] neg_lo:[0,1] neg_hi:[0,1]
	v_pk_add_f32 v[90:91], v[96:97], v[98:99] neg_lo:[0,1] neg_hi:[0,1]
	v_pk_add_f32 v[96:97], v[104:105], v[106:107] neg_lo:[0,1] neg_hi:[0,1]
	v_pk_add_f32 v[110:111], v[64:65], v[80:81]
	v_pk_add_f32 v[64:65], v[64:65], v[80:81] neg_lo:[0,1] neg_hi:[0,1]
	v_xor_b32_e32 v73, 0x80000000, v68
	v_mov_b32_e32 v72, v69
	v_pk_mul_f32 v[98:99], v[96:97], s[24:25] op_sel_hi:[1,0]
	v_pk_add_f32 v[108:109], v[104:105], v[106:107]
	v_pk_add_f32 v[68:69], v[64:65], v[72:73]
	v_pk_fma_f32 v[104:105], v[96:97], s[24:25], v[98:99] op_sel:[0,0,1] op_sel_hi:[1,0,0]
	v_pk_fma_f32 v[96:97], v[96:97], s[24:25], v[98:99] op_sel_hi:[1,0,0] neg_lo:[0,0,1] neg_hi:[0,0,1]
	v_pk_mul_f32 v[80:81], v[68:69], s[22:23] op_sel_hi:[1,0]
	v_mov_b32_e32 v105, v97
	v_pk_add_f32 v[96:97], v[110:111], v[112:113] neg_lo:[0,1] neg_hi:[0,1]
	v_pk_add_f32 v[34:35], v[34:35], v[76:77] neg_lo:[0,1] neg_hi:[0,1]
	v_pk_fma_f32 v[82:83], v[68:69], s[30:31], v[80:81] op_sel:[0,0,1] op_sel_hi:[1,0,0]
	v_pk_fma_f32 v[68:69], v[68:69], s[30:31], v[80:81] op_sel:[0,0,1] op_sel_hi:[1,0,0] neg_lo:[0,0,1] neg_hi:[0,0,1]
	v_mul_f32_e32 v0, 0x3f3504f3, v96
	v_pk_add_f32 v[62:63], v[62:63], v[78:79] neg_lo:[0,1] neg_hi:[0,1]
	v_pk_mul_f32 v[76:77], v[34:35], s[22:23] op_sel_hi:[1,0]
	v_pk_add_f32 v[32:33], v[32:33], v[74:75] neg_lo:[0,1] neg_hi:[0,1]
	v_xor_b32_e32 v75, 0x80000000, v66
	v_mov_b32_e32 v74, v67
	v_mov_b32_e32 v83, v69
	v_pk_fma_f32 v[96:97], v[96:97], s[24:25], v[0:1] op_sel:[1,0,0] op_sel_hi:[1,1,0] neg_lo:[0,0,1] neg_hi:[0,0,1]
	v_mul_f32_e32 v0, 0x3f3504f3, v62
	v_pk_fma_f32 v[78:79], v[34:35], s[30:31], v[76:77] op_sel:[0,0,1] op_sel_hi:[1,0,0]
	v_pk_fma_f32 v[34:35], v[34:35], s[30:31], v[76:77] op_sel:[0,0,1] op_sel_hi:[1,0,0] neg_lo:[0,0,1] neg_hi:[0,0,1]
	v_pk_add_f32 v[66:67], v[32:33], v[74:75]
	v_mov_b32_e32 v87, v71
	v_pk_add_f32 v[68:69], v[84:85], v[82:83] neg_lo:[0,1] neg_hi:[0,1]
	v_xor_b32_e32 v93, 0x80000000, v90
	v_mov_b32_e32 v92, v91
	v_pk_add_f32 v[98:99], v[104:105], v[96:97] neg_lo:[0,1] neg_hi:[0,1]
	v_pk_fma_f32 v[62:63], v[62:63], s[24:25], v[0:1] op_sel:[1,0,0] op_sel_hi:[1,1,0] neg_lo:[0,0,1] neg_hi:[0,0,1]
	v_mov_b32_e32 v79, v35
	v_pk_add_f32 v[34:35], v[64:65], v[72:73] neg_lo:[0,1] neg_hi:[0,1]
	v_cvt_f32_ubyte0_e32 v0, v29
	v_pk_add_f32 v[70:71], v[66:67], v[86:87] neg_lo:[0,1] neg_hi:[0,1]
	v_xor_b32_e32 v81, 0x80000000, v68
	v_mov_b32_e32 v80, v69
	v_pk_add_f32 v[90:91], v[88:89], v[92:93] neg_lo:[0,1] neg_hi:[0,1]
	v_xor_b32_e32 v107, 0x80000000, v98
	v_mov_b32_e32 v106, v99
	v_pk_mul_f32 v[64:65], v[34:35], s[30:31]
	v_mul_f32_e32 v0, 0x39800000, v0
	v_pk_add_f32 v[68:69], v[70:71], v[80:81]
	v_pk_add_f32 v[98:99], v[90:91], v[106:107]
	v_pk_fma_f32 v[34:35], v[34:35], s[22:23], v[64:65] op_sel:[0,0,1] op_sel_hi:[1,0,0] neg_lo:[1,0,0] neg_hi:[1,0,0]
	v_pk_add_f32 v[70:71], v[70:71], v[80:81] neg_lo:[0,1] neg_hi:[0,1]
	v_pk_add_f32 v[80:81], v[90:91], v[106:107] neg_lo:[0,1] neg_hi:[0,1]
	v_sin_f32_e32 v90, v0
	v_pk_add_f32 v[102:103], v[94:95], v[100:101]
	v_pk_add_f32 v[64:65], v[78:79], v[34:35] neg_lo:[0,1] neg_hi:[0,1]
	v_pk_add_f32 v[34:35], v[78:79], v[34:35]
	v_pk_add_f32 v[78:79], v[94:95], v[100:101] neg_lo:[0,1] neg_hi:[0,1]
	v_cos_f32_e32 v100, v0
	v_pk_add_f32 v[32:33], v[32:33], v[74:75] neg_lo:[0,1] neg_hi:[0,1]
	v_pk_add_f32 v[66:67], v[66:67], v[86:87]
	v_pk_add_f32 v[82:83], v[84:85], v[82:83]
	v_pk_add_f32 v[74:75], v[32:33], v[62:63] neg_lo:[0,1] neg_hi:[0,1]
	v_xor_b32_e32 v73, 0x80000000, v64
	v_mov_b32_e32 v72, v65
	v_pk_add_f32 v[84:85], v[66:67], v[82:83] neg_lo:[0,1] neg_hi:[0,1]
	v_pk_add_f32 v[66:67], v[66:67], v[82:83]
	v_pk_add_f32 v[64:65], v[74:75], v[72:73]
	v_pk_add_f32 v[72:73], v[74:75], v[72:73] neg_lo:[0,1] neg_hi:[0,1]
	v_pk_mul_f32 v[74:75], v[90:91], v[66:67] op_sel:[0,1] op_sel_hi:[0,0]
	v_pk_add_f32 v[86:87], v[88:89], v[92:93]
	v_pk_add_f32 v[88:89], v[104:105], v[96:97]
	v_pk_fma_f32 v[82:83], v[100:101], v[66:67], v[74:75]
	v_pk_fma_f32 v[66:67], v[100:101], v[66:67], v[74:75] op_sel_hi:[0,1,1] neg_lo:[0,0,1] neg_hi:[0,0,1]
	v_mov_b32_e32 v101, v90
	v_pk_add_f32 v[92:93], v[86:87], v[88:89] neg_lo:[0,1] neg_hi:[0,1]
	v_mov_b32_e32 v83, v67
	v_pk_mul_f32 v[66:67], v[100:101], v[100:101]
	v_pk_add_f32 v[74:75], v[86:87], v[88:89]
	v_mul_f32_e32 v87, v100, v90
	v_mov_b32_e32 v86, v66
	v_pk_mov_b32 v[66:67], v[66:67], v[86:87] op_sel:[1,1]
	v_pk_add_f32 v[114:115], v[110:111], v[112:113]
	v_pk_add_f32 v[88:89], v[86:87], v[66:67] neg_lo:[0,1] neg_hi:[0,1]
	v_pk_add_f32 v[66:67], v[86:87], v[66:67]
	v_pk_add_f32 v[116:117], v[108:109], v[114:115]
	v_pk_add_f32 v[32:33], v[32:33], v[62:63]
	v_pk_mov_b32 v[86:87], v[88:89], v[66:67] op_sel:[0,1]
	v_pk_mul_f32 v[66:67], v[66:67], v[74:75] op_sel:[1,1] op_sel_hi:[1,0]
	v_mov_b32_e32 v91, v100
	v_pk_add_f32 v[30:31], v[102:103], v[116:117]
	v_pk_add_f32 v[76:77], v[102:103], v[116:117] neg_lo:[0,1] neg_hi:[0,1]
	v_pk_add_f32 v[62:63], v[32:33], v[34:35] neg_lo:[0,1] neg_hi:[0,1]
	v_pk_fma_f32 v[102:103], v[88:89], v[74:75], v[66:67]
	v_pk_fma_f32 v[66:67], v[88:89], v[74:75], v[66:67] op_sel_hi:[0,1,1] neg_lo:[0,0,1] neg_hi:[0,0,1]
	v_pk_add_f32 v[32:33], v[32:33], v[34:35]
	v_pk_mul_f32 v[34:35], v[90:91], v[86:87]
	v_mov_b32_e32 v103, v67
	v_pk_mul_f32 v[66:67], v[100:101], v[86:87]
	v_pk_add_f32 v[34:35], v[34:35], v[34:35] op_sel:[1,0] op_sel_hi:[1,0]
	v_pk_add_f32 v[66:67], v[66:67], v[66:67] op_sel:[0,1] op_sel_hi:[0,1] neg_lo:[0,1] neg_hi:[0,1]
	v_pk_mul_f32 v[34:35], v[34:35], v[32:33] op_sel:[0,1] op_sel_hi:[1,0]
	v_mul_f32_e32 v29, 4.0, v0
	v_pk_fma_f32 v[74:75], v[66:67], v[32:33], v[34:35]
	v_pk_fma_f32 v[32:33], v[66:67], v[32:33], v[34:35] neg_lo:[0,0,1] neg_hi:[0,0,1]
	v_pk_add_f32 v[94:95], v[108:109], v[114:115] neg_lo:[0,1] neg_hi:[0,1]
	v_sin_f32_e32 v32, v29
	v_cos_f32_e32 v34, v29
	v_xor_b32_e32 v97, 0x80000000, v94
	v_mov_b32_e32 v96, v95
	v_pk_add_f32 v[66:67], v[78:79], v[96:97]
	v_pk_add_f32 v[94:95], v[78:79], v[96:97] neg_lo:[0,1] neg_hi:[0,1]
	v_pk_mul_f32 v[78:79], v[32:33], v[66:67] op_sel:[0,1] op_sel_hi:[0,0]
	v_mov_b32_e32 v75, v33
	v_pk_fma_f32 v[86:87], v[34:35], v[66:67], v[78:79]
	v_pk_fma_f32 v[66:67], v[34:35], v[66:67], v[78:79] op_sel_hi:[0,1,1] neg_lo:[0,0,1] neg_hi:[0,0,1]
	v_mov_b32_e32 v35, v32
	v_mov_b32_e32 v33, v34
	v_mov_b32_e32 v87, v67
	v_pk_mul_f32 v[66:67], v[100:101], v[34:35]
	v_pk_mul_f32 v[32:33], v[100:101], v[32:33]
	v_pk_mov_b32 v[34:35], v[66:67], v[32:33] op_sel:[0,0]
	v_mov_b32_e32 v32, v67
	v_pk_add_f32 v[66:67], v[34:35], v[32:33] neg_lo:[0,1] neg_hi:[0,1]
	v_pk_add_f32 v[32:33], v[34:35], v[32:33]
	v_pk_mov_b32 v[34:35], v[66:67], v[32:33] op_sel:[0,1]
	v_pk_mul_f32 v[32:33], v[32:33], v[68:69] op_sel:[1,1] op_sel_hi:[1,0]
	v_mul_f32_e32 v29, 0x41000000, v0
	v_pk_fma_f32 v[78:79], v[66:67], v[68:69], v[32:33]
	v_pk_fma_f32 v[32:33], v[66:67], v[68:69], v[32:33] op_sel_hi:[0,1,1] neg_lo:[0,0,1] neg_hi:[0,0,1]
	v_mov_b32_e32 v79, v33
	v_pk_mul_f32 v[32:33], v[100:101], v[34:35]
	v_pk_mul_f32 v[34:35], v[90:91], v[34:35]
	v_pk_mov_b32 v[66:67], v[32:33], v[34:35] op_sel:[0,1]
	v_pk_mov_b32 v[32:33], v[32:33], v[34:35] op_sel:[1,0]
	v_sin_f32_e32 v88, v29
	v_pk_add_f32 v[34:35], v[66:67], v[32:33] neg_lo:[0,1] neg_hi:[0,1]
	v_pk_add_f32 v[32:33], v[66:67], v[32:33]
	v_pk_mov_b32 v[66:67], v[34:35], v[32:33] op_sel:[0,1]
	v_pk_mul_f32 v[32:33], v[32:33], v[98:99] op_sel:[1,1] op_sel_hi:[1,0]
	v_cos_f32_e32 v96, v29
	v_pk_fma_f32 v[68:69], v[34:35], v[98:99], v[32:33]
	v_pk_fma_f32 v[32:33], v[34:35], v[98:99], v[32:33] op_sel_hi:[0,1,1] neg_lo:[0,0,1] neg_hi:[0,0,1]
	v_pk_mul_f32 v[34:35], v[90:91], v[66:67]
	v_mov_b32_e32 v69, v33
	v_pk_mul_f32 v[32:33], v[100:101], v[66:67]
	v_pk_add_f32 v[34:35], v[34:35], v[34:35] op_sel:[1,0] op_sel_hi:[1,0]
	v_pk_add_f32 v[32:33], v[32:33], v[32:33] op_sel:[0,1] op_sel_hi:[0,1] neg_lo:[0,1] neg_hi:[0,1]
	v_pk_mul_f32 v[34:35], v[34:35], v[64:65] op_sel:[0,1] op_sel_hi:[1,0]
	v_mul_f32_e32 v0, 0x41400000, v0
	v_pk_fma_f32 v[66:67], v[32:33], v[64:65], v[34:35]
	v_pk_fma_f32 v[32:33], v[32:33], v[64:65], v[34:35] neg_lo:[0,0,1] neg_hi:[0,0,1]
	s_ashr_i32 s53, s52, 31
	v_mov_b32_e32 v67, v33
	v_pk_mul_f32 v[32:33], v[88:89], v[76:77] op_sel:[0,1] op_sel_hi:[0,0]
	v_pk_fma_f32 v[34:35], v[96:97], v[76:77], v[32:33]
	v_pk_fma_f32 v[32:33], v[96:97], v[76:77], v[32:33] op_sel_hi:[0,1,1] neg_lo:[0,0,1] neg_hi:[0,0,1]
	v_mov_b32_e32 v97, v88
	v_mov_b32_e32 v89, v96
	v_mov_b32_e32 v35, v33
	v_pk_mul_f32 v[32:33], v[100:101], v[96:97]
	v_pk_mul_f32 v[64:65], v[100:101], v[88:89]
	v_pk_mov_b32 v[76:77], v[32:33], v[64:65] op_sel:[0,0]
	v_mov_b32_e32 v64, v33
	v_pk_add_f32 v[32:33], v[76:77], v[64:65] neg_lo:[0,1] neg_hi:[0,1]
	v_pk_add_f32 v[64:65], v[76:77], v[64:65]
	v_pk_mov_b32 v[76:77], v[32:33], v[64:65] op_sel:[0,1]
	v_pk_mul_f32 v[64:65], v[64:65], v[84:85] op_sel:[1,1] op_sel_hi:[1,0]
	v_cos_f32_e32 v96, v0
	v_pk_fma_f32 v[88:89], v[32:33], v[84:85], v[64:65]
	v_pk_fma_f32 v[32:33], v[32:33], v[84:85], v[64:65] op_sel_hi:[0,1,1] neg_lo:[0,0,1] neg_hi:[0,0,1]
	v_mov_b32_e32 v89, v33
	v_pk_mul_f32 v[32:33], v[100:101], v[76:77]
	v_pk_mul_f32 v[64:65], v[90:91], v[76:77]
	v_pk_mov_b32 v[76:77], v[32:33], v[64:65] op_sel:[0,1]
	v_pk_mov_b32 v[32:33], v[32:33], v[64:65] op_sel:[1,0]
	s_mov_b32 s10, 0
	v_pk_add_f32 v[64:65], v[76:77], v[32:33] neg_lo:[0,1] neg_hi:[0,1]
	v_pk_add_f32 v[32:33], v[76:77], v[32:33]
	v_mov_b32_e32 v76, v64
	v_mov_b32_e32 v77, v33
	v_pk_mul_f32 v[32:33], v[32:33], v[92:93] op_sel:[1,1] op_sel_hi:[1,0]
	s_nop 0
	v_pk_fma_f32 v[84:85], v[64:65], v[92:93], v[32:33]
	v_pk_fma_f32 v[32:33], v[64:65], v[92:93], v[32:33] op_sel_hi:[0,1,1] neg_lo:[0,0,1] neg_hi:[0,0,1]
	v_pk_mul_f32 v[64:65], v[90:91], v[76:77]
	v_sin_f32_e32 v92, v0
	v_mov_b32_e32 v85, v33
	v_pk_mul_f32 v[32:33], v[100:101], v[76:77]
	v_pk_add_f32 v[64:65], v[64:65], v[64:65] op_sel:[1,0] op_sel_hi:[1,0]
	v_pk_add_f32 v[32:33], v[32:33], v[32:33] op_sel:[0,1] op_sel_hi:[0,1] neg_lo:[0,1] neg_hi:[0,1]
	v_pk_mul_f32 v[64:65], v[64:65], v[62:63] op_sel:[0,1] op_sel_hi:[1,0]
	v_mov_b32_e32 v0, v208
	v_pk_fma_f32 v[76:77], v[32:33], v[62:63], v[64:65]
	v_pk_fma_f32 v[32:33], v[32:33], v[62:63], v[64:65] neg_lo:[0,0,1] neg_hi:[0,0,1]
	s_nop 0
	v_mov_b32_e32 v77, v33
	v_pk_mul_f32 v[32:33], v[92:93], v[94:95] op_sel:[0,1] op_sel_hi:[0,0]
	v_pk_fma_f32 v[62:63], v[96:97], v[94:95], v[32:33]
	v_pk_fma_f32 v[32:33], v[96:97], v[94:95], v[32:33] op_sel_hi:[0,1,1] neg_lo:[0,0,1] neg_hi:[0,0,1]
	v_mov_b32_e32 v97, v92
	v_mov_b32_e32 v93, v96
	v_mov_b32_e32 v63, v33
	v_pk_mul_f32 v[32:33], v[100:101], v[96:97]
	v_pk_mul_f32 v[64:65], v[100:101], v[92:93]
	v_pk_mov_b32 v[92:93], v[32:33], v[64:65] op_sel:[0,0]
	v_mov_b32_e32 v64, v33
	v_pk_add_f32 v[32:33], v[92:93], v[64:65] neg_lo:[0,1] neg_hi:[0,1]
	v_pk_add_f32 v[64:65], v[92:93], v[64:65]
	v_mov_b32_e32 v92, v32
	v_mov_b32_e32 v93, v65
	v_pk_mul_f32 v[64:65], v[64:65], v[70:71] op_sel:[1,1] op_sel_hi:[1,0]
	s_nop 0
	v_pk_fma_f32 v[94:95], v[32:33], v[70:71], v[64:65]
	v_pk_fma_f32 v[32:33], v[32:33], v[70:71], v[64:65] op_sel_hi:[0,1,1] neg_lo:[0,0,1] neg_hi:[0,0,1]
	v_mov_b32_e32 v95, v33
	v_pk_mul_f32 v[32:33], v[100:101], v[92:93]
	v_pk_mul_f32 v[64:65], v[90:91], v[92:93]
	v_mov_b32_e32 v70, v32
	v_mov_b32_e32 v71, v65
	v_pk_mov_b32 v[32:33], v[32:33], v[64:65] op_sel:[1,0]
	s_nop 0
	v_pk_add_f32 v[64:65], v[70:71], v[32:33] neg_lo:[0,1] neg_hi:[0,1]
	v_pk_add_f32 v[32:33], v[70:71], v[32:33]
	v_mov_b32_e32 v70, v64
	v_mov_b32_e32 v71, v33
	v_pk_mul_f32 v[32:33], v[32:33], v[80:81] op_sel:[1,1] op_sel_hi:[1,0]
	s_nop 0
	v_pk_fma_f32 v[92:93], v[64:65], v[80:81], v[32:33]
	v_pk_fma_f32 v[32:33], v[64:65], v[80:81], v[32:33] op_sel_hi:[0,1,1] neg_lo:[0,0,1] neg_hi:[0,0,1]
	v_pk_mul_f32 v[64:65], v[90:91], v[70:71]
	v_mov_b32_e32 v93, v33
	v_pk_mul_f32 v[32:33], v[100:101], v[70:71]
	v_pk_add_f32 v[64:65], v[64:65], v[64:65] op_sel:[1,0] op_sel_hi:[1,0]
	v_pk_add_f32 v[32:33], v[32:33], v[32:33] op_sel:[0,1] op_sel_hi:[0,1] neg_lo:[0,1] neg_hi:[0,1]
	v_pk_mul_f32 v[64:65], v[64:65], v[72:73] op_sel:[0,1] op_sel_hi:[1,0]
	s_nop 0
	v_pk_fma_f32 v[70:71], v[32:33], v[72:73], v[64:65]
	v_pk_fma_f32 v[32:33], v[32:33], v[72:73], v[64:65] neg_lo:[0,0,1] neg_hi:[0,0,1]
	s_nop 0
	v_mov_b32_e32 v71, v33
	ds_write_b64 v55, v[30:31]
	ds_write_b64 v55, v[82:83] offset:2176
	ds_write_b64 v55, v[102:103] offset:4352
	ds_write_b64 v55, v[74:75] offset:6528
	ds_write_b64 v55, v[86:87] offset:8704
	ds_write_b64 v55, v[78:79] offset:10880
	ds_write_b64 v55, v[68:69] offset:13056
	ds_write_b64 v55, v[66:67] offset:15232
	ds_write_b64 v55, v[34:35] offset:17408
	ds_write_b64 v55, v[88:89] offset:19584
	ds_write_b64 v55, v[84:85] offset:21760
	ds_write_b64 v55, v[76:77] offset:23936
	ds_write_b64 v55, v[62:63] offset:26112
	ds_write_b64 v55, v[94:95] offset:28288
	ds_write_b64 v55, v[92:93] offset:30464
	ds_write_b64 v55, v[70:71] offset:32640
	s_waitcnt lgkmcnt(0)
	s_barrier
	s_nop 0
	v_and_b32_e32 v29, 15, v0
	v_lshlrev_b32_e32 v0, 4, v0
	v_and_b32_e32 v0, 0xffffff00, v0
	v_ashrrev_i32_e32 v30, 1, v0
	v_add_u32_e32 v30, 0, v30
	v_lshlrev_b32_e32 v0, 3, v0
	v_lshlrev_b32_e32 v31, 3, v29
	v_add3_u32 v55, v30, v0, v31
	ds_read_b64 v[32:33], v55
	ds_read_b64 v[34:35], v55 offset:136
	ds_read_b64 v[62:63], v55 offset:272
	ds_read_b64 v[64:65], v55 offset:408
	ds_read_b64 v[66:67], v55 offset:544
	ds_read_b64 v[68:69], v55 offset:680
	ds_read_b64 v[70:71], v55 offset:1088
	ds_read_b64 v[72:73], v55 offset:1224
	ds_read_b64 v[74:75], v55 offset:1632
	ds_read_b64 v[76:77], v55 offset:1768
	ds_read_b64 v[78:79], v55 offset:816
	ds_read_b64 v[80:81], v55 offset:952
	ds_read_b64 v[82:83], v55 offset:1360
	ds_read_b64 v[84:85], v55 offset:1496
	ds_read_b64 v[86:87], v55 offset:1904
	ds_read_b64 v[88:89], v55 offset:2040
	s_waitcnt lgkmcnt(8)
	v_pk_add_f32 v[104:105], v[34:35], v[72:73]
	s_waitcnt lgkmcnt(6)
	v_pk_add_f32 v[92:93], v[66:67], v[74:75]
	v_pk_add_f32 v[106:107], v[68:69], v[76:77]
	v_pk_add_f32 v[66:67], v[66:67], v[74:75] neg_lo:[0,1] neg_hi:[0,1]
	s_waitcnt lgkmcnt(0)
	v_pk_add_f32 v[74:75], v[78:79], v[86:87] neg_lo:[0,1] neg_hi:[0,1]
	v_pk_add_f32 v[68:69], v[68:69], v[76:77] neg_lo:[0,1] neg_hi:[0,1]
	v_pk_add_f32 v[96:97], v[62:63], v[82:83]
	v_pk_add_f32 v[98:99], v[78:79], v[86:87]
	v_pk_add_f32 v[62:63], v[62:63], v[82:83] neg_lo:[0,1] neg_hi:[0,1]
	v_xor_b32_e32 v79, 0x80000000, v74
	v_mov_b32_e32 v78, v75
	v_pk_add_f32 v[34:35], v[34:35], v[72:73] neg_lo:[0,1] neg_hi:[0,1]
	v_xor_b32_e32 v73, 0x80000000, v68
	v_mov_b32_e32 v72, v69
	v_pk_add_f32 v[74:75], v[62:63], v[78:79]
	v_pk_add_f32 v[68:69], v[34:35], v[72:73]
	v_pk_mul_f32 v[82:83], v[74:75], s[24:25] op_sel_hi:[1,0]
	v_pk_mul_f32 v[76:77], v[68:69], s[30:31] op_sel_hi:[1,0]
	v_pk_add_f32 v[90:91], v[32:33], v[70:71]
	v_pk_fma_f32 v[86:87], v[74:75], s[24:25], v[82:83] op_sel:[0,0,1] op_sel_hi:[1,0,0]
	v_pk_fma_f32 v[74:75], v[74:75], s[24:25], v[82:83] op_sel_hi:[1,0,0] neg_lo:[0,0,1] neg_hi:[0,0,1]
	v_pk_fma_f32 v[82:83], v[68:69], s[22:23], v[76:77] op_sel:[0,0,1] op_sel_hi:[1,0,0]
	v_pk_fma_f32 v[68:69], v[68:69], s[22:23], v[76:77] op_sel:[0,0,1] op_sel_hi:[1,0,0] neg_lo:[0,0,1] neg_hi:[0,0,1]
	v_pk_add_f32 v[94:95], v[90:91], v[92:93]
	v_pk_add_f32 v[100:101], v[96:97], v[98:99]
	v_pk_add_f32 v[112:113], v[80:81], v[88:89]
	v_mov_b32_e32 v83, v69
	v_pk_add_f32 v[68:69], v[80:81], v[88:89] neg_lo:[0,1] neg_hi:[0,1]
	v_pk_add_f32 v[88:89], v[90:91], v[92:93] neg_lo:[0,1] neg_hi:[0,1]
	v_pk_add_f32 v[90:91], v[96:97], v[98:99] neg_lo:[0,1] neg_hi:[0,1]
	v_pk_add_f32 v[96:97], v[104:105], v[106:107] neg_lo:[0,1] neg_hi:[0,1]
	v_pk_add_f32 v[110:111], v[64:65], v[84:85]
	v_pk_add_f32 v[64:65], v[64:65], v[84:85] neg_lo:[0,1] neg_hi:[0,1]
	v_xor_b32_e32 v77, 0x80000000, v68
	v_mov_b32_e32 v76, v69
	v_pk_mul_f32 v[98:99], v[96:97], s[24:25] op_sel_hi:[1,0]
	v_pk_add_f32 v[108:109], v[104:105], v[106:107]
	v_pk_add_f32 v[68:69], v[64:65], v[76:77]
	v_pk_fma_f32 v[104:105], v[96:97], s[24:25], v[98:99] op_sel:[0,0,1] op_sel_hi:[1,0,0]
	v_pk_fma_f32 v[96:97], v[96:97], s[24:25], v[98:99] op_sel_hi:[1,0,0] neg_lo:[0,0,1] neg_hi:[0,0,1]
	v_pk_mul_f32 v[80:81], v[68:69], s[22:23] op_sel_hi:[1,0]
	v_mov_b32_e32 v105, v97
	v_pk_add_f32 v[96:97], v[110:111], v[112:113] neg_lo:[0,1] neg_hi:[0,1]
	v_pk_add_f32 v[34:35], v[34:35], v[72:73] neg_lo:[0,1] neg_hi:[0,1]
	v_pk_fma_f32 v[84:85], v[68:69], s[30:31], v[80:81] op_sel:[0,0,1] op_sel_hi:[1,0,0]
	v_pk_fma_f32 v[68:69], v[68:69], s[30:31], v[80:81] op_sel:[0,0,1] op_sel_hi:[1,0,0] neg_lo:[0,0,1] neg_hi:[0,0,1]
	v_mul_f32_e32 v0, 0x3f3504f3, v96
	v_pk_add_f32 v[62:63], v[62:63], v[78:79] neg_lo:[0,1] neg_hi:[0,1]
	v_pk_mul_f32 v[72:73], v[34:35], s[22:23] op_sel_hi:[1,0]
	v_pk_add_f32 v[32:33], v[32:33], v[70:71] neg_lo:[0,1] neg_hi:[0,1]
	v_xor_b32_e32 v71, 0x80000000, v66
	v_mov_b32_e32 v70, v67
	v_mov_b32_e32 v85, v69
	v_pk_fma_f32 v[96:97], v[96:97], s[24:25], v[0:1] op_sel:[1,0,0] op_sel_hi:[1,1,0] neg_lo:[0,0,1] neg_hi:[0,0,1]
	v_mul_f32_e32 v0, 0x3f3504f3, v62
	v_pk_fma_f32 v[78:79], v[34:35], s[30:31], v[72:73] op_sel:[0,0,1] op_sel_hi:[1,0,0]
	v_pk_fma_f32 v[34:35], v[34:35], s[30:31], v[72:73] op_sel:[0,0,1] op_sel_hi:[1,0,0] neg_lo:[0,0,1] neg_hi:[0,0,1]
	v_pk_add_f32 v[66:67], v[32:33], v[70:71]
	v_mov_b32_e32 v87, v75
	v_pk_add_f32 v[68:69], v[82:83], v[84:85] neg_lo:[0,1] neg_hi:[0,1]
	v_xor_b32_e32 v93, 0x80000000, v90
	v_mov_b32_e32 v92, v91
	v_pk_add_f32 v[98:99], v[104:105], v[96:97] neg_lo:[0,1] neg_hi:[0,1]
	v_pk_fma_f32 v[62:63], v[62:63], s[24:25], v[0:1] op_sel:[1,0,0] op_sel_hi:[1,1,0] neg_lo:[0,0,1] neg_hi:[0,0,1]
	v_mov_b32_e32 v79, v35
	v_pk_add_f32 v[34:35], v[64:65], v[76:77] neg_lo:[0,1] neg_hi:[0,1]
	v_cvt_f32_ubyte0_e32 v0, v29
	v_pk_add_f32 v[74:75], v[66:67], v[86:87] neg_lo:[0,1] neg_hi:[0,1]
	v_xor_b32_e32 v81, 0x80000000, v68
	v_mov_b32_e32 v80, v69
	v_pk_add_f32 v[90:91], v[88:89], v[92:93] neg_lo:[0,1] neg_hi:[0,1]
	v_xor_b32_e32 v107, 0x80000000, v98
	v_mov_b32_e32 v106, v99
	v_pk_mul_f32 v[64:65], v[34:35], s[30:31]
	v_mul_f32_e32 v0, 0x3b800000, v0
	v_pk_add_f32 v[68:69], v[74:75], v[80:81]
	v_pk_add_f32 v[98:99], v[90:91], v[106:107]
	v_pk_fma_f32 v[34:35], v[34:35], s[22:23], v[64:65] op_sel:[0,0,1] op_sel_hi:[1,0,0] neg_lo:[1,0,0] neg_hi:[1,0,0]
	v_pk_add_f32 v[74:75], v[74:75], v[80:81] neg_lo:[0,1] neg_hi:[0,1]
	v_pk_add_f32 v[80:81], v[90:91], v[106:107] neg_lo:[0,1] neg_hi:[0,1]
	v_sin_f32_e32 v90, v0
	v_pk_add_f32 v[102:103], v[94:95], v[100:101]
	v_pk_add_f32 v[64:65], v[78:79], v[34:35] neg_lo:[0,1] neg_hi:[0,1]
	v_pk_add_f32 v[34:35], v[78:79], v[34:35]
	v_pk_add_f32 v[78:79], v[94:95], v[100:101] neg_lo:[0,1] neg_hi:[0,1]
	v_cos_f32_e32 v100, v0
	v_pk_add_f32 v[32:33], v[32:33], v[70:71] neg_lo:[0,1] neg_hi:[0,1]
	v_pk_add_f32 v[66:67], v[66:67], v[86:87]
	v_pk_add_f32 v[82:83], v[82:83], v[84:85]
	v_pk_add_f32 v[70:71], v[32:33], v[62:63] neg_lo:[0,1] neg_hi:[0,1]
	v_xor_b32_e32 v73, 0x80000000, v64
	v_mov_b32_e32 v72, v65
	v_pk_add_f32 v[84:85], v[66:67], v[82:83] neg_lo:[0,1] neg_hi:[0,1]
	v_pk_add_f32 v[66:67], v[66:67], v[82:83]
	v_pk_add_f32 v[64:65], v[70:71], v[72:73]
	v_pk_add_f32 v[70:71], v[70:71], v[72:73] neg_lo:[0,1] neg_hi:[0,1]
	v_pk_mul_f32 v[72:73], v[90:91], v[66:67] op_sel:[0,1] op_sel_hi:[0,0]
	v_pk_add_f32 v[86:87], v[88:89], v[92:93]
	v_pk_add_f32 v[88:89], v[104:105], v[96:97]
	v_pk_fma_f32 v[82:83], v[100:101], v[66:67], v[72:73]
	v_pk_fma_f32 v[66:67], v[100:101], v[66:67], v[72:73] op_sel_hi:[0,1,1] neg_lo:[0,0,1] neg_hi:[0,0,1]
	v_mov_b32_e32 v101, v90
	v_pk_add_f32 v[92:93], v[86:87], v[88:89] neg_lo:[0,1] neg_hi:[0,1]
	v_mov_b32_e32 v83, v67
	v_pk_mul_f32 v[66:67], v[100:101], v[100:101]
	v_pk_add_f32 v[72:73], v[86:87], v[88:89]
	v_mul_f32_e32 v87, v100, v90
	v_mov_b32_e32 v86, v66
	v_pk_mov_b32 v[66:67], v[66:67], v[86:87] op_sel:[1,1]
	v_pk_add_f32 v[114:115], v[110:111], v[112:113]
	v_pk_add_f32 v[88:89], v[86:87], v[66:67] neg_lo:[0,1] neg_hi:[0,1]
	v_pk_add_f32 v[66:67], v[86:87], v[66:67]
	v_pk_add_f32 v[116:117], v[108:109], v[114:115]
	v_pk_add_f32 v[32:33], v[32:33], v[62:63]
	v_pk_mov_b32 v[86:87], v[88:89], v[66:67] op_sel:[0,1]
	v_pk_mul_f32 v[66:67], v[66:67], v[72:73] op_sel:[1,1] op_sel_hi:[1,0]
	v_mov_b32_e32 v91, v100
	v_pk_add_f32 v[30:31], v[102:103], v[116:117]
	v_pk_add_f32 v[76:77], v[102:103], v[116:117] neg_lo:[0,1] neg_hi:[0,1]
	v_pk_add_f32 v[62:63], v[32:33], v[34:35] neg_lo:[0,1] neg_hi:[0,1]
	v_pk_fma_f32 v[102:103], v[88:89], v[72:73], v[66:67]
	v_pk_fma_f32 v[66:67], v[88:89], v[72:73], v[66:67] op_sel_hi:[0,1,1] neg_lo:[0,0,1] neg_hi:[0,0,1]
	v_pk_add_f32 v[32:33], v[32:33], v[34:35]
	v_pk_mul_f32 v[34:35], v[90:91], v[86:87]
	v_mov_b32_e32 v103, v67
	v_pk_mul_f32 v[66:67], v[100:101], v[86:87]
	v_pk_add_f32 v[34:35], v[34:35], v[34:35] op_sel:[1,0] op_sel_hi:[1,0]
	v_pk_add_f32 v[66:67], v[66:67], v[66:67] op_sel:[0,1] op_sel_hi:[0,1] neg_lo:[0,1] neg_hi:[0,1]
	v_pk_mul_f32 v[34:35], v[34:35], v[32:33] op_sel:[0,1] op_sel_hi:[1,0]
	v_mul_f32_e32 v29, 4.0, v0
	v_pk_fma_f32 v[72:73], v[66:67], v[32:33], v[34:35]
	v_pk_fma_f32 v[32:33], v[66:67], v[32:33], v[34:35] neg_lo:[0,0,1] neg_hi:[0,0,1]
	v_pk_add_f32 v[94:95], v[108:109], v[114:115] neg_lo:[0,1] neg_hi:[0,1]
	v_sin_f32_e32 v32, v29
	v_cos_f32_e32 v34, v29
	v_xor_b32_e32 v97, 0x80000000, v94
	v_mov_b32_e32 v96, v95
	v_pk_add_f32 v[66:67], v[78:79], v[96:97]
	v_pk_add_f32 v[94:95], v[78:79], v[96:97] neg_lo:[0,1] neg_hi:[0,1]
	v_pk_mul_f32 v[78:79], v[32:33], v[66:67] op_sel:[0,1] op_sel_hi:[0,0]
	v_mov_b32_e32 v73, v33
	v_pk_fma_f32 v[86:87], v[34:35], v[66:67], v[78:79]
	v_pk_fma_f32 v[66:67], v[34:35], v[66:67], v[78:79] op_sel_hi:[0,1,1] neg_lo:[0,0,1] neg_hi:[0,0,1]
	v_mov_b32_e32 v35, v32
	v_mov_b32_e32 v33, v34
	v_mov_b32_e32 v87, v67
	v_pk_mul_f32 v[66:67], v[100:101], v[34:35]
	v_pk_mul_f32 v[32:33], v[100:101], v[32:33]
	v_pk_mov_b32 v[34:35], v[66:67], v[32:33] op_sel:[0,0]
	v_mov_b32_e32 v32, v67
	v_pk_add_f32 v[66:67], v[34:35], v[32:33] neg_lo:[0,1] neg_hi:[0,1]
	v_pk_add_f32 v[32:33], v[34:35], v[32:33]
	v_pk_mov_b32 v[34:35], v[66:67], v[32:33] op_sel:[0,1]
	v_pk_mul_f32 v[32:33], v[32:33], v[68:69] op_sel:[1,1] op_sel_hi:[1,0]
	v_mul_f32_e32 v29, 0x41000000, v0
	v_pk_fma_f32 v[78:79], v[66:67], v[68:69], v[32:33]
	v_pk_fma_f32 v[32:33], v[66:67], v[68:69], v[32:33] op_sel_hi:[0,1,1] neg_lo:[0,0,1] neg_hi:[0,0,1]
	v_mov_b32_e32 v79, v33
	v_pk_mul_f32 v[32:33], v[100:101], v[34:35]
	v_pk_mul_f32 v[34:35], v[90:91], v[34:35]
	v_pk_mov_b32 v[66:67], v[32:33], v[34:35] op_sel:[0,1]
	v_pk_mov_b32 v[32:33], v[32:33], v[34:35] op_sel:[1,0]
	v_sin_f32_e32 v88, v29
	v_pk_add_f32 v[34:35], v[66:67], v[32:33] neg_lo:[0,1] neg_hi:[0,1]
	v_pk_add_f32 v[32:33], v[66:67], v[32:33]
	v_pk_mov_b32 v[66:67], v[34:35], v[32:33] op_sel:[0,1]
	v_pk_mul_f32 v[32:33], v[32:33], v[98:99] op_sel:[1,1] op_sel_hi:[1,0]
	v_cos_f32_e32 v96, v29
	v_pk_fma_f32 v[68:69], v[34:35], v[98:99], v[32:33]
	v_pk_fma_f32 v[32:33], v[34:35], v[98:99], v[32:33] op_sel_hi:[0,1,1] neg_lo:[0,0,1] neg_hi:[0,0,1]
	v_pk_mul_f32 v[34:35], v[90:91], v[66:67]
	v_mov_b32_e32 v69, v33
	v_pk_mul_f32 v[32:33], v[100:101], v[66:67]
	v_pk_add_f32 v[34:35], v[34:35], v[34:35] op_sel:[1,0] op_sel_hi:[1,0]
	v_pk_add_f32 v[32:33], v[32:33], v[32:33] op_sel:[0,1] op_sel_hi:[0,1] neg_lo:[0,1] neg_hi:[0,1]
	v_pk_mul_f32 v[34:35], v[34:35], v[64:65] op_sel:[0,1] op_sel_hi:[1,0]
	v_mul_f32_e32 v0, 0x41400000, v0
	v_pk_fma_f32 v[66:67], v[32:33], v[64:65], v[34:35]
	v_pk_fma_f32 v[32:33], v[32:33], v[64:65], v[34:35] neg_lo:[0,0,1] neg_hi:[0,0,1]
	s_nop 0
	v_mov_b32_e32 v67, v33
	v_pk_mul_f32 v[32:33], v[88:89], v[76:77] op_sel:[0,1] op_sel_hi:[0,0]
	v_pk_fma_f32 v[34:35], v[96:97], v[76:77], v[32:33]
	v_pk_fma_f32 v[32:33], v[96:97], v[76:77], v[32:33] op_sel_hi:[0,1,1] neg_lo:[0,0,1] neg_hi:[0,0,1]
	v_mov_b32_e32 v97, v88
	v_mov_b32_e32 v89, v96
	v_mov_b32_e32 v35, v33
	v_pk_mul_f32 v[32:33], v[100:101], v[96:97]
	v_pk_mul_f32 v[64:65], v[100:101], v[88:89]
	v_pk_mov_b32 v[76:77], v[32:33], v[64:65] op_sel:[0,0]
	v_mov_b32_e32 v64, v33
	v_pk_add_f32 v[32:33], v[76:77], v[64:65] neg_lo:[0,1] neg_hi:[0,1]
	v_pk_add_f32 v[64:65], v[76:77], v[64:65]
	v_pk_mov_b32 v[76:77], v[32:33], v[64:65] op_sel:[0,1]
	v_pk_mul_f32 v[64:65], v[64:65], v[84:85] op_sel:[1,1] op_sel_hi:[1,0]
	v_cos_f32_e32 v96, v0
	v_pk_fma_f32 v[88:89], v[32:33], v[84:85], v[64:65]
	v_pk_fma_f32 v[32:33], v[32:33], v[84:85], v[64:65] op_sel_hi:[0,1,1] neg_lo:[0,0,1] neg_hi:[0,0,1]
	v_mov_b32_e32 v89, v33
	v_pk_mul_f32 v[32:33], v[100:101], v[76:77]
	v_pk_mul_f32 v[64:65], v[90:91], v[76:77]
	v_mov_b32_e32 v76, v32
	v_mov_b32_e32 v77, v65
	v_pk_mov_b32 v[32:33], v[32:33], v[64:65] op_sel:[1,0]
	s_nop 0
	v_pk_add_f32 v[64:65], v[76:77], v[32:33] neg_lo:[0,1] neg_hi:[0,1]
	v_pk_add_f32 v[32:33], v[76:77], v[32:33]
	v_mov_b32_e32 v76, v64
	v_mov_b32_e32 v77, v33
	v_pk_mul_f32 v[32:33], v[32:33], v[92:93] op_sel:[1,1] op_sel_hi:[1,0]
	s_nop 0
	v_pk_fma_f32 v[84:85], v[64:65], v[92:93], v[32:33]
	v_pk_fma_f32 v[32:33], v[64:65], v[92:93], v[32:33] op_sel_hi:[0,1,1] neg_lo:[0,0,1] neg_hi:[0,0,1]
	v_pk_mul_f32 v[64:65], v[90:91], v[76:77]
	v_sin_f32_e32 v92, v0
	v_mov_b32_e32 v85, v33
	v_pk_mul_f32 v[32:33], v[100:101], v[76:77]
	v_pk_add_f32 v[64:65], v[64:65], v[64:65] op_sel:[1,0] op_sel_hi:[1,0]
	v_pk_add_f32 v[32:33], v[32:33], v[32:33] op_sel:[0,1] op_sel_hi:[0,1] neg_lo:[0,1] neg_hi:[0,1]
	v_pk_mul_f32 v[64:65], v[64:65], v[62:63] op_sel:[0,1] op_sel_hi:[1,0]
	v_mov_b32_e32 v0, v208
	v_pk_fma_f32 v[76:77], v[32:33], v[62:63], v[64:65]
	v_pk_fma_f32 v[32:33], v[32:33], v[62:63], v[64:65] neg_lo:[0,0,1] neg_hi:[0,0,1]
	s_nop 0
	v_mov_b32_e32 v77, v33
	v_pk_mul_f32 v[32:33], v[92:93], v[94:95] op_sel:[0,1] op_sel_hi:[0,0]
	v_pk_fma_f32 v[62:63], v[96:97], v[94:95], v[32:33]
	v_pk_fma_f32 v[32:33], v[96:97], v[94:95], v[32:33] op_sel_hi:[0,1,1] neg_lo:[0,0,1] neg_hi:[0,0,1]
	v_mov_b32_e32 v97, v92
	v_mov_b32_e32 v93, v96
	v_mov_b32_e32 v63, v33
	v_pk_mul_f32 v[32:33], v[100:101], v[96:97]
	v_pk_mul_f32 v[64:65], v[100:101], v[92:93]
	v_pk_mov_b32 v[92:93], v[32:33], v[64:65] op_sel:[0,0]
	v_mov_b32_e32 v64, v33
	v_pk_add_f32 v[32:33], v[92:93], v[64:65] neg_lo:[0,1] neg_hi:[0,1]
	v_pk_add_f32 v[64:65], v[92:93], v[64:65]
	v_mov_b32_e32 v92, v32
	v_mov_b32_e32 v93, v65
	v_pk_mul_f32 v[64:65], v[64:65], v[74:75] op_sel:[1,1] op_sel_hi:[1,0]
	s_nop 0
	v_pk_fma_f32 v[94:95], v[32:33], v[74:75], v[64:65]
	v_pk_fma_f32 v[32:33], v[32:33], v[74:75], v[64:65] op_sel_hi:[0,1,1] neg_lo:[0,0,1] neg_hi:[0,0,1]
	v_mov_b32_e32 v95, v33
	v_pk_mul_f32 v[32:33], v[100:101], v[92:93]
	v_pk_mul_f32 v[64:65], v[90:91], v[92:93]
	v_mov_b32_e32 v74, v32
	v_mov_b32_e32 v75, v65
	v_pk_mov_b32 v[32:33], v[32:33], v[64:65] op_sel:[1,0]
	s_nop 0
	v_pk_add_f32 v[64:65], v[74:75], v[32:33] neg_lo:[0,1] neg_hi:[0,1]
	v_pk_add_f32 v[32:33], v[74:75], v[32:33]
	v_mov_b32_e32 v74, v64
	v_mov_b32_e32 v75, v33
	v_pk_mul_f32 v[32:33], v[32:33], v[80:81] op_sel:[1,1] op_sel_hi:[1,0]
	s_nop 0
	v_pk_fma_f32 v[92:93], v[64:65], v[80:81], v[32:33]
	v_pk_fma_f32 v[32:33], v[64:65], v[80:81], v[32:33] op_sel_hi:[0,1,1] neg_lo:[0,0,1] neg_hi:[0,0,1]
	v_pk_mul_f32 v[64:65], v[90:91], v[74:75]
	v_mov_b32_e32 v93, v33
	v_pk_mul_f32 v[32:33], v[100:101], v[74:75]
	v_pk_add_f32 v[64:65], v[64:65], v[64:65] op_sel:[1,0] op_sel_hi:[1,0]
	v_pk_add_f32 v[32:33], v[32:33], v[32:33] op_sel:[0,1] op_sel_hi:[0,1] neg_lo:[0,1] neg_hi:[0,1]
	v_pk_mul_f32 v[64:65], v[64:65], v[70:71] op_sel:[0,1] op_sel_hi:[1,0]
	s_nop 0
	v_pk_fma_f32 v[74:75], v[32:33], v[70:71], v[64:65]
	v_pk_fma_f32 v[32:33], v[32:33], v[70:71], v[64:65] neg_lo:[0,0,1] neg_hi:[0,0,1]
	s_nop 0
	v_mov_b32_e32 v75, v33
	ds_write2_b64 v55, v[30:31], v[82:83] offset1:17
	ds_write2_b64 v55, v[102:103], v[72:73] offset0:34 offset1:51
	ds_write2_b64 v55, v[86:87], v[78:79] offset0:68 offset1:85
	ds_write2_b64 v55, v[68:69], v[66:67] offset0:102 offset1:119
	ds_write2_b64 v55, v[34:35], v[88:89] offset0:136 offset1:153
	ds_write2_b64 v55, v[84:85], v[76:77] offset0:170 offset1:187
	ds_write2_b64 v55, v[62:63], v[94:95] offset0:204 offset1:221
	ds_write2_b64 v55, v[92:93], v[74:75] offset0:238 offset1:255
	s_waitcnt lgkmcnt(0)
	s_nop 0
	v_lshlrev_b32_e32 v29, 4, v0
	v_ashrrev_i32_e32 v29, 1, v29
	v_lshlrev_b32_e32 v0, 7, v0
	v_add3_u32 v29, 0, v29, v0
	ds_read_b64 v[30:31], v29
	ds_read_b64 v[32:33], v29 offset:8
	ds_read_b64 v[62:63], v29 offset:16
	ds_read_b64 v[64:65], v29 offset:24
	ds_read_b64 v[66:67], v29 offset:64
	ds_read_b64 v[68:69], v29 offset:72
	ds_read_b64 v[70:71], v29 offset:32
	ds_read_b64 v[72:73], v29 offset:40
	ds_read_b64 v[74:75], v29 offset:48
	ds_read_b64 v[76:77], v29 offset:56
	ds_read_b64 v[78:79], v29 offset:96
	ds_read_b64 v[80:81], v29 offset:104
	ds_read_b64 v[82:83], v29 offset:80
	ds_read_b64 v[84:85], v29 offset:88
	ds_read_b64 v[86:87], v29 offset:112
	ds_read_b64 v[88:89], v29 offset:120
	s_waitcnt lgkmcnt(10)
	v_pk_add_f32 v[34:35], v[30:31], v[66:67]
	v_pk_add_f32 v[30:31], v[30:31], v[66:67] neg_lo:[0,1] neg_hi:[0,1]
	s_waitcnt lgkmcnt(4)
	v_pk_add_f32 v[66:67], v[70:71], v[78:79]
	v_pk_add_f32 v[70:71], v[70:71], v[78:79] neg_lo:[0,1] neg_hi:[0,1]
	s_nop 0
	v_xor_b32_e32 v79, 0x80000000, v70
	v_mov_b32_e32 v78, v71
	v_pk_add_f32 v[70:71], v[34:35], v[66:67]
	v_pk_add_f32 v[34:35], v[34:35], v[66:67] neg_lo:[0,1] neg_hi:[0,1]
	v_pk_add_f32 v[66:67], v[30:31], v[78:79]
	v_pk_add_f32 v[30:31], v[30:31], v[78:79] neg_lo:[0,1] neg_hi:[0,1]
	v_pk_add_f32 v[78:79], v[32:33], v[68:69]
	v_pk_add_f32 v[32:33], v[32:33], v[68:69] neg_lo:[0,1] neg_hi:[0,1]
	v_pk_add_f32 v[68:69], v[72:73], v[80:81]
	v_pk_add_f32 v[72:73], v[72:73], v[80:81] neg_lo:[0,1] neg_hi:[0,1]
	s_nop 0
	v_xor_b32_e32 v81, 0x80000000, v72
	v_mov_b32_e32 v80, v73
	v_pk_add_f32 v[72:73], v[78:79], v[68:69]
	v_pk_add_f32 v[68:69], v[78:79], v[68:69] neg_lo:[0,1] neg_hi:[0,1]
	v_pk_add_f32 v[78:79], v[32:33], v[80:81]
	v_pk_add_f32 v[32:33], v[32:33], v[80:81] neg_lo:[0,1] neg_hi:[0,1]
	s_waitcnt lgkmcnt(2)
	v_pk_add_f32 v[80:81], v[62:63], v[82:83]
	v_pk_add_f32 v[62:63], v[62:63], v[82:83] neg_lo:[0,1] neg_hi:[0,1]
	s_waitcnt lgkmcnt(0)
	v_pk_add_f32 v[82:83], v[74:75], v[86:87]
	v_pk_add_f32 v[74:75], v[74:75], v[86:87] neg_lo:[0,1] neg_hi:[0,1]
	s_nop 0
	v_xor_b32_e32 v87, 0x80000000, v74
	v_mov_b32_e32 v86, v75
	v_pk_add_f32 v[74:75], v[80:81], v[82:83]
	v_pk_add_f32 v[80:81], v[80:81], v[82:83] neg_lo:[0,1] neg_hi:[0,1]
	v_pk_add_f32 v[82:83], v[62:63], v[86:87]
	v_pk_add_f32 v[62:63], v[62:63], v[86:87] neg_lo:[0,1] neg_hi:[0,1]
	v_pk_add_f32 v[86:87], v[64:65], v[84:85]
	v_pk_add_f32 v[64:65], v[64:65], v[84:85] neg_lo:[0,1] neg_hi:[0,1]
	v_pk_add_f32 v[84:85], v[76:77], v[88:89]
	v_pk_add_f32 v[76:77], v[76:77], v[88:89] neg_lo:[0,1] neg_hi:[0,1]
	v_mul_f32_e32 v0, 0x3f3504f3, v62
	v_xor_b32_e32 v89, 0x80000000, v76
	v_mov_b32_e32 v88, v77
	v_pk_add_f32 v[76:77], v[86:87], v[84:85]
	v_pk_add_f32 v[84:85], v[86:87], v[84:85] neg_lo:[0,1] neg_hi:[0,1]
	v_pk_add_f32 v[86:87], v[64:65], v[88:89]
	v_pk_add_f32 v[64:65], v[64:65], v[88:89] neg_lo:[0,1] neg_hi:[0,1]
	v_pk_mul_f32 v[88:89], v[78:79], s[30:31] op_sel_hi:[1,0]
	v_pk_fma_f32 v[62:63], v[62:63], s[24:25], v[0:1] op_sel:[1,0,0] op_sel_hi:[1,1,0] neg_lo:[0,0,1] neg_hi:[0,0,1]
	v_pk_fma_f32 v[90:91], v[78:79], s[22:23], v[88:89] op_sel:[0,0,1] op_sel_hi:[1,0,0]
	v_pk_fma_f32 v[78:79], v[78:79], s[22:23], v[88:89] op_sel:[0,0,1] op_sel_hi:[1,0,0] neg_lo:[0,0,1] neg_hi:[0,0,1]
	v_mul_f32_e32 v0, 0x3f3504f3, v84
	v_mov_b32_e32 v91, v79
	v_pk_mul_f32 v[78:79], v[68:69], s[24:25] op_sel_hi:[1,0]
	s_nop 0
	v_pk_fma_f32 v[88:89], v[68:69], s[24:25], v[78:79] op_sel:[0,0,1] op_sel_hi:[1,0,0]
	v_pk_fma_f32 v[68:69], v[68:69], s[24:25], v[78:79] op_sel_hi:[1,0,0] neg_lo:[0,0,1] neg_hi:[0,0,1]
	s_nop 0
	v_mov_b32_e32 v89, v69
	v_pk_mul_f32 v[68:69], v[32:33], s[22:23] op_sel_hi:[1,0]
	s_nop 0
	v_pk_fma_f32 v[78:79], v[32:33], s[30:31], v[68:69] op_sel:[0,0,1] op_sel_hi:[1,0,0]
	v_pk_fma_f32 v[32:33], v[32:33], s[30:31], v[68:69] op_sel:[0,0,1] op_sel_hi:[1,0,0] neg_lo:[0,0,1] neg_hi:[0,0,1]
	s_nop 0
	v_mov_b32_e32 v79, v33
	v_pk_mul_f32 v[32:33], v[82:83], s[24:25] op_sel_hi:[1,0]
	s_nop 0
	v_pk_fma_f32 v[68:69], v[82:83], s[24:25], v[32:33] op_sel:[0,0,1] op_sel_hi:[1,0,0]
	v_pk_fma_f32 v[32:33], v[82:83], s[24:25], v[32:33] op_sel_hi:[1,0,0] neg_lo:[0,0,1] neg_hi:[0,0,1]
	s_nop 0
	v_mov_b32_e32 v69, v33
	v_xor_b32_e32 v33, 0x80000000, v80
	v_mov_b32_e32 v32, v81
	v_pk_mul_f32 v[80:81], v[86:87], s[22:23] op_sel_hi:[1,0]
	s_nop 0
	v_pk_fma_f32 v[82:83], v[86:87], s[30:31], v[80:81] op_sel:[0,0,1] op_sel_hi:[1,0,0]
	v_pk_fma_f32 v[80:81], v[86:87], s[30:31], v[80:81] op_sel:[0,0,1] op_sel_hi:[1,0,0] neg_lo:[0,0,1] neg_hi:[0,0,1]
	s_nop 0
	v_mov_b32_e32 v83, v81
	v_pk_fma_f32 v[80:81], v[84:85], s[24:25], v[0:1] op_sel:[1,0,0] op_sel_hi:[1,1,0] neg_lo:[0,0,1] neg_hi:[0,0,1]
	v_pk_mul_f32 v[84:85], v[64:65], s[30:31]
	v_mul_f32_e32 v0, v7, v138
	v_pk_fma_f32 v[64:65], v[64:65], s[22:23], v[84:85] op_sel:[0,0,1] op_sel_hi:[1,0,0] neg_lo:[1,0,0] neg_hi:[1,0,0]
	v_pk_add_f32 v[84:85], v[70:71], v[74:75]
	v_pk_add_f32 v[70:71], v[70:71], v[74:75] neg_lo:[0,1] neg_hi:[0,1]
	v_pk_add_f32 v[74:75], v[72:73], v[76:77]
	v_pk_add_f32 v[72:73], v[72:73], v[76:77] neg_lo:[0,1] neg_hi:[0,1]
	s_nop 0
	v_xor_b32_e32 v77, 0x80000000, v72
	v_mov_b32_e32 v76, v73
	v_pk_add_f32 v[72:73], v[84:85], v[74:75]
	v_pk_add_f32 v[74:75], v[84:85], v[74:75] neg_lo:[0,1] neg_hi:[0,1]
	v_pk_add_f32 v[84:85], v[70:71], v[76:77]
	v_pk_add_f32 v[70:71], v[70:71], v[76:77] neg_lo:[0,1] neg_hi:[0,1]
	v_pk_add_f32 v[76:77], v[66:67], v[68:69]
	v_pk_add_f32 v[66:67], v[66:67], v[68:69] neg_lo:[0,1] neg_hi:[0,1]
	v_pk_add_f32 v[68:69], v[90:91], v[82:83]
	v_pk_add_f32 v[82:83], v[90:91], v[82:83] neg_lo:[0,1] neg_hi:[0,1]
	s_nop 0
	v_xor_b32_e32 v87, 0x80000000, v82
	v_mov_b32_e32 v86, v83
	v_pk_add_f32 v[82:83], v[76:77], v[68:69]
	v_pk_add_f32 v[68:69], v[76:77], v[68:69] neg_lo:[0,1] neg_hi:[0,1]
	v_pk_add_f32 v[76:77], v[66:67], v[86:87]
	v_pk_add_f32 v[66:67], v[66:67], v[86:87] neg_lo:[0,1] neg_hi:[0,1]
	v_pk_add_f32 v[86:87], v[34:35], v[32:33]
	v_pk_add_f32 v[32:33], v[34:35], v[32:33] neg_lo:[0,1] neg_hi:[0,1]
	v_pk_add_f32 v[34:35], v[88:89], v[80:81]
	v_pk_add_f32 v[80:81], v[88:89], v[80:81] neg_lo:[0,1] neg_hi:[0,1]
	s_nop 0
	v_xor_b32_e32 v89, 0x80000000, v80
	v_mov_b32_e32 v88, v81
	v_pk_add_f32 v[80:81], v[86:87], v[34:35]
	v_pk_add_f32 v[34:35], v[86:87], v[34:35] neg_lo:[0,1] neg_hi:[0,1]
	v_pk_add_f32 v[86:87], v[32:33], v[88:89]
	v_pk_add_f32 v[32:33], v[32:33], v[88:89] neg_lo:[0,1] neg_hi:[0,1]
	v_pk_add_f32 v[88:89], v[30:31], v[62:63]
	v_pk_add_f32 v[30:31], v[30:31], v[62:63] neg_lo:[0,1] neg_hi:[0,1]
	v_pk_add_f32 v[62:63], v[78:79], v[64:65]
	v_pk_add_f32 v[64:65], v[78:79], v[64:65] neg_lo:[0,1] neg_hi:[0,1]
	s_nop 0
	v_xor_b32_e32 v79, 0x80000000, v64
	v_mov_b32_e32 v78, v65
	v_pk_add_f32 v[64:65], v[88:89], v[62:63]
	v_pk_add_f32 v[62:63], v[88:89], v[62:63] neg_lo:[0,1] neg_hi:[0,1]
	v_pk_add_f32 v[88:89], v[30:31], v[78:79]
	v_pk_add_f32 v[30:31], v[30:31], v[78:79] neg_lo:[0,1] neg_hi:[0,1]
	ds_write2_b64 v29, v[72:73], v[82:83] offset1:1
	ds_write2_b64 v29, v[80:81], v[64:65] offset0:2 offset1:3
	ds_write2_b64 v29, v[84:85], v[76:77] offset0:4 offset1:5
	ds_write2_b64 v29, v[86:87], v[88:89] offset0:6 offset1:7
	ds_write2_b64 v29, v[74:75], v[68:69] offset0:8 offset1:9
	ds_write2_b64 v29, v[34:35], v[62:63] offset0:10 offset1:11
	ds_write2_b64 v29, v[70:71], v[66:67] offset0:12 offset1:13
	ds_write2_b64 v29, v[32:33], v[30:31] offset0:14 offset1:15
	v_cos_f32_e32 v30, v0
	v_sin_f32_e32 v32, v0
	v_add_u32_e32 v0, s52, v48
	v_ashrrev_i32_e32 v29, 4, v0
	v_lshlrev_b32_e32 v29, 3, v29
	v_lshlrev_b32_e32 v55, 3, v0
	v_add3_u32 v0, s35, v29, v55
	v_mul_f32_e32 v29, v7, v141
	v_cos_f32_e32 v31, v29
	v_sin_f32_e32 v33, v29
	v_add_u32_e32 v29, s52, v140
	v_ashrrev_i32_e32 v29, 4, v29
	v_lshlrev_b32_e32 v29, 3, v29
	v_add3_u32 v165, s35, v29, v55
	v_mul_f32_e32 v29, v7, v143
	v_cos_f32_e32 v34, v29
	v_sin_f32_e32 v62, v29
	v_add_u32_e32 v29, s52, v142
	v_ashrrev_i32_e32 v29, 4, v29
	v_lshlrev_b32_e32 v29, 3, v29
	v_add3_u32 v166, s35, v29, v55
	v_mul_f32_e32 v29, v7, v145
	v_cos_f32_e32 v35, v29
	v_sin_f32_e32 v63, v29
	v_add_u32_e32 v29, s52, v144
	v_ashrrev_i32_e32 v29, 4, v29
	v_lshlrev_b32_e32 v29, 3, v29
	v_add3_u32 v167, s35, v29, v55
	v_mul_f32_e32 v29, v7, v147
	v_cos_f32_e32 v64, v29
	v_sin_f32_e32 v66, v29
	v_add_u32_e32 v29, s52, v146
	v_ashrrev_i32_e32 v29, 4, v29
	v_lshlrev_b32_e32 v29, 3, v29
	v_add3_u32 v168, s35, v29, v55
	v_mul_f32_e32 v29, v7, v149
	v_cos_f32_e32 v65, v29
	v_sin_f32_e32 v67, v29
	v_add_u32_e32 v29, s52, v148
	v_ashrrev_i32_e32 v29, 4, v29
	v_lshlrev_b32_e32 v29, 3, v29
	v_add3_u32 v169, s35, v29, v55
	v_mul_f32_e32 v29, v7, v151
	v_mul_f32_e32 v7, v7, v153
	v_cos_f32_e32 v68, v29
	v_sin_f32_e32 v70, v29
	v_cos_f32_e32 v69, v7
	v_sin_f32_e32 v71, v7
	v_add_u32_e32 v29, s52, v150
	v_add_u32_e32 v7, s52, v152
	v_ashrrev_i32_e32 v29, 4, v29
	v_ashrrev_i32_e32 v7, 4, v7
	v_lshlrev_b32_e32 v29, 3, v29
	v_lshlrev_b32_e32 v7, 3, v7
	v_add3_u32 v174, s35, v29, v55
	v_add3_u32 v175, s35, v7, v55
	v_mov_b32_e32 v55, v54
	v_mov_b32_e32 v7, v6
	v_mov_b32_e32 v29, v28
	v_pk_mov_b32 v[72:73], v[30:31], v[30:31] op_sel:[0,0]
	v_pk_mov_b32 v[74:75], v[32:33], v[32:33] op_sel:[0,0]
	v_pk_mov_b32 v[76:77], v[30:31], v[30:31] op_sel:[1,1]
	v_pk_mov_b32 v[78:79], v[32:33], v[32:33] op_sel:[1,1]
	v_pk_mov_b32 v[80:81], v[34:35], v[34:35] op_sel:[0,0]
	v_pk_mov_b32 v[82:83], v[62:63], v[62:63] op_sel:[0,0]
	v_pk_mov_b32 v[84:85], v[34:35], v[34:35] op_sel:[1,1]
	v_pk_mov_b32 v[86:87], v[62:63], v[62:63] op_sel:[1,1]
	v_pk_mov_b32 v[88:89], v[64:65], v[64:65] op_sel:[0,0]
	v_pk_mov_b32 v[90:91], v[66:67], v[66:67] op_sel:[0,0]
	v_pk_mov_b32 v[92:93], v[64:65], v[64:65] op_sel:[1,1]
	v_pk_mov_b32 v[94:95], v[66:67], v[66:67] op_sel:[1,1]
	v_pk_mov_b32 v[96:97], v[68:69], v[68:69] op_sel:[0,0]
	v_pk_mov_b32 v[98:99], v[70:71], v[70:71] op_sel:[0,0]
	v_pk_mov_b32 v[100:101], v[68:69], v[68:69] op_sel:[1,1]
	v_pk_mov_b32 v[102:103], v[70:71], v[70:71] op_sel:[1,1]
	s_waitcnt lgkmcnt(0)
	s_barrier
	s_branch .LBB0_277

.LBB0_290:
	s_waitcnt vmcnt(0)
	v_mov_b32_e32 v4, v16
	v_mov_b32_e32 v5, v8
	v_pk_mov_b32 v[2:3], v[8:9], v[16:17] op_sel:[0,0]
	v_pk_mul_f32 v[4:5], v[74:75], v[4:5]
	ds_write_b64 v154, v[2:3]
	v_pk_fma_f32 v[24:25], v[72:73], v[8:9], v[4:5]
	v_pk_fma_f32 v[2:3], v[72:73], v[2:3], v[4:5] neg_lo:[0,0,1] neg_hi:[0,0,1]
	v_pk_mov_b32 v[4:5], v[16:17], v[8:9] op_sel:[1,1]
	v_mov_b32_e32 v25, v3
	v_pk_mov_b32 v[2:3], v[8:9], v[16:17] op_sel:[1,1]
	v_pk_mul_f32 v[4:5], v[78:79], v[4:5]
	ds_write_b64 v0, v[24:25]
	ds_write_b64 v154, v[2:3] offset:8
	v_pk_fma_f32 v[24:25], v[76:77], v[2:3], v[4:5]
	v_pk_fma_f32 v[2:3], v[76:77], v[2:3], v[4:5] neg_lo:[0,0,1] neg_hi:[0,0,1]
	v_pk_mov_b32 v[4:5], v[18:19], v[10:11] op_sel:[0,0]
	v_mov_b32_e32 v25, v3
	v_pk_mov_b32 v[2:3], v[10:11], v[18:19] op_sel:[0,0]
	v_pk_mul_f32 v[4:5], v[82:83], v[4:5]
	ds_write_b64 v165, v[24:25] offset:8
	ds_write_b64 v154, v[2:3] offset:16
	v_pk_fma_f32 v[24:25], v[80:81], v[10:11], v[4:5]
	v_pk_fma_f32 v[2:3], v[80:81], v[2:3], v[4:5] neg_lo:[0,0,1] neg_hi:[0,0,1]
	v_pk_mov_b32 v[4:5], v[18:19], v[10:11] op_sel:[1,1]
	v_mov_b32_e32 v25, v3
	v_pk_mov_b32 v[2:3], v[10:11], v[18:19] op_sel:[1,1]
	v_pk_mul_f32 v[4:5], v[86:87], v[4:5]
	ds_write_b64 v166, v[24:25] offset:16
	ds_write_b64 v154, v[2:3] offset:24
	v_pk_fma_f32 v[24:25], v[84:85], v[2:3], v[4:5]
	v_pk_fma_f32 v[2:3], v[84:85], v[2:3], v[4:5] neg_lo:[0,0,1] neg_hi:[0,0,1]
	v_pk_mov_b32 v[4:5], v[20:21], v[12:13] op_sel:[0,0]
	v_mov_b32_e32 v25, v3
	v_pk_mov_b32 v[2:3], v[12:13], v[20:21] op_sel:[0,0]
	v_pk_mul_f32 v[4:5], v[90:91], v[4:5]
	ds_write_b64 v167, v[24:25] offset:24
	ds_write_b64 v154, v[2:3] offset:32
	v_pk_fma_f32 v[24:25], v[88:89], v[12:13], v[4:5]
	v_pk_fma_f32 v[2:3], v[88:89], v[2:3], v[4:5] neg_lo:[0,0,1] neg_hi:[0,0,1]
	v_pk_mov_b32 v[4:5], v[20:21], v[12:13] op_sel:[1,1]
	v_mov_b32_e32 v25, v3
	v_pk_mov_b32 v[2:3], v[12:13], v[20:21] op_sel:[1,1]
	v_pk_mul_f32 v[4:5], v[94:95], v[4:5]
	ds_write_b64 v168, v[24:25] offset:32
	ds_write_b64 v154, v[2:3] offset:40
	v_pk_fma_f32 v[24:25], v[92:93], v[2:3], v[4:5]
	v_pk_fma_f32 v[2:3], v[92:93], v[2:3], v[4:5] neg_lo:[0,0,1] neg_hi:[0,0,1]
	v_pk_mov_b32 v[4:5], v[22:23], v[14:15] op_sel:[0,0]
	v_mov_b32_e32 v25, v3
	v_pk_mov_b32 v[2:3], v[14:15], v[22:23] op_sel:[0,0]
	v_pk_mul_f32 v[4:5], v[98:99], v[4:5]
	ds_write_b64 v169, v[24:25] offset:40
	ds_write_b64 v154, v[2:3] offset:48
	v_pk_fma_f32 v[24:25], v[96:97], v[14:15], v[4:5]
	v_pk_fma_f32 v[2:3], v[96:97], v[2:3], v[4:5] neg_lo:[0,0,1] neg_hi:[0,0,1]
	v_pk_mov_b32 v[4:5], v[22:23], v[14:15] op_sel:[1,1]
	s_lshl_b64 s[36:37], s[14:15], 1
	v_mov_b32_e32 v25, v3
	v_mov_b32_e32 v2, v15
	v_mov_b32_e32 v3, v23
	v_pk_mul_f32 v[4:5], v[102:103], v[4:5]
	s_add_u32 vcc_lo, s40, s36
	ds_write_b64 v174, v[24:25] offset:48
	ds_write_b64 v154, v[2:3] offset:56
	v_pk_fma_f32 v[24:25], v[100:101], v[2:3], v[4:5]
	v_pk_fma_f32 v[2:3], v[100:101], v[2:3], v[4:5] neg_lo:[0,0,1] neg_hi:[0,0,1]
	s_addc_u32 vcc_hi, s41, s37
	v_mov_b32_e32 v25, v3
	ds_write_b64 v175, v[24:25] offset:56
	v_lshl_add_u64 v[24:25], v[44:45], 1, vcc
	global_load_dwordx4 v[2:5], v[24:25], off
	v_mov_b32_e32 v161, 0
	v_mov_b32_e32 v162, 0
	s_and_saveexec_b64 s[88:89], s[44:45]
	s_cbranch_execz .LBB0_292
	v_lshl_add_u64 v[26:27], v[48:49], 1, vcc
	global_load_ushort v162, v[26:27], off offset:-2

.LBB0_299:
	s_or_b64 exec, exec, s[16:17]
	v_mov_b32_e32 v206, v208
	s_waitcnt lgkmcnt(0)
	s_barrier
	s_xor_b64 s[16:17], s[18:19], -1
	v_and_b32_e32 v104, 0xff, v206
	v_lshlrev_b32_e32 v105, 4, v206
	v_and_or_b32 v104, v105, s93, v104
	v_ashrrev_i32_e32 v105, 4, v104
	v_lshlrev_b32_e32 v105, 3, v105
	v_lshlrev_b32_e32 v104, 3, v104
	v_add3_u32 v207, s35, v105, v104
	ds_read_b64 v[106:107], v207
	ds_read_b64 v[108:109], v207 offset:2176
	ds_read_b64 v[110:111], v207 offset:4352
	ds_read_b64 v[112:113], v207 offset:6528
	ds_read_b64 v[114:115], v207 offset:8704
	ds_read_b64 v[116:117], v207 offset:10880
	ds_read_b64 v[118:119], v207 offset:13056
	ds_read_b64 v[120:121], v207 offset:15232
	ds_read_b64 v[122:123], v207 offset:17408
	ds_read_b64 v[124:125], v207 offset:19584
	ds_read_b64 v[126:127], v207 offset:21760
	ds_read_b64 v[128:129], v207 offset:23936
	ds_read_b64 v[130:131], v207 offset:26112
	ds_read_b64 v[132:133], v207 offset:28288
	ds_read_b64 v[134:135], v207 offset:30464
	ds_read_b64 v[176:177], v207 offset:32640
	s_waitcnt lgkmcnt(5)
	v_pk_add_f32 v[184:185], v[110:111], v[126:127]
	v_pk_add_f32 v[110:111], v[110:111], v[126:127] neg_lo:[0,1] neg_hi:[0,1]
	s_waitcnt lgkmcnt(2)
	v_pk_add_f32 v[194:195], v[116:117], v[132:133]
	s_waitcnt lgkmcnt(1)
	v_pk_add_f32 v[186:187], v[118:119], v[134:135]
	v_pk_add_f32 v[118:119], v[118:119], v[134:135] neg_lo:[0,1] neg_hi:[0,1]
	v_pk_add_f32 v[116:117], v[116:117], v[132:133] neg_lo:[0,1] neg_hi:[0,1]
	v_xor_b32_e32 v127, 0x80000000, v118
	v_mov_b32_e32 v126, v119
	v_pk_add_f32 v[192:193], v[108:109], v[124:125]
	v_pk_add_f32 v[118:119], v[110:111], v[126:127]
	v_pk_add_f32 v[108:109], v[108:109], v[124:125] neg_lo:[0,1] neg_hi:[0,1]
	v_xor_b32_e32 v125, 0x80000000, v116
	v_mov_b32_e32 v124, v117
	v_pk_add_f32 v[180:181], v[114:115], v[130:131]
	v_pk_add_f32 v[114:115], v[114:115], v[130:131] neg_lo:[0,1] neg_hi:[0,1]
	v_pk_mul_f32 v[130:131], v[118:119], s[24:25] op_sel_hi:[1,0]
	v_pk_add_f32 v[116:117], v[108:109], v[124:125]
	v_pk_fma_f32 v[134:135], v[118:119], s[24:25], v[130:131] op_sel:[0,0,1] op_sel_hi:[1,0,0]
	v_pk_fma_f32 v[118:119], v[118:119], s[24:25], v[130:131] op_sel_hi:[1,0,0] neg_lo:[0,0,1] neg_hi:[0,0,1]
	v_pk_mul_f32 v[130:131], v[116:117], s[30:31] op_sel_hi:[1,0]
	v_pk_add_f32 v[178:179], v[106:107], v[122:123]
	v_pk_fma_f32 v[132:133], v[116:117], s[22:23], v[130:131] op_sel:[0,0,1] op_sel_hi:[1,0,0]
	v_pk_fma_f32 v[116:117], v[116:117], s[22:23], v[130:131] op_sel:[0,0,1] op_sel_hi:[1,0,0] neg_lo:[0,0,1] neg_hi:[0,0,1]
	v_pk_add_f32 v[182:183], v[178:179], v[180:181]
	v_pk_add_f32 v[188:189], v[184:185], v[186:187]
	s_waitcnt lgkmcnt(0)
	v_pk_add_f32 v[200:201], v[120:121], v[176:177]
	v_mov_b32_e32 v133, v117
	v_pk_add_f32 v[116:117], v[120:121], v[176:177] neg_lo:[0,1] neg_hi:[0,1]
	v_pk_add_f32 v[176:177], v[178:179], v[180:181] neg_lo:[0,1] neg_hi:[0,1]
	v_pk_add_f32 v[178:179], v[184:185], v[186:187] neg_lo:[0,1] neg_hi:[0,1]
	v_pk_add_f32 v[184:185], v[192:193], v[194:195] neg_lo:[0,1] neg_hi:[0,1]
	v_pk_add_f32 v[198:199], v[112:113], v[128:129]
	v_pk_add_f32 v[112:113], v[112:113], v[128:129] neg_lo:[0,1] neg_hi:[0,1]
	v_xor_b32_e32 v121, 0x80000000, v116
	v_mov_b32_e32 v120, v117
	v_pk_mul_f32 v[186:187], v[184:185], s[24:25] op_sel_hi:[1,0]
	v_pk_add_f32 v[196:197], v[192:193], v[194:195]
	v_pk_add_f32 v[116:117], v[112:113], v[120:121]
	v_pk_fma_f32 v[192:193], v[184:185], s[24:25], v[186:187] op_sel:[0,0,1] op_sel_hi:[1,0,0]
	v_pk_fma_f32 v[184:185], v[184:185], s[24:25], v[186:187] op_sel_hi:[1,0,0] neg_lo:[0,0,1] neg_hi:[0,0,1]
	v_pk_mul_f32 v[128:129], v[116:117], s[22:23] op_sel_hi:[1,0]
	v_mov_b32_e32 v193, v185
	v_pk_add_f32 v[184:185], v[198:199], v[200:201] neg_lo:[0,1] neg_hi:[0,1]
	v_pk_fma_f32 v[130:131], v[116:117], s[30:31], v[128:129] op_sel:[0,0,1] op_sel_hi:[1,0,0]
	v_pk_fma_f32 v[116:117], v[116:117], s[30:31], v[128:129] op_sel:[0,0,1] op_sel_hi:[1,0,0] neg_lo:[0,0,1] neg_hi:[0,0,1]
	v_mul_f32_e32 v186, 0x3f3504f3, v184
	v_pk_add_f32 v[106:107], v[106:107], v[122:123] neg_lo:[0,1] neg_hi:[0,1]
	v_xor_b32_e32 v123, 0x80000000, v114
	v_mov_b32_e32 v122, v115
	v_mov_b32_e32 v131, v117
	v_pk_fma_f32 v[184:185], v[184:185], s[24:25], v[186:187] op_sel:[1,0,0] op_sel_hi:[1,1,0] neg_lo:[0,0,1] neg_hi:[0,0,1]
	v_pk_add_f32 v[108:109], v[108:109], v[124:125] neg_lo:[0,1] neg_hi:[0,1]
	v_pk_add_f32 v[114:115], v[106:107], v[122:123]
	v_mov_b32_e32 v135, v119
	v_pk_add_f32 v[116:117], v[132:133], v[130:131] neg_lo:[0,1] neg_hi:[0,1]
	v_xor_b32_e32 v181, 0x80000000, v178
	v_mov_b32_e32 v180, v179
	v_pk_add_f32 v[186:187], v[192:193], v[184:185] neg_lo:[0,1] neg_hi:[0,1]
	v_pk_mul_f32 v[124:125], v[108:109], s[22:23] op_sel_hi:[1,0]
	v_pk_add_f32 v[118:119], v[114:115], v[134:135] neg_lo:[0,1] neg_hi:[0,1]
	v_xor_b32_e32 v129, 0x80000000, v116
	v_mov_b32_e32 v128, v117
	v_pk_add_f32 v[178:179], v[176:177], v[180:181] neg_lo:[0,1] neg_hi:[0,1]
	v_xor_b32_e32 v195, 0x80000000, v186
	v_mov_b32_e32 v194, v187
	v_pk_add_f32 v[110:111], v[110:111], v[126:127] neg_lo:[0,1] neg_hi:[0,1]
	v_pk_fma_f32 v[126:127], v[108:109], s[30:31], v[124:125] op_sel:[0,0,1] op_sel_hi:[1,0,0]
	v_pk_fma_f32 v[108:109], v[108:109], s[30:31], v[124:125] op_sel:[0,0,1] op_sel_hi:[1,0,0] neg_lo:[0,0,1] neg_hi:[0,0,1]
	v_pk_add_f32 v[116:117], v[118:119], v[128:129]
	v_pk_add_f32 v[186:187], v[178:179], v[194:195]
	v_mov_b32_e32 v127, v109
	v_pk_add_f32 v[108:109], v[112:113], v[120:121] neg_lo:[0,1] neg_hi:[0,1]
	v_pk_add_f32 v[118:119], v[118:119], v[128:129] neg_lo:[0,1] neg_hi:[0,1]
	v_pk_add_f32 v[128:129], v[178:179], v[194:195] neg_lo:[0,1] neg_hi:[0,1]
	v_cvt_f32_ubyte0_e32 v178, v206
	v_pk_mul_f32 v[112:113], v[108:109], s[30:31]
	v_pk_add_f32 v[114:115], v[114:115], v[134:135]
	v_pk_add_f32 v[134:135], v[176:177], v[180:181]
	v_pk_add_f32 v[176:177], v[192:193], v[184:185]
	v_mul_f32_e32 v192, 0x39800000, v178
	v_pk_fma_f32 v[108:109], v[108:109], s[22:23], v[112:113] op_sel:[0,0,1] op_sel_hi:[1,0,0] neg_lo:[1,0,0] neg_hi:[1,0,0]
	v_sin_f32_e32 v178, v192
	v_pk_add_f32 v[190:191], v[182:183], v[188:189]
	v_pk_add_f32 v[106:107], v[106:107], v[122:123] neg_lo:[0,1] neg_hi:[0,1]
	v_mul_f32_e32 v122, 0x3f3504f3, v110
	v_pk_add_f32 v[112:113], v[126:127], v[108:109] neg_lo:[0,1] neg_hi:[0,1]
	v_pk_add_f32 v[108:109], v[126:127], v[108:109]
	v_pk_add_f32 v[126:127], v[182:183], v[188:189] neg_lo:[0,1] neg_hi:[0,1]
	v_cos_f32_e32 v188, v192
	v_pk_fma_f32 v[110:111], v[110:111], s[24:25], v[122:123] op_sel:[1,0,0] op_sel_hi:[1,1,0] neg_lo:[0,0,1] neg_hi:[0,0,1]
	v_pk_add_f32 v[130:131], v[132:133], v[130:131]
	v_pk_add_f32 v[122:123], v[106:107], v[110:111] neg_lo:[0,1] neg_hi:[0,1]
	v_xor_b32_e32 v121, 0x80000000, v112
	v_mov_b32_e32 v120, v113
	v_pk_add_f32 v[132:133], v[114:115], v[130:131] neg_lo:[0,1] neg_hi:[0,1]
	v_pk_add_f32 v[114:115], v[114:115], v[130:131]
	v_pk_add_f32 v[112:113], v[122:123], v[120:121]
	v_pk_add_f32 v[120:121], v[122:123], v[120:121] neg_lo:[0,1] neg_hi:[0,1]
	v_pk_mul_f32 v[122:123], v[178:179], v[114:115] op_sel:[0,1] op_sel_hi:[0,0]
	v_pk_fma_f32 v[130:131], v[188:189], v[114:115], v[122:123]
	v_pk_fma_f32 v[114:115], v[188:189], v[114:115], v[122:123] op_sel_hi:[0,1,1] neg_lo:[0,0,1] neg_hi:[0,0,1]
	v_mov_b32_e32 v189, v178
	v_pk_add_f32 v[180:181], v[134:135], v[176:177] neg_lo:[0,1] neg_hi:[0,1]
	v_mov_b32_e32 v131, v115
	v_pk_mul_f32 v[114:115], v[188:189], v[188:189]
	v_pk_add_f32 v[122:123], v[134:135], v[176:177]
	v_mul_f32_e32 v135, v188, v178
	v_mov_b32_e32 v134, v114
	v_pk_mov_b32 v[114:115], v[114:115], v[134:135] op_sel:[1,1]
	v_pk_add_f32 v[202:203], v[198:199], v[200:201]
	v_pk_add_f32 v[176:177], v[134:135], v[114:115] neg_lo:[0,1] neg_hi:[0,1]
	v_pk_add_f32 v[114:115], v[134:135], v[114:115]
	v_pk_add_f32 v[204:205], v[196:197], v[202:203]
	v_pk_add_f32 v[106:107], v[106:107], v[110:111]
	v_pk_mov_b32 v[134:135], v[176:177], v[114:115] op_sel:[0,1]
	v_pk_mul_f32 v[114:115], v[114:115], v[122:123] op_sel:[1,1] op_sel_hi:[1,0]
	v_mov_b32_e32 v179, v188
	v_pk_add_f32 v[104:105], v[190:191], v[204:205]
	v_pk_add_f32 v[124:125], v[190:191], v[204:205] neg_lo:[0,1] neg_hi:[0,1]
	v_pk_add_f32 v[110:111], v[106:107], v[108:109] neg_lo:[0,1] neg_hi:[0,1]
	v_pk_fma_f32 v[190:191], v[176:177], v[122:123], v[114:115]
	v_pk_fma_f32 v[114:115], v[176:177], v[122:123], v[114:115] op_sel_hi:[0,1,1] neg_lo:[0,0,1] neg_hi:[0,0,1]
	v_pk_add_f32 v[106:107], v[106:107], v[108:109]
	v_pk_mul_f32 v[108:109], v[178:179], v[134:135]
	v_mov_b32_e32 v191, v115
	v_pk_mul_f32 v[114:115], v[188:189], v[134:135]
	v_pk_add_f32 v[108:109], v[108:109], v[108:109] op_sel:[1,0] op_sel_hi:[1,0]
	v_pk_add_f32 v[114:115], v[114:115], v[114:115] op_sel:[0,1] op_sel_hi:[0,1] neg_lo:[0,1] neg_hi:[0,1]
	v_pk_mul_f32 v[108:109], v[108:109], v[106:107] op_sel:[0,1] op_sel_hi:[1,0]
	v_pk_add_f32 v[182:183], v[196:197], v[202:203] neg_lo:[0,1] neg_hi:[0,1]
	v_pk_fma_f32 v[122:123], v[114:115], v[106:107], v[108:109]
	v_pk_fma_f32 v[106:107], v[114:115], v[106:107], v[108:109] neg_lo:[0,0,1] neg_hi:[0,0,1]
	v_mul_f32_e32 v108, 4.0, v192
	v_sin_f32_e32 v106, v108
	v_cos_f32_e32 v108, v108
	v_xor_b32_e32 v185, 0x80000000, v182
	v_mov_b32_e32 v184, v183
	v_pk_add_f32 v[114:115], v[126:127], v[184:185]
	v_pk_add_f32 v[182:183], v[126:127], v[184:185] neg_lo:[0,1] neg_hi:[0,1]
	v_pk_mul_f32 v[126:127], v[106:107], v[114:115] op_sel:[0,1] op_sel_hi:[0,0]
	v_mov_b32_e32 v123, v107
	v_pk_fma_f32 v[134:135], v[108:109], v[114:115], v[126:127]
	v_pk_fma_f32 v[114:115], v[108:109], v[114:115], v[126:127] op_sel_hi:[0,1,1] neg_lo:[0,0,1] neg_hi:[0,0,1]
	v_mov_b32_e32 v109, v106
	v_mov_b32_e32 v107, v108
	v_mov_b32_e32 v135, v115
	v_pk_mul_f32 v[114:115], v[188:189], v[108:109]
	v_pk_mul_f32 v[106:107], v[188:189], v[106:107]
	v_pk_mov_b32 v[108:109], v[114:115], v[106:107] op_sel:[0,0]
	v_mov_b32_e32 v106, v115
	v_pk_add_f32 v[114:115], v[108:109], v[106:107] neg_lo:[0,1] neg_hi:[0,1]
	v_pk_add_f32 v[106:107], v[108:109], v[106:107]
	v_pk_mov_b32 v[108:109], v[114:115], v[106:107] op_sel:[0,1]
	v_pk_mul_f32 v[106:107], v[106:107], v[116:117] op_sel:[1,1] op_sel_hi:[1,0]
	s_mov_b32 s18, s25
	v_pk_fma_f32 v[126:127], v[114:115], v[116:117], v[106:107]
	v_pk_fma_f32 v[106:107], v[114:115], v[116:117], v[106:107] op_sel_hi:[0,1,1] neg_lo:[0,0,1] neg_hi:[0,0,1]
	v_mov_b32_e32 v127, v107
	v_pk_mul_f32 v[106:107], v[188:189], v[108:109]
	v_pk_mul_f32 v[108:109], v[178:179], v[108:109]
	v_pk_mov_b32 v[114:115], v[106:107], v[108:109] op_sel:[0,1]
	v_pk_mov_b32 v[106:107], v[106:107], v[108:109] op_sel:[1,0]
	s_mov_b32 s19, s24
	v_pk_add_f32 v[108:109], v[114:115], v[106:107] neg_lo:[0,1] neg_hi:[0,1]
	v_pk_add_f32 v[106:107], v[114:115], v[106:107]
	v_pk_mov_b32 v[114:115], v[108:109], v[106:107] op_sel:[0,1]
	v_pk_mul_f32 v[106:107], v[106:107], v[186:187] op_sel:[1,1] op_sel_hi:[1,0]
	s_mov_b32 s88, s31
	v_pk_fma_f32 v[116:117], v[108:109], v[186:187], v[106:107]
	v_pk_fma_f32 v[106:107], v[108:109], v[186:187], v[106:107] op_sel_hi:[0,1,1] neg_lo:[0,0,1] neg_hi:[0,0,1]
	v_pk_mul_f32 v[108:109], v[178:179], v[114:115]
	v_mov_b32_e32 v117, v107
	v_pk_mul_f32 v[106:107], v[188:189], v[114:115]
	v_pk_add_f32 v[108:109], v[108:109], v[108:109] op_sel:[1,0] op_sel_hi:[1,0]
	v_pk_add_f32 v[106:107], v[106:107], v[106:107] op_sel:[0,1] op_sel_hi:[0,1] neg_lo:[0,1] neg_hi:[0,1]
	v_pk_mul_f32 v[108:109], v[108:109], v[112:113] op_sel:[0,1] op_sel_hi:[1,0]
	s_mov_b32 s89, s30
	v_pk_fma_f32 v[114:115], v[106:107], v[112:113], v[108:109]
	v_pk_fma_f32 v[106:107], v[106:107], v[112:113], v[108:109] neg_lo:[0,0,1] neg_hi:[0,0,1]
	v_mul_f32_e32 v115, 0x41000000, v192
	v_sin_f32_e32 v176, v115
	v_cos_f32_e32 v184, v115
	v_mov_b32_e32 v115, v107
	v_pk_mul_f32 v[106:107], v[176:177], v[124:125] op_sel:[0,1] op_sel_hi:[0,0]
	v_pk_fma_f32 v[108:109], v[184:185], v[124:125], v[106:107]
	v_pk_fma_f32 v[106:107], v[184:185], v[124:125], v[106:107] op_sel_hi:[0,1,1] neg_lo:[0,0,1] neg_hi:[0,0,1]
	v_mov_b32_e32 v185, v176
	v_mov_b32_e32 v177, v184
	v_mov_b32_e32 v109, v107
	v_pk_mul_f32 v[106:107], v[188:189], v[184:185]
	v_pk_mul_f32 v[112:113], v[188:189], v[176:177]
	v_pk_mov_b32 v[124:125], v[106:107], v[112:113] op_sel:[0,0]
	v_mov_b32_e32 v112, v107
	v_pk_add_f32 v[106:107], v[124:125], v[112:113] neg_lo:[0,1] neg_hi:[0,1]
	v_pk_add_f32 v[112:113], v[124:125], v[112:113]
	v_mov_b32_e32 v124, v106
	v_mov_b32_e32 v125, v113
	v_pk_mul_f32 v[112:113], v[112:113], v[132:133] op_sel:[1,1] op_sel_hi:[1,0]
	s_nop 0
	v_pk_fma_f32 v[176:177], v[106:107], v[132:133], v[112:113]
	v_pk_fma_f32 v[106:107], v[106:107], v[132:133], v[112:113] op_sel_hi:[0,1,1] neg_lo:[0,0,1] neg_hi:[0,0,1]
	v_mov_b32_e32 v177, v107
	v_pk_mul_f32 v[106:107], v[188:189], v[124:125]
	v_pk_mul_f32 v[112:113], v[178:179], v[124:125]
	v_mov_b32_e32 v124, v106
	v_mov_b32_e32 v125, v113
	v_pk_mov_b32 v[106:107], v[106:107], v[112:113] op_sel:[1,0]
	s_nop 0
	v_pk_add_f32 v[112:113], v[124:125], v[106:107] neg_lo:[0,1] neg_hi:[0,1]
	v_pk_add_f32 v[106:107], v[124:125], v[106:107]
	v_mov_b32_e32 v124, v112
	v_mov_b32_e32 v125, v107
	v_pk_mul_f32 v[106:107], v[106:107], v[180:181] op_sel:[1,1] op_sel_hi:[1,0]
	s_nop 0
	v_pk_fma_f32 v[132:133], v[112:113], v[180:181], v[106:107]
	v_pk_fma_f32 v[106:107], v[112:113], v[180:181], v[106:107] op_sel_hi:[0,1,1] neg_lo:[0,0,1] neg_hi:[0,0,1]
	v_pk_mul_f32 v[112:113], v[178:179], v[124:125]
	v_mov_b32_e32 v133, v107
	v_pk_mul_f32 v[106:107], v[188:189], v[124:125]
	v_pk_add_f32 v[112:113], v[112:113], v[112:113] op_sel:[1,0] op_sel_hi:[1,0]
	v_pk_add_f32 v[106:107], v[106:107], v[106:107] op_sel:[0,1] op_sel_hi:[0,1] neg_lo:[0,1] neg_hi:[0,1]
	v_pk_mul_f32 v[112:113], v[112:113], v[110:111] op_sel:[0,1] op_sel_hi:[1,0]
	s_nop 0
	v_pk_fma_f32 v[124:125], v[106:107], v[110:111], v[112:113]
	v_pk_fma_f32 v[106:107], v[106:107], v[110:111], v[112:113] neg_lo:[0,0,1] neg_hi:[0,0,1]
	v_mul_f32_e32 v125, 0x41400000, v192
	v_sin_f32_e32 v180, v125
	v_cos_f32_e32 v184, v125
	v_mov_b32_e32 v125, v107
	v_pk_mul_f32 v[106:107], v[180:181], v[182:183] op_sel:[0,1] op_sel_hi:[0,0]
	v_pk_fma_f32 v[110:111], v[184:185], v[182:183], v[106:107]
	v_pk_fma_f32 v[106:107], v[184:185], v[182:183], v[106:107] op_sel_hi:[0,1,1] neg_lo:[0,0,1] neg_hi:[0,0,1]
	v_mov_b32_e32 v185, v180
	v_mov_b32_e32 v181, v184
	v_mov_b32_e32 v111, v107
	v_pk_mul_f32 v[106:107], v[188:189], v[184:185]
	v_pk_mul_f32 v[112:113], v[188:189], v[180:181]
	v_pk_mov_b32 v[180:181], v[106:107], v[112:113] op_sel:[0,0]
	v_mov_b32_e32 v112, v107
	v_pk_add_f32 v[106:107], v[180:181], v[112:113] neg_lo:[0,1] neg_hi:[0,1]
	v_pk_add_f32 v[112:113], v[180:181], v[112:113]
	v_mov_b32_e32 v180, v106
	v_mov_b32_e32 v181, v113
	v_pk_mul_f32 v[112:113], v[112:113], v[118:119] op_sel:[1,1] op_sel_hi:[1,0]
	s_nop 0
	v_pk_fma_f32 v[182:183], v[106:107], v[118:119], v[112:113]
	v_pk_fma_f32 v[106:107], v[106:107], v[118:119], v[112:113] op_sel_hi:[0,1,1] neg_lo:[0,0,1] neg_hi:[0,0,1]
	v_mov_b32_e32 v183, v107
	v_pk_mul_f32 v[106:107], v[188:189], v[180:181]
	v_pk_mul_f32 v[112:113], v[178:179], v[180:181]
	v_mov_b32_e32 v118, v106
	v_mov_b32_e32 v119, v113
	v_pk_mov_b32 v[106:107], v[106:107], v[112:113] op_sel:[1,0]
	s_nop 0
	v_pk_add_f32 v[112:113], v[118:119], v[106:107] neg_lo:[0,1] neg_hi:[0,1]
	v_pk_add_f32 v[106:107], v[118:119], v[106:107]
	v_mov_b32_e32 v118, v112
	v_mov_b32_e32 v119, v107
	v_pk_mul_f32 v[106:107], v[106:107], v[128:129] op_sel:[1,1] op_sel_hi:[1,0]
	s_nop 0
	v_pk_fma_f32 v[180:181], v[112:113], v[128:129], v[106:107]
	v_pk_fma_f32 v[106:107], v[112:113], v[128:129], v[106:107] op_sel_hi:[0,1,1] neg_lo:[0,0,1] neg_hi:[0,0,1]
	v_pk_mul_f32 v[112:113], v[178:179], v[118:119]
	v_mov_b32_e32 v181, v107
	v_pk_mul_f32 v[106:107], v[188:189], v[118:119]
	v_pk_add_f32 v[112:113], v[112:113], v[112:113] op_sel:[1,0] op_sel_hi:[1,0]
	v_pk_add_f32 v[106:107], v[106:107], v[106:107] op_sel:[0,1] op_sel_hi:[0,1] neg_lo:[0,1] neg_hi:[0,1]
	v_pk_mul_f32 v[112:113], v[112:113], v[120:121] op_sel:[0,1] op_sel_hi:[1,0]
	s_nop 0
	v_pk_fma_f32 v[118:119], v[106:107], v[120:121], v[112:113]
	v_pk_fma_f32 v[106:107], v[106:107], v[120:121], v[112:113] neg_lo:[0,0,1] neg_hi:[0,0,1]
	s_nop 0
	v_mov_b32_e32 v119, v107
	ds_write_b64 v207, v[104:105]
	ds_write_b64 v207, v[130:131] offset:2176
	ds_write_b64 v207, v[190:191] offset:4352
	ds_write_b64 v207, v[122:123] offset:6528
	ds_write_b64 v207, v[134:135] offset:8704
	ds_write_b64 v207, v[126:127] offset:10880
	ds_write_b64 v207, v[116:117] offset:13056
	ds_write_b64 v207, v[114:115] offset:15232
	ds_write_b64 v207, v[108:109] offset:17408
	ds_write_b64 v207, v[176:177] offset:19584
	ds_write_b64 v207, v[132:133] offset:21760
	ds_write_b64 v207, v[124:125] offset:23936
	ds_write_b64 v207, v[110:111] offset:26112
	ds_write_b64 v207, v[182:183] offset:28288
	ds_write_b64 v207, v[180:181] offset:30464
	ds_write_b64 v207, v[118:119] offset:32640
	v_mov_b32_e32 v104, v208
	s_waitcnt lgkmcnt(0)
	s_barrier
	s_nop 0
	v_and_b32_e32 v206, 15, v104
	v_lshlrev_b32_e32 v104, 4, v104
	v_and_b32_e32 v104, 0xffffff00, v104
	v_ashrrev_i32_e32 v105, 1, v104
	v_add_u32_e32 v105, s35, v105
	v_lshlrev_b32_e32 v104, 3, v104
	v_lshlrev_b32_e32 v106, 3, v206
	v_add3_u32 v207, v105, v104, v106
	ds_read_b64 v[106:107], v207
	ds_read_b64 v[108:109], v207 offset:136
	ds_read_b64 v[110:111], v207 offset:272
	ds_read_b64 v[112:113], v207 offset:408
	ds_read_b64 v[114:115], v207 offset:544
	ds_read_b64 v[116:117], v207 offset:680
	ds_read_b64 v[118:119], v207 offset:1088
	ds_read_b64 v[120:121], v207 offset:1224
	ds_read_b64 v[122:123], v207 offset:1632
	ds_read_b64 v[124:125], v207 offset:1768
	ds_read_b64 v[126:127], v207 offset:816
	ds_read_b64 v[128:129], v207 offset:952
	ds_read_b64 v[130:131], v207 offset:1360
	ds_read_b64 v[132:133], v207 offset:1496
	ds_read_b64 v[176:177], v207 offset:1904
	ds_read_b64 v[178:179], v207 offset:2040
	s_waitcnt lgkmcnt(8)
	v_pk_add_f32 v[192:193], v[108:109], v[120:121]
	s_waitcnt lgkmcnt(6)
	v_pk_add_f32 v[180:181], v[114:115], v[122:123]
	v_pk_add_f32 v[194:195], v[116:117], v[124:125]
	v_pk_add_f32 v[114:115], v[114:115], v[122:123] neg_lo:[0,1] neg_hi:[0,1]
	s_waitcnt lgkmcnt(0)
	v_pk_add_f32 v[122:123], v[126:127], v[176:177] neg_lo:[0,1] neg_hi:[0,1]
	v_pk_add_f32 v[116:117], v[116:117], v[124:125] neg_lo:[0,1] neg_hi:[0,1]
	v_pk_add_f32 v[184:185], v[110:111], v[130:131]
	v_pk_add_f32 v[186:187], v[126:127], v[176:177]
	v_pk_add_f32 v[110:111], v[110:111], v[130:131] neg_lo:[0,1] neg_hi:[0,1]
	v_xor_b32_e32 v127, 0x80000000, v122
	v_mov_b32_e32 v126, v123
	v_pk_add_f32 v[108:109], v[108:109], v[120:121] neg_lo:[0,1] neg_hi:[0,1]
	v_xor_b32_e32 v121, 0x80000000, v116
	v_mov_b32_e32 v120, v117
	v_pk_add_f32 v[122:123], v[110:111], v[126:127]
	v_pk_add_f32 v[116:117], v[108:109], v[120:121]
	v_pk_mul_f32 v[130:131], v[122:123], s[24:25] op_sel_hi:[1,0]
	v_pk_mul_f32 v[124:125], v[116:117], s[30:31] op_sel_hi:[1,0]
	v_pk_fma_f32 v[176:177], v[122:123], s[24:25], v[130:131] op_sel:[0,0,1] op_sel_hi:[1,0,0]
	v_pk_fma_f32 v[122:123], v[122:123], s[24:25], v[130:131] op_sel_hi:[1,0,0] neg_lo:[0,0,1] neg_hi:[0,0,1]
	v_pk_fma_f32 v[130:131], v[116:117], s[22:23], v[124:125] op_sel:[0,0,1] op_sel_hi:[1,0,0]
	v_pk_fma_f32 v[116:117], v[116:117], s[22:23], v[124:125] op_sel:[0,0,1] op_sel_hi:[1,0,0] neg_lo:[0,0,1] neg_hi:[0,0,1]
	v_pk_add_f32 v[188:189], v[184:185], v[186:187]
	v_pk_add_f32 v[200:201], v[128:129], v[178:179]
	v_mov_b32_e32 v131, v117
	v_pk_add_f32 v[116:117], v[128:129], v[178:179] neg_lo:[0,1] neg_hi:[0,1]
	v_pk_add_f32 v[178:179], v[184:185], v[186:187] neg_lo:[0,1] neg_hi:[0,1]
	v_pk_add_f32 v[184:185], v[192:193], v[194:195] neg_lo:[0,1] neg_hi:[0,1]
	v_pk_add_f32 v[198:199], v[112:113], v[132:133]
	v_pk_add_f32 v[112:113], v[112:113], v[132:133] neg_lo:[0,1] neg_hi:[0,1]
	v_xor_b32_e32 v125, 0x80000000, v116
	v_mov_b32_e32 v124, v117
	v_pk_mul_f32 v[186:187], v[184:185], s[24:25] op_sel_hi:[1,0]
	v_pk_add_f32 v[196:197], v[192:193], v[194:195]
	v_pk_add_f32 v[116:117], v[112:113], v[124:125]
	v_pk_fma_f32 v[192:193], v[184:185], s[24:25], v[186:187] op_sel:[0,0,1] op_sel_hi:[1,0,0]
	v_pk_fma_f32 v[184:185], v[184:185], s[24:25], v[186:187] op_sel_hi:[1,0,0] neg_lo:[0,0,1] neg_hi:[0,0,1]
	v_pk_mul_f32 v[128:129], v[116:117], s[22:23] op_sel_hi:[1,0]
	v_mov_b32_e32 v193, v185
	v_pk_add_f32 v[184:185], v[198:199], v[200:201] neg_lo:[0,1] neg_hi:[0,1]
	v_pk_fma_f32 v[132:133], v[116:117], s[30:31], v[128:129] op_sel:[0,0,1] op_sel_hi:[1,0,0]
	v_pk_fma_f32 v[116:117], v[116:117], s[30:31], v[128:129] op_sel:[0,0,1] op_sel_hi:[1,0,0] neg_lo:[0,0,1] neg_hi:[0,0,1]
	v_mul_f32_e32 v186, 0x3f3504f3, v184
	v_pk_add_f32 v[134:135], v[106:107], v[118:119]
	v_pk_add_f32 v[106:107], v[106:107], v[118:119] neg_lo:[0,1] neg_hi:[0,1]
	v_xor_b32_e32 v119, 0x80000000, v114
	v_mov_b32_e32 v118, v115
	v_mov_b32_e32 v133, v117
	v_pk_fma_f32 v[184:185], v[184:185], s[24:25], v[186:187] op_sel:[1,0,0] op_sel_hi:[1,1,0] neg_lo:[0,0,1] neg_hi:[0,0,1]
	v_pk_add_f32 v[108:109], v[108:109], v[120:121] neg_lo:[0,1] neg_hi:[0,1]
	v_pk_add_f32 v[182:183], v[134:135], v[180:181]
	v_pk_add_f32 v[114:115], v[106:107], v[118:119]
	v_mov_b32_e32 v177, v123
	v_pk_add_f32 v[116:117], v[130:131], v[132:133] neg_lo:[0,1] neg_hi:[0,1]
	v_pk_add_f32 v[134:135], v[134:135], v[180:181] neg_lo:[0,1] neg_hi:[0,1]
	v_xor_b32_e32 v181, 0x80000000, v178
	v_mov_b32_e32 v180, v179
	v_pk_add_f32 v[186:187], v[192:193], v[184:185] neg_lo:[0,1] neg_hi:[0,1]
	v_pk_mul_f32 v[120:121], v[108:109], s[22:23] op_sel_hi:[1,0]
	v_pk_add_f32 v[122:123], v[114:115], v[176:177] neg_lo:[0,1] neg_hi:[0,1]
	v_xor_b32_e32 v129, 0x80000000, v116
	v_mov_b32_e32 v128, v117
	v_pk_add_f32 v[178:179], v[134:135], v[180:181] neg_lo:[0,1] neg_hi:[0,1]
	v_xor_b32_e32 v195, 0x80000000, v186
	v_mov_b32_e32 v194, v187
	v_pk_add_f32 v[110:111], v[110:111], v[126:127] neg_lo:[0,1] neg_hi:[0,1]
	v_pk_fma_f32 v[126:127], v[108:109], s[30:31], v[120:121] op_sel:[0,0,1] op_sel_hi:[1,0,0]
	v_pk_fma_f32 v[108:109], v[108:109], s[30:31], v[120:121] op_sel:[0,0,1] op_sel_hi:[1,0,0] neg_lo:[0,0,1] neg_hi:[0,0,1]
	v_pk_add_f32 v[116:117], v[122:123], v[128:129]
	v_pk_add_f32 v[186:187], v[178:179], v[194:195]
	v_mov_b32_e32 v127, v109
	v_pk_add_f32 v[108:109], v[112:113], v[124:125] neg_lo:[0,1] neg_hi:[0,1]
	v_pk_add_f32 v[122:123], v[122:123], v[128:129] neg_lo:[0,1] neg_hi:[0,1]
	v_pk_add_f32 v[128:129], v[178:179], v[194:195] neg_lo:[0,1] neg_hi:[0,1]
	v_cvt_f32_ubyte0_e32 v178, v206
	v_pk_mul_f32 v[112:113], v[108:109], s[30:31]
	v_pk_add_f32 v[114:115], v[114:115], v[176:177]
	v_pk_add_f32 v[176:177], v[192:193], v[184:185]
	v_mul_f32_e32 v192, 0x3b800000, v178
	v_pk_fma_f32 v[108:109], v[108:109], s[22:23], v[112:113] op_sel:[0,0,1] op_sel_hi:[1,0,0] neg_lo:[1,0,0] neg_hi:[1,0,0]
	v_sin_f32_e32 v178, v192
	v_pk_add_f32 v[190:191], v[182:183], v[188:189]
	v_pk_add_f32 v[106:107], v[106:107], v[118:119] neg_lo:[0,1] neg_hi:[0,1]
	v_mul_f32_e32 v118, 0x3f3504f3, v110
	v_pk_add_f32 v[112:113], v[126:127], v[108:109] neg_lo:[0,1] neg_hi:[0,1]
	v_pk_add_f32 v[108:109], v[126:127], v[108:109]
	v_pk_add_f32 v[126:127], v[182:183], v[188:189] neg_lo:[0,1] neg_hi:[0,1]
	v_cos_f32_e32 v188, v192
	v_pk_fma_f32 v[110:111], v[110:111], s[24:25], v[118:119] op_sel:[1,0,0] op_sel_hi:[1,1,0] neg_lo:[0,0,1] neg_hi:[0,0,1]
	v_pk_add_f32 v[130:131], v[130:131], v[132:133]
	v_pk_add_f32 v[118:119], v[106:107], v[110:111] neg_lo:[0,1] neg_hi:[0,1]
	v_xor_b32_e32 v121, 0x80000000, v112
	v_mov_b32_e32 v120, v113
	v_pk_add_f32 v[132:133], v[114:115], v[130:131] neg_lo:[0,1] neg_hi:[0,1]
	v_pk_add_f32 v[114:115], v[114:115], v[130:131]
	v_pk_add_f32 v[112:113], v[118:119], v[120:121]
	v_pk_add_f32 v[118:119], v[118:119], v[120:121] neg_lo:[0,1] neg_hi:[0,1]
	v_pk_mul_f32 v[120:121], v[178:179], v[114:115] op_sel:[0,1] op_sel_hi:[0,0]
	v_pk_add_f32 v[134:135], v[134:135], v[180:181]
	v_pk_fma_f32 v[130:131], v[188:189], v[114:115], v[120:121]
	v_pk_fma_f32 v[114:115], v[188:189], v[114:115], v[120:121] op_sel_hi:[0,1,1] neg_lo:[0,0,1] neg_hi:[0,0,1]
	v_mov_b32_e32 v189, v178
	v_pk_add_f32 v[180:181], v[134:135], v[176:177] neg_lo:[0,1] neg_hi:[0,1]
	v_mov_b32_e32 v131, v115
	v_pk_mul_f32 v[114:115], v[188:189], v[188:189]
	v_pk_add_f32 v[120:121], v[134:135], v[176:177]
	v_mul_f32_e32 v135, v188, v178
	v_mov_b32_e32 v134, v114
	v_pk_mov_b32 v[114:115], v[114:115], v[134:135] op_sel:[1,1]
	v_pk_add_f32 v[202:203], v[198:199], v[200:201]
	v_pk_add_f32 v[176:177], v[134:135], v[114:115] neg_lo:[0,1] neg_hi:[0,1]
	v_pk_add_f32 v[114:115], v[134:135], v[114:115]
	v_pk_add_f32 v[204:205], v[196:197], v[202:203]
	v_pk_add_f32 v[106:107], v[106:107], v[110:111]
	v_pk_mov_b32 v[134:135], v[176:177], v[114:115] op_sel:[0,1]
	v_pk_mul_f32 v[114:115], v[114:115], v[120:121] op_sel:[1,1] op_sel_hi:[1,0]
	v_mov_b32_e32 v179, v188
	v_pk_add_f32 v[104:105], v[190:191], v[204:205]
	v_pk_add_f32 v[124:125], v[190:191], v[204:205] neg_lo:[0,1] neg_hi:[0,1]
	v_pk_add_f32 v[110:111], v[106:107], v[108:109] neg_lo:[0,1] neg_hi:[0,1]
	v_pk_fma_f32 v[190:191], v[176:177], v[120:121], v[114:115]
	v_pk_fma_f32 v[114:115], v[176:177], v[120:121], v[114:115] op_sel_hi:[0,1,1] neg_lo:[0,0,1] neg_hi:[0,0,1]
	v_pk_add_f32 v[106:107], v[106:107], v[108:109]
	v_pk_mul_f32 v[108:109], v[178:179], v[134:135]
	v_mov_b32_e32 v191, v115
	v_pk_mul_f32 v[114:115], v[188:189], v[134:135]
	v_pk_add_f32 v[108:109], v[108:109], v[108:109] op_sel:[1,0] op_sel_hi:[1,0]
	v_pk_add_f32 v[114:115], v[114:115], v[114:115] op_sel:[0,1] op_sel_hi:[0,1] neg_lo:[0,1] neg_hi:[0,1]
	v_pk_mul_f32 v[108:109], v[108:109], v[106:107] op_sel:[0,1] op_sel_hi:[1,0]
	v_pk_add_f32 v[182:183], v[196:197], v[202:203] neg_lo:[0,1] neg_hi:[0,1]
	v_pk_fma_f32 v[120:121], v[114:115], v[106:107], v[108:109]
	v_pk_fma_f32 v[106:107], v[114:115], v[106:107], v[108:109] neg_lo:[0,0,1] neg_hi:[0,0,1]
	v_mul_f32_e32 v108, 4.0, v192
	v_sin_f32_e32 v106, v108
	v_cos_f32_e32 v108, v108
	v_xor_b32_e32 v185, 0x80000000, v182
	v_mov_b32_e32 v184, v183
	v_pk_add_f32 v[114:115], v[126:127], v[184:185]
	v_pk_add_f32 v[182:183], v[126:127], v[184:185] neg_lo:[0,1] neg_hi:[0,1]
	v_pk_mul_f32 v[126:127], v[106:107], v[114:115] op_sel:[0,1] op_sel_hi:[0,0]
	v_mov_b32_e32 v121, v107
	v_pk_fma_f32 v[134:135], v[108:109], v[114:115], v[126:127]
	v_pk_fma_f32 v[114:115], v[108:109], v[114:115], v[126:127] op_sel_hi:[0,1,1] neg_lo:[0,0,1] neg_hi:[0,0,1]
	v_mov_b32_e32 v109, v106
	v_mov_b32_e32 v107, v108
	v_mov_b32_e32 v135, v115
	v_pk_mul_f32 v[114:115], v[188:189], v[108:109]
	v_pk_mul_f32 v[106:107], v[188:189], v[106:107]
	v_pk_mov_b32 v[108:109], v[114:115], v[106:107] op_sel:[0,0]
	v_mov_b32_e32 v106, v115
	v_pk_add_f32 v[114:115], v[108:109], v[106:107] neg_lo:[0,1] neg_hi:[0,1]
	v_pk_add_f32 v[106:107], v[108:109], v[106:107]
	v_mov_b32_e32 v108, v114
	v_mov_b32_e32 v109, v107
	v_pk_mul_f32 v[106:107], v[106:107], v[116:117] op_sel:[1,1] op_sel_hi:[1,0]
	s_nop 0
	v_pk_fma_f32 v[126:127], v[114:115], v[116:117], v[106:107]
	v_pk_fma_f32 v[106:107], v[114:115], v[116:117], v[106:107] op_sel_hi:[0,1,1] neg_lo:[0,0,1] neg_hi:[0,0,1]
	v_mov_b32_e32 v127, v107
	v_pk_mul_f32 v[106:107], v[188:189], v[108:109]
	v_pk_mul_f32 v[108:109], v[178:179], v[108:109]
	v_mov_b32_e32 v114, v106
	v_mov_b32_e32 v115, v109
	v_pk_mov_b32 v[106:107], v[106:107], v[108:109] op_sel:[1,0]
	s_nop 0
	v_pk_add_f32 v[108:109], v[114:115], v[106:107] neg_lo:[0,1] neg_hi:[0,1]
	v_pk_add_f32 v[106:107], v[114:115], v[106:107]
	v_mov_b32_e32 v114, v108
	v_mov_b32_e32 v115, v107
	v_pk_mul_f32 v[106:107], v[106:107], v[186:187] op_sel:[1,1] op_sel_hi:[1,0]
	s_nop 0
	v_pk_fma_f32 v[116:117], v[108:109], v[186:187], v[106:107]
	v_pk_fma_f32 v[106:107], v[108:109], v[186:187], v[106:107] op_sel_hi:[0,1,1] neg_lo:[0,0,1] neg_hi:[0,0,1]
	v_pk_mul_f32 v[108:109], v[178:179], v[114:115]
	v_mov_b32_e32 v117, v107
	v_pk_mul_f32 v[106:107], v[188:189], v[114:115]
	v_pk_add_f32 v[108:109], v[108:109], v[108:109] op_sel:[1,0] op_sel_hi:[1,0]
	v_pk_add_f32 v[106:107], v[106:107], v[106:107] op_sel:[0,1] op_sel_hi:[0,1] neg_lo:[0,1] neg_hi:[0,1]
	v_pk_mul_f32 v[108:109], v[108:109], v[112:113] op_sel:[0,1] op_sel_hi:[1,0]
	s_nop 0
	v_pk_fma_f32 v[114:115], v[106:107], v[112:113], v[108:109]
	v_pk_fma_f32 v[106:107], v[106:107], v[112:113], v[108:109] neg_lo:[0,0,1] neg_hi:[0,0,1]
	v_mul_f32_e32 v115, 0x41000000, v192
	v_sin_f32_e32 v176, v115
	v_cos_f32_e32 v184, v115
	v_mov_b32_e32 v115, v107
	v_pk_mul_f32 v[106:107], v[176:177], v[124:125] op_sel:[0,1] op_sel_hi:[0,0]
	v_pk_fma_f32 v[108:109], v[184:185], v[124:125], v[106:107]
	v_pk_fma_f32 v[106:107], v[184:185], v[124:125], v[106:107] op_sel_hi:[0,1,1] neg_lo:[0,0,1] neg_hi:[0,0,1]
	v_mov_b32_e32 v185, v176
	v_mov_b32_e32 v177, v184
	v_mov_b32_e32 v109, v107
	v_pk_mul_f32 v[106:107], v[188:189], v[184:185]
	v_pk_mul_f32 v[112:113], v[188:189], v[176:177]
	v_pk_mov_b32 v[124:125], v[106:107], v[112:113] op_sel:[0,0]
	v_mov_b32_e32 v112, v107
	v_pk_add_f32 v[106:107], v[124:125], v[112:113] neg_lo:[0,1] neg_hi:[0,1]
	v_pk_add_f32 v[112:113], v[124:125], v[112:113]
	v_mov_b32_e32 v124, v106
	v_mov_b32_e32 v125, v113
	v_pk_mul_f32 v[112:113], v[112:113], v[132:133] op_sel:[1,1] op_sel_hi:[1,0]
	s_nop 0
	v_pk_fma_f32 v[176:177], v[106:107], v[132:133], v[112:113]
	v_pk_fma_f32 v[106:107], v[106:107], v[132:133], v[112:113] op_sel_hi:[0,1,1] neg_lo:[0,0,1] neg_hi:[0,0,1]
	v_mov_b32_e32 v177, v107
	v_pk_mul_f32 v[106:107], v[188:189], v[124:125]
	v_pk_mul_f32 v[112:113], v[178:179], v[124:125]
	v_mov_b32_e32 v124, v106
	v_mov_b32_e32 v125, v113
	v_pk_mov_b32 v[106:107], v[106:107], v[112:113] op_sel:[1,0]
	s_nop 0
	v_pk_add_f32 v[112:113], v[124:125], v[106:107] neg_lo:[0,1] neg_hi:[0,1]
	v_pk_add_f32 v[106:107], v[124:125], v[106:107]
	v_mov_b32_e32 v124, v112
	v_mov_b32_e32 v125, v107
	v_pk_mul_f32 v[106:107], v[106:107], v[180:181] op_sel:[1,1] op_sel_hi:[1,0]
	s_nop 0
	v_pk_fma_f32 v[132:133], v[112:113], v[180:181], v[106:107]
	v_pk_fma_f32 v[106:107], v[112:113], v[180:181], v[106:107] op_sel_hi:[0,1,1] neg_lo:[0,0,1] neg_hi:[0,0,1]
	v_pk_mul_f32 v[112:113], v[178:179], v[124:125]
	v_mov_b32_e32 v133, v107
	v_pk_mul_f32 v[106:107], v[188:189], v[124:125]
	v_pk_add_f32 v[112:113], v[112:113], v[112:113] op_sel:[1,0] op_sel_hi:[1,0]
	v_pk_add_f32 v[106:107], v[106:107], v[106:107] op_sel:[0,1] op_sel_hi:[0,1] neg_lo:[0,1] neg_hi:[0,1]
	v_pk_mul_f32 v[112:113], v[112:113], v[110:111] op_sel:[0,1] op_sel_hi:[1,0]
	s_nop 0
	v_pk_fma_f32 v[124:125], v[106:107], v[110:111], v[112:113]
	v_pk_fma_f32 v[106:107], v[106:107], v[110:111], v[112:113] neg_lo:[0,0,1] neg_hi:[0,0,1]
	v_mul_f32_e32 v125, 0x41400000, v192
	v_sin_f32_e32 v180, v125
	v_cos_f32_e32 v184, v125
	v_mov_b32_e32 v125, v107
	v_pk_mul_f32 v[106:107], v[180:181], v[182:183] op_sel:[0,1] op_sel_hi:[0,0]
	v_pk_fma_f32 v[110:111], v[184:185], v[182:183], v[106:107]
	v_pk_fma_f32 v[106:107], v[184:185], v[182:183], v[106:107] op_sel_hi:[0,1,1] neg_lo:[0,0,1] neg_hi:[0,0,1]
	v_mov_b32_e32 v185, v180
	v_mov_b32_e32 v181, v184
	v_mov_b32_e32 v111, v107
	v_pk_mul_f32 v[106:107], v[188:189], v[184:185]
	v_pk_mul_f32 v[112:113], v[188:189], v[180:181]
	v_pk_mov_b32 v[180:181], v[106:107], v[112:113] op_sel:[0,0]
	v_mov_b32_e32 v112, v107
	v_pk_add_f32 v[106:107], v[180:181], v[112:113] neg_lo:[0,1] neg_hi:[0,1]
	v_pk_add_f32 v[112:113], v[180:181], v[112:113]
	v_mov_b32_e32 v180, v106
	v_mov_b32_e32 v181, v113
	v_pk_mul_f32 v[112:113], v[112:113], v[122:123] op_sel:[1,1] op_sel_hi:[1,0]
	s_nop 0
	v_pk_fma_f32 v[182:183], v[106:107], v[122:123], v[112:113]
	v_pk_fma_f32 v[106:107], v[106:107], v[122:123], v[112:113] op_sel_hi:[0,1,1] neg_lo:[0,0,1] neg_hi:[0,0,1]
	v_mov_b32_e32 v183, v107
	v_pk_mul_f32 v[106:107], v[188:189], v[180:181]
	v_pk_mul_f32 v[112:113], v[178:179], v[180:181]
	v_mov_b32_e32 v122, v106
	v_mov_b32_e32 v123, v113
	v_pk_mov_b32 v[106:107], v[106:107], v[112:113] op_sel:[1,0]
	s_nop 0
	v_pk_add_f32 v[112:113], v[122:123], v[106:107] neg_lo:[0,1] neg_hi:[0,1]
	v_pk_add_f32 v[106:107], v[122:123], v[106:107]
	v_mov_b32_e32 v122, v112
	v_mov_b32_e32 v123, v107
	v_pk_mul_f32 v[106:107], v[106:107], v[128:129] op_sel:[1,1] op_sel_hi:[1,0]
	s_nop 0
	v_pk_fma_f32 v[180:181], v[112:113], v[128:129], v[106:107]
	v_pk_fma_f32 v[106:107], v[112:113], v[128:129], v[106:107] op_sel_hi:[0,1,1] neg_lo:[0,0,1] neg_hi:[0,0,1]
	v_pk_mul_f32 v[112:113], v[178:179], v[122:123]
	v_mov_b32_e32 v181, v107
	v_pk_mul_f32 v[106:107], v[188:189], v[122:123]
	v_pk_add_f32 v[112:113], v[112:113], v[112:113] op_sel:[1,0] op_sel_hi:[1,0]
	v_pk_add_f32 v[106:107], v[106:107], v[106:107] op_sel:[0,1] op_sel_hi:[0,1] neg_lo:[0,1] neg_hi:[0,1]
	v_pk_mul_f32 v[112:113], v[112:113], v[118:119] op_sel:[0,1] op_sel_hi:[1,0]
	s_nop 0
	v_pk_fma_f32 v[122:123], v[106:107], v[118:119], v[112:113]
	v_pk_fma_f32 v[106:107], v[106:107], v[118:119], v[112:113] neg_lo:[0,0,1] neg_hi:[0,0,1]
	s_nop 0
	v_mov_b32_e32 v123, v107
	ds_write2_b64 v207, v[104:105], v[130:131] offset1:17
	ds_write2_b64 v207, v[190:191], v[120:121] offset0:34 offset1:51
	ds_write2_b64 v207, v[134:135], v[126:127] offset0:68 offset1:85
	ds_write2_b64 v207, v[116:117], v[114:115] offset0:102 offset1:119
	ds_write2_b64 v207, v[108:109], v[176:177] offset0:136 offset1:153
	ds_write2_b64 v207, v[132:133], v[124:125] offset0:170 offset1:187
	ds_write2_b64 v207, v[110:111], v[182:183] offset0:204 offset1:221
	ds_write2_b64 v207, v[180:181], v[122:123] offset0:238 offset1:255
	v_mov_b32_e32 v104, v208
	s_waitcnt lgkmcnt(0)
	s_nop 0
	v_lshlrev_b32_e32 v105, 4, v104
	v_bfe_i32 v104, v104, 0, 28
	v_add_lshl_u32 v182, v104, v105, 3
	v_add_u32_e32 v188, s35, v182
	ds_read_b64 v[104:105], v188
	ds_read_b64 v[106:107], v188 offset:8
	ds_read_b64 v[108:109], v188 offset:16
	ds_read_b64 v[110:111], v188 offset:24
	ds_read_b64 v[112:113], v188 offset:64
	ds_read_b64 v[114:115], v188 offset:72
	ds_read_b64 v[116:117], v188 offset:32
	ds_read_b64 v[118:119], v188 offset:40
	ds_read_b64 v[120:121], v188 offset:48
	ds_read_b64 v[122:123], v188 offset:56
	ds_read_b64 v[124:125], v188 offset:96
	ds_read_b64 v[126:127], v188 offset:104
	ds_read_b64 v[128:129], v188 offset:80
	ds_read_b64 v[130:131], v188 offset:88
	ds_read_b64 v[132:133], v188 offset:112
	ds_read_b64 v[134:135], v188 offset:120
	s_waitcnt lgkmcnt(10)
	v_pk_add_f32 v[176:177], v[104:105], v[112:113]
	v_pk_add_f32 v[104:105], v[104:105], v[112:113] neg_lo:[0,1] neg_hi:[0,1]
	s_waitcnt lgkmcnt(4)
	v_pk_add_f32 v[112:113], v[116:117], v[124:125]
	v_pk_add_f32 v[116:117], v[116:117], v[124:125] neg_lo:[0,1] neg_hi:[0,1]
	v_add_u32_e32 v189, 0, v182
	v_xor_b32_e32 v125, 0x80000000, v116
	v_mov_b32_e32 v124, v117
	v_pk_add_f32 v[116:117], v[176:177], v[112:113]
	v_pk_add_f32 v[112:113], v[176:177], v[112:113] neg_lo:[0,1] neg_hi:[0,1]
	v_pk_add_f32 v[176:177], v[104:105], v[124:125]
	v_pk_add_f32 v[104:105], v[104:105], v[124:125] neg_lo:[0,1] neg_hi:[0,1]
	v_pk_add_f32 v[124:125], v[106:107], v[114:115]
	v_pk_add_f32 v[106:107], v[106:107], v[114:115] neg_lo:[0,1] neg_hi:[0,1]
	v_pk_add_f32 v[114:115], v[118:119], v[126:127]
	v_pk_add_f32 v[118:119], v[118:119], v[126:127] neg_lo:[0,1] neg_hi:[0,1]
	s_nop 0
	v_xor_b32_e32 v127, 0x80000000, v118
	v_mov_b32_e32 v126, v119
	v_pk_add_f32 v[118:119], v[124:125], v[114:115]
	v_pk_add_f32 v[114:115], v[124:125], v[114:115] neg_lo:[0,1] neg_hi:[0,1]
	v_pk_add_f32 v[124:125], v[106:107], v[126:127]
	v_pk_add_f32 v[106:107], v[106:107], v[126:127] neg_lo:[0,1] neg_hi:[0,1]
	s_waitcnt lgkmcnt(2)
	v_pk_add_f32 v[126:127], v[108:109], v[128:129]
	v_pk_add_f32 v[108:109], v[108:109], v[128:129] neg_lo:[0,1] neg_hi:[0,1]
	s_waitcnt lgkmcnt(0)
	v_pk_add_f32 v[128:129], v[120:121], v[132:133]
	v_pk_add_f32 v[120:121], v[120:121], v[132:133] neg_lo:[0,1] neg_hi:[0,1]
	s_nop 0
	v_xor_b32_e32 v133, 0x80000000, v120
	v_mov_b32_e32 v132, v121
	v_pk_add_f32 v[120:121], v[126:127], v[128:129]
	v_pk_add_f32 v[126:127], v[126:127], v[128:129] neg_lo:[0,1] neg_hi:[0,1]
	v_pk_add_f32 v[128:129], v[108:109], v[132:133]
	v_pk_add_f32 v[108:109], v[108:109], v[132:133] neg_lo:[0,1] neg_hi:[0,1]
	v_pk_add_f32 v[132:133], v[110:111], v[130:131]
	v_pk_add_f32 v[110:111], v[110:111], v[130:131] neg_lo:[0,1] neg_hi:[0,1]
	v_pk_add_f32 v[130:131], v[122:123], v[134:135]
	v_pk_add_f32 v[122:123], v[122:123], v[134:135] neg_lo:[0,1] neg_hi:[0,1]
	s_nop 0
	v_xor_b32_e32 v135, 0x80000000, v122
	v_mov_b32_e32 v134, v123
	v_pk_add_f32 v[122:123], v[132:133], v[130:131]
	v_pk_add_f32 v[130:131], v[132:133], v[130:131] neg_lo:[0,1] neg_hi:[0,1]
	v_pk_add_f32 v[132:133], v[110:111], v[134:135]
	v_pk_add_f32 v[110:111], v[110:111], v[134:135] neg_lo:[0,1] neg_hi:[0,1]
	v_pk_mul_f32 v[134:135], v[124:125], s[30:31] op_sel_hi:[1,0]
	s_nop 0
	v_pk_fma_f32 v[178:179], v[124:125], s[22:23], v[134:135] op_sel:[0,0,1] op_sel_hi:[1,0,0]
	v_pk_fma_f32 v[124:125], v[124:125], s[22:23], v[134:135] op_sel:[0,0,1] op_sel_hi:[1,0,0] neg_lo:[0,0,1] neg_hi:[0,0,1]
	s_nop 0
	v_mov_b32_e32 v179, v125
	v_pk_mul_f32 v[124:125], v[114:115], s[24:25] op_sel_hi:[1,0]
	s_nop 0
	v_pk_fma_f32 v[134:135], v[114:115], s[24:25], v[124:125] op_sel:[0,0,1] op_sel_hi:[1,0,0]
	v_pk_fma_f32 v[114:115], v[114:115], s[24:25], v[124:125] op_sel_hi:[1,0,0] neg_lo:[0,0,1] neg_hi:[0,0,1]
	s_nop 0
	v_mov_b32_e32 v135, v115
	v_pk_mul_f32 v[114:115], v[106:107], s[22:23] op_sel_hi:[1,0]
	s_nop 0
	v_pk_fma_f32 v[124:125], v[106:107], s[30:31], v[114:115] op_sel:[0,0,1] op_sel_hi:[1,0,0]
	v_pk_fma_f32 v[106:107], v[106:107], s[30:31], v[114:115] op_sel:[0,0,1] op_sel_hi:[1,0,0] neg_lo:[0,0,1] neg_hi:[0,0,1]
	s_nop 0
	v_mov_b32_e32 v125, v107
	v_pk_mul_f32 v[106:107], v[128:129], s[24:25] op_sel_hi:[1,0]
	s_nop 0
	v_pk_fma_f32 v[114:115], v[128:129], s[24:25], v[106:107] op_sel:[0,0,1] op_sel_hi:[1,0,0]
	v_pk_fma_f32 v[106:107], v[128:129], s[24:25], v[106:107] op_sel_hi:[1,0,0] neg_lo:[0,0,1] neg_hi:[0,0,1]
	s_nop 0
	v_mov_b32_e32 v115, v107
	v_xor_b32_e32 v107, 0x80000000, v126
	v_mul_f32_e32 v126, 0x3f3504f3, v108
	v_mov_b32_e32 v106, v127
	v_pk_fma_f32 v[108:109], v[108:109], s[24:25], v[126:127] op_sel:[1,0,0] op_sel_hi:[1,1,0] neg_lo:[0,0,1] neg_hi:[0,0,1]
	v_pk_mul_f32 v[126:127], v[132:133], s[22:23] op_sel_hi:[1,0]
	s_nop 0
	v_pk_fma_f32 v[128:129], v[132:133], s[30:31], v[126:127] op_sel:[0,0,1] op_sel_hi:[1,0,0]
	v_pk_fma_f32 v[126:127], v[132:133], s[30:31], v[126:127] op_sel:[0,0,1] op_sel_hi:[1,0,0] neg_lo:[0,0,1] neg_hi:[0,0,1]
	s_nop 0
	v_mul_f32_e32 v126, 0x3f3504f3, v130
	v_mov_b32_e32 v129, v127
	v_pk_fma_f32 v[126:127], v[130:131], s[24:25], v[126:127] op_sel:[1,0,0] op_sel_hi:[1,1,0] neg_lo:[0,0,1] neg_hi:[0,0,1]
	v_pk_mul_f32 v[130:131], v[110:111], s[30:31]
	v_pk_add_f32 v[132:133], v[178:179], v[128:129]
	v_pk_fma_f32 v[110:111], v[110:111], s[22:23], v[130:131] op_sel:[0,0,1] op_sel_hi:[1,0,0] neg_lo:[1,0,0] neg_hi:[1,0,0]
	v_pk_add_f32 v[130:131], v[116:117], v[120:121]
	v_pk_add_f32 v[116:117], v[116:117], v[120:121] neg_lo:[0,1] neg_hi:[0,1]
	v_pk_add_f32 v[120:121], v[118:119], v[122:123]
	v_pk_add_f32 v[118:119], v[118:119], v[122:123] neg_lo:[0,1] neg_hi:[0,1]
	v_pk_add_f32 v[128:129], v[178:179], v[128:129] neg_lo:[0,1] neg_hi:[0,1]
	v_xor_b32_e32 v123, 0x80000000, v118
	v_mov_b32_e32 v122, v119
	v_pk_add_f32 v[118:119], v[130:131], v[120:121]
	v_pk_add_f32 v[120:121], v[130:131], v[120:121] neg_lo:[0,1] neg_hi:[0,1]
	v_pk_add_f32 v[130:131], v[116:117], v[122:123]
	v_pk_add_f32 v[116:117], v[116:117], v[122:123] neg_lo:[0,1] neg_hi:[0,1]
	v_pk_add_f32 v[122:123], v[176:177], v[114:115]
	v_pk_add_f32 v[114:115], v[176:177], v[114:115] neg_lo:[0,1] neg_hi:[0,1]
	v_xor_b32_e32 v177, 0x80000000, v128
	v_mov_b32_e32 v176, v129
	v_pk_add_f32 v[128:129], v[122:123], v[132:133]
	v_pk_add_f32 v[122:123], v[122:123], v[132:133] neg_lo:[0,1] neg_hi:[0,1]
	v_pk_add_f32 v[132:133], v[114:115], v[176:177]
	v_pk_add_f32 v[114:115], v[114:115], v[176:177] neg_lo:[0,1] neg_hi:[0,1]
	v_pk_add_f32 v[176:177], v[112:113], v[106:107]
	v_pk_add_f32 v[106:107], v[112:113], v[106:107] neg_lo:[0,1] neg_hi:[0,1]
	v_pk_add_f32 v[112:113], v[134:135], v[126:127]
	v_pk_add_f32 v[126:127], v[134:135], v[126:127] neg_lo:[0,1] neg_hi:[0,1]
	v_pk_add_f32 v[178:179], v[104:105], v[108:109]
	v_xor_b32_e32 v135, 0x80000000, v126
	v_mov_b32_e32 v134, v127
	v_pk_add_f32 v[108:109], v[104:105], v[108:109] neg_lo:[0,1] neg_hi:[0,1]
	v_pk_add_f32 v[104:105], v[124:125], v[110:111] neg_lo:[0,1] neg_hi:[0,1]
	v_pk_add_f32 v[126:127], v[176:177], v[112:113]
	v_pk_add_f32 v[112:113], v[176:177], v[112:113] neg_lo:[0,1] neg_hi:[0,1]
	v_pk_add_f32 v[176:177], v[106:107], v[134:135]
	v_pk_add_f32 v[134:135], v[106:107], v[134:135] neg_lo:[0,1] neg_hi:[0,1]
	v_pk_add_f32 v[180:181], v[124:125], v[110:111]
	v_xor_b32_e32 v111, 0x80000000, v104
	v_mov_b32_e32 v110, v105
	ds_read_b64 v[104:105], v189
	ds_read_b64 v[106:107], v189 offset:8
	v_pk_add_f32 v[124:125], v[178:179], v[180:181]
	v_pk_add_f32 v[178:179], v[178:179], v[180:181] neg_lo:[0,1] neg_hi:[0,1]
	v_pk_add_f32 v[180:181], v[108:109], v[110:111]
	v_pk_add_f32 v[182:183], v[108:109], v[110:111] neg_lo:[0,1] neg_hi:[0,1]
	ds_read_b64 v[108:109], v189 offset:16
	ds_read_b64 v[110:111], v189 offset:24
	s_waitcnt lgkmcnt(2)
	v_pk_mul_f32 v[184:185], v[104:105], v[118:119] op_sel:[1,1] op_sel_hi:[0,1]
	v_pk_fma_f32 v[186:187], v[104:105], v[118:119], v[184:185] neg_lo:[0,0,1] neg_hi:[0,0,1]
	v_pk_fma_f32 v[104:105], v[104:105], v[118:119], v[184:185] op_sel_hi:[1,0,1]
	s_nop 0
	v_mov_b32_e32 v187, v105
	v_pk_mul_f32 v[104:105], v[106:107], v[128:129] op_sel:[1,1] op_sel_hi:[0,1]
	v_pk_fma_f32 v[184:185], v[106:107], v[128:129], v[104:105] neg_lo:[0,0,1] neg_hi:[0,0,1]
	v_pk_fma_f32 v[104:105], v[106:107], v[128:129], v[104:105] op_sel_hi:[1,0,1]
	v_pk_mul_f32 v[118:119], v[28:29], v[186:187]
	v_mov_b32_e32 v185, v105
	s_waitcnt lgkmcnt(0)
	v_pk_mul_f32 v[104:105], v[108:109], v[126:127] op_sel:[1,1] op_sel_hi:[0,1]
	v_pk_fma_f32 v[106:107], v[108:109], v[126:127], v[104:105] neg_lo:[0,0,1] neg_hi:[0,0,1]
	v_pk_fma_f32 v[104:105], v[108:109], v[126:127], v[104:105] op_sel_hi:[1,0,1]
	v_pk_mul_f32 v[108:109], v[110:111], v[124:125] op_sel:[1,1] op_sel_hi:[0,1]
	v_mov_b32_e32 v107, v105
	v_pk_mul_f32 v[126:127], v[28:29], v[106:107]
	ds_read_b64 v[104:105], v189 offset:32
	ds_read_b64 v[106:107], v189 offset:40
	v_pk_mul_f32 v[128:129], v[28:29], v[184:185]
	v_pk_fma_f32 v[184:185], v[110:111], v[124:125], v[108:109] neg_lo:[0,0,1] neg_hi:[0,0,1]
	v_pk_fma_f32 v[108:109], v[110:111], v[124:125], v[108:109] op_sel_hi:[1,0,1]
	s_nop 0
	v_mov_b32_e32 v185, v109
	ds_read_b64 v[108:109], v189 offset:48
	ds_read_b64 v[110:111], v189 offset:56
	v_pk_mul_f32 v[124:125], v[28:29], v[184:185]
	s_waitcnt lgkmcnt(2)
	v_pk_mul_f32 v[184:185], v[104:105], v[130:131] op_sel:[1,1] op_sel_hi:[0,1]
	v_pk_fma_f32 v[186:187], v[104:105], v[130:131], v[184:185] neg_lo:[0,0,1] neg_hi:[0,0,1]
	v_pk_fma_f32 v[104:105], v[104:105], v[130:131], v[184:185] op_sel_hi:[1,0,1]
	s_nop 0
	v_mov_b32_e32 v187, v105
	v_pk_mul_f32 v[104:105], v[106:107], v[132:133] op_sel:[1,1] op_sel_hi:[0,1]
	v_pk_fma_f32 v[184:185], v[106:107], v[132:133], v[104:105] neg_lo:[0,0,1] neg_hi:[0,0,1]
	v_pk_fma_f32 v[104:105], v[106:107], v[132:133], v[104:105] op_sel_hi:[1,0,1]
	v_pk_mul_f32 v[130:131], v[28:29], v[186:187]
	v_mov_b32_e32 v185, v105
	s_waitcnt lgkmcnt(0)
	v_pk_mul_f32 v[104:105], v[108:109], v[176:177] op_sel:[1,1] op_sel_hi:[0,1]
	v_pk_fma_f32 v[106:107], v[108:109], v[176:177], v[104:105] neg_lo:[0,0,1] neg_hi:[0,0,1]
	v_pk_fma_f32 v[104:105], v[108:109], v[176:177], v[104:105] op_sel_hi:[1,0,1]
	v_pk_mul_f32 v[108:109], v[110:111], v[180:181] op_sel:[1,1] op_sel_hi:[0,1]
	v_mov_b32_e32 v107, v105
	v_pk_mul_f32 v[176:177], v[28:29], v[106:107]
	ds_read_b64 v[104:105], v189 offset:64
	ds_read_b64 v[106:107], v189 offset:72
	v_pk_mul_f32 v[132:133], v[28:29], v[184:185]
	v_pk_fma_f32 v[184:185], v[110:111], v[180:181], v[108:109] neg_lo:[0,0,1] neg_hi:[0,0,1]
	v_pk_fma_f32 v[108:109], v[110:111], v[180:181], v[108:109] op_sel_hi:[1,0,1]
	s_nop 0
	v_mov_b32_e32 v185, v109
	ds_read_b64 v[108:109], v189 offset:80
	ds_read_b64 v[110:111], v189 offset:88
	v_pk_mul_f32 v[180:181], v[28:29], v[184:185]
	s_waitcnt lgkmcnt(2)
	v_pk_mul_f32 v[184:185], v[120:121], v[104:105] op_sel:[1,1] op_sel_hi:[1,0]
	s_nop 0
	v_pk_fma_f32 v[186:187], v[120:121], v[104:105], v[184:185] neg_lo:[0,0,1] neg_hi:[0,0,1]
	v_pk_fma_f32 v[104:105], v[120:121], v[104:105], v[184:185] op_sel_hi:[0,1,1]
	v_mov_b32_e32 v187, v105
	v_pk_mul_f32 v[104:105], v[106:107], v[122:123] op_sel:[1,1] op_sel_hi:[0,1]
	v_pk_fma_f32 v[184:185], v[106:107], v[122:123], v[104:105] neg_lo:[0,0,1] neg_hi:[0,0,1]
	v_pk_fma_f32 v[104:105], v[106:107], v[122:123], v[104:105] op_sel_hi:[1,0,1]
	v_pk_mul_f32 v[120:121], v[28:29], v[186:187]
	v_mov_b32_e32 v185, v105
	s_waitcnt lgkmcnt(0)
	v_pk_mul_f32 v[104:105], v[112:113], v[108:109] op_sel:[1,1] op_sel_hi:[1,0]
	v_pk_mul_f32 v[122:123], v[28:29], v[184:185]
	v_pk_fma_f32 v[106:107], v[112:113], v[108:109], v[104:105] neg_lo:[0,0,1] neg_hi:[0,0,1]
	v_pk_fma_f32 v[104:105], v[112:113], v[108:109], v[104:105] op_sel_hi:[0,1,1]
	v_mov_b32_e32 v107, v105
	v_pk_mul_f32 v[112:113], v[28:29], v[106:107]
	v_pk_mul_f32 v[108:109], v[178:179], v[110:111] op_sel:[1,1] op_sel_hi:[1,0]
	ds_read_b64 v[104:105], v189 offset:96
	ds_read_b64 v[106:107], v189 offset:104
	v_pk_fma_f32 v[184:185], v[178:179], v[110:111], v[108:109] neg_lo:[0,0,1] neg_hi:[0,0,1]
	v_pk_fma_f32 v[108:109], v[178:179], v[110:111], v[108:109] op_sel_hi:[0,1,1]
	v_mov_b32_e32 v185, v109
	ds_read_b64 v[108:109], v189 offset:112
	ds_read_b64 v[110:111], v189 offset:120
	v_pk_mul_f32 v[178:179], v[28:29], v[184:185]
	s_waitcnt lgkmcnt(2)
	v_pk_mul_f32 v[184:185], v[116:117], v[104:105] op_sel:[1,1] op_sel_hi:[1,0]
	s_nop 0
	v_pk_fma_f32 v[186:187], v[116:117], v[104:105], v[184:185] neg_lo:[0,0,1] neg_hi:[0,0,1]
	v_pk_fma_f32 v[104:105], v[116:117], v[104:105], v[184:185] op_sel_hi:[0,1,1]
	v_pk_mul_f32 v[116:117], v[106:107], v[114:115] op_sel:[1,1] op_sel_hi:[0,1]
	v_pk_fma_f32 v[184:185], v[106:107], v[114:115], v[116:117] neg_lo:[0,0,1] neg_hi:[0,0,1]
	v_pk_fma_f32 v[106:107], v[106:107], v[114:115], v[116:117] op_sel_hi:[1,0,1]
	s_waitcnt lgkmcnt(0)
	v_pk_mul_f32 v[114:115], v[134:135], v[108:109] op_sel:[1,1] op_sel_hi:[1,0]
	v_mov_b32_e32 v187, v105
	v_pk_fma_f32 v[116:117], v[134:135], v[108:109], v[114:115] neg_lo:[0,0,1] neg_hi:[0,0,1]
	v_pk_fma_f32 v[108:109], v[134:135], v[108:109], v[114:115] op_sel_hi:[0,1,1]
	v_mov_b32_e32 v117, v109
	v_pk_mul_f32 v[114:115], v[182:183], v[110:111] op_sel:[1,1] op_sel_hi:[1,0]
	v_pk_mul_f32 v[108:109], v[28:29], v[116:117]
	v_pk_fma_f32 v[116:117], v[182:183], v[110:111], v[114:115] neg_lo:[0,0,1] neg_hi:[0,0,1]
	v_pk_fma_f32 v[110:111], v[182:183], v[110:111], v[114:115] op_sel_hi:[0,1,1]
	v_pk_mul_f32 v[104:105], v[28:29], v[186:187]
	v_mov_b32_e32 v185, v107
	v_mov_b32_e32 v117, v111
	v_pk_mul_f32 v[106:107], v[28:29], v[184:185]
	v_pk_mul_f32 v[110:111], v[28:29], v[116:117]
	ds_write2_b64 v188, v[118:119], v[128:129] offset1:1
	ds_write2_b64 v188, v[126:127], v[124:125] offset0:2 offset1:3
	ds_write2_b64 v188, v[130:131], v[132:133] offset0:4 offset1:5
	ds_write2_b64 v188, v[176:177], v[180:181] offset0:6 offset1:7
	ds_write2_b64 v188, v[120:121], v[122:123] offset0:8 offset1:9
	ds_write2_b64 v188, v[112:113], v[178:179] offset0:10 offset1:11
	ds_write2_b64 v188, v[104:105], v[106:107] offset0:12 offset1:13
	ds_write2_b64 v188, v[108:109], v[110:111] offset0:14 offset1:15
	v_mov_b32_e32 v104, v208
	s_waitcnt lgkmcnt(0)
	s_barrier
	s_nop 0
	v_lshlrev_b32_e32 v105, 4, v104
	v_ashrrev_i32_e32 v105, 1, v105
	v_lshlrev_b32_e32 v104, 7, v104
	v_add3_u32 v180, s35, v105, v104
	ds_read_b64 v[104:105], v180
	ds_read_b64 v[106:107], v180 offset:8
	ds_read_b64 v[108:109], v180 offset:16
	ds_read_b64 v[110:111], v180 offset:24
	ds_read_b64 v[112:113], v180 offset:64
	ds_read_b64 v[114:115], v180 offset:72
	ds_read_b64 v[116:117], v180 offset:32
	ds_read_b64 v[118:119], v180 offset:40
	ds_read_b64 v[120:121], v180 offset:48
	ds_read_b64 v[122:123], v180 offset:56
	ds_read_b64 v[124:125], v180 offset:96
	ds_read_b64 v[126:127], v180 offset:104
	ds_read_b64 v[128:129], v180 offset:80
	ds_read_b64 v[130:131], v180 offset:88
	ds_read_b64 v[132:133], v180 offset:112
	ds_read_b64 v[134:135], v180 offset:120
	s_waitcnt lgkmcnt(10)
	v_pk_add_f32 v[176:177], v[104:105], v[112:113]
	v_pk_add_f32 v[104:105], v[104:105], v[112:113] neg_lo:[0,1] neg_hi:[0,1]
	s_waitcnt lgkmcnt(4)
	v_pk_add_f32 v[112:113], v[116:117], v[124:125]
	v_pk_add_f32 v[116:117], v[116:117], v[124:125] neg_lo:[0,1] neg_hi:[0,1]
	s_nop 0
	v_xor_b32_e32 v124, 0x80000000, v117
	v_mov_b32_e32 v125, v116
	v_pk_add_f32 v[116:117], v[176:177], v[112:113]
	v_pk_add_f32 v[112:113], v[176:177], v[112:113] neg_lo:[0,1] neg_hi:[0,1]
	v_pk_add_f32 v[176:177], v[104:105], v[124:125]
	v_pk_add_f32 v[104:105], v[104:105], v[124:125] neg_lo:[0,1] neg_hi:[0,1]
	v_pk_add_f32 v[124:125], v[106:107], v[114:115]
	v_pk_add_f32 v[106:107], v[106:107], v[114:115] neg_lo:[0,1] neg_hi:[0,1]
	v_pk_add_f32 v[114:115], v[118:119], v[126:127]
	v_pk_add_f32 v[118:119], v[118:119], v[126:127] neg_lo:[0,1] neg_hi:[0,1]
	s_nop 0
	v_xor_b32_e32 v126, 0x80000000, v119
	v_mov_b32_e32 v127, v118
	v_pk_add_f32 v[118:119], v[124:125], v[114:115]
	v_pk_add_f32 v[114:115], v[124:125], v[114:115] neg_lo:[0,1] neg_hi:[0,1]
	v_pk_add_f32 v[124:125], v[106:107], v[126:127]
	v_pk_add_f32 v[106:107], v[106:107], v[126:127] neg_lo:[0,1] neg_hi:[0,1]
	s_waitcnt lgkmcnt(2)
	v_pk_add_f32 v[126:127], v[108:109], v[128:129]
	v_pk_add_f32 v[108:109], v[108:109], v[128:129] neg_lo:[0,1] neg_hi:[0,1]
	s_waitcnt lgkmcnt(0)
	v_pk_add_f32 v[128:129], v[120:121], v[132:133]
	v_pk_add_f32 v[120:121], v[120:121], v[132:133] neg_lo:[0,1] neg_hi:[0,1]
	s_nop 0
	v_xor_b32_e32 v132, 0x80000000, v121
	v_mov_b32_e32 v133, v120
	v_pk_add_f32 v[120:121], v[126:127], v[128:129]
	v_pk_add_f32 v[126:127], v[126:127], v[128:129] neg_lo:[0,1] neg_hi:[0,1]
	v_pk_add_f32 v[128:129], v[108:109], v[132:133]
	v_pk_add_f32 v[108:109], v[108:109], v[132:133] neg_lo:[0,1] neg_hi:[0,1]
	v_pk_add_f32 v[132:133], v[110:111], v[130:131]
	v_pk_add_f32 v[110:111], v[110:111], v[130:131] neg_lo:[0,1] neg_hi:[0,1]
	v_pk_add_f32 v[130:131], v[122:123], v[134:135]
	v_pk_add_f32 v[122:123], v[122:123], v[134:135] neg_lo:[0,1] neg_hi:[0,1]
	s_nop 0
	v_xor_b32_e32 v134, 0x80000000, v123
	v_mov_b32_e32 v135, v122
	v_pk_add_f32 v[122:123], v[132:133], v[130:131]
	v_pk_add_f32 v[130:131], v[132:133], v[130:131] neg_lo:[0,1] neg_hi:[0,1]
	v_pk_add_f32 v[132:133], v[110:111], v[134:135]
	v_pk_add_f32 v[110:111], v[110:111], v[134:135] neg_lo:[0,1] neg_hi:[0,1]
	v_pk_mul_f32 v[134:135], v[124:125], s[30:31] op_sel_hi:[1,0]
	s_nop 0
	v_pk_fma_f32 v[178:179], v[124:125], s[22:23], v[134:135] op_sel:[0,0,1] op_sel_hi:[1,0,0] neg_lo:[0,0,1] neg_hi:[0,0,1]
	v_pk_fma_f32 v[124:125], v[124:125], s[22:23], v[134:135] op_sel:[0,0,1] op_sel_hi:[1,0,0]
	s_nop 0
	v_mov_b32_e32 v179, v125
	v_pk_mul_f32 v[124:125], v[114:115], s[24:25] op_sel_hi:[1,0]
	s_nop 0
	v_pk_fma_f32 v[134:135], v[114:115], s[24:25], v[124:125] op_sel:[0,0,1] op_sel_hi:[1,0,0] neg_lo:[0,0,1] neg_hi:[0,0,1]
	v_pk_fma_f32 v[114:115], v[114:115], s[24:25], v[124:125] op_sel_hi:[1,0,0]
	s_nop 0
	v_mov_b32_e32 v135, v115
	v_pk_mul_f32 v[114:115], v[106:107], s[22:23] op_sel_hi:[1,0]
	s_nop 0
	v_pk_fma_f32 v[124:125], v[106:107], s[30:31], v[114:115] op_sel:[0,0,1] op_sel_hi:[1,0,0] neg_lo:[0,0,1] neg_hi:[0,0,1]
	v_pk_fma_f32 v[106:107], v[106:107], s[30:31], v[114:115] op_sel:[0,0,1] op_sel_hi:[1,0,0]
	s_nop 0
	v_mov_b32_e32 v125, v107
	v_pk_mul_f32 v[106:107], v[128:129], s[24:25] op_sel_hi:[1,0]
	s_nop 0
	v_pk_fma_f32 v[114:115], v[128:129], s[24:25], v[106:107] op_sel:[0,0,1] op_sel_hi:[1,0,0] neg_lo:[0,0,1] neg_hi:[0,0,1]
	v_pk_fma_f32 v[106:107], v[128:129], s[24:25], v[106:107] op_sel_hi:[1,0,0]
	s_nop 0
	v_mov_b32_e32 v115, v107
	v_mov_b32_e32 v107, v126
	v_mul_f32_e32 v126, 0x3f3504f3, v109
	v_xor_b32_e32 v106, 0x80000000, v127
	v_pk_fma_f32 v[108:109], v[108:109], s[18:19], v[126:127] op_sel_hi:[0,1,0] neg_lo:[0,0,1] neg_hi:[0,0,1]
	v_pk_mul_f32 v[126:127], v[132:133], s[22:23] op_sel_hi:[1,0]
	s_nop 0
	v_pk_fma_f32 v[128:129], v[132:133], s[30:31], v[126:127] op_sel:[0,0,1] op_sel_hi:[1,0,0] neg_lo:[0,0,1] neg_hi:[0,0,1]
	v_pk_fma_f32 v[126:127], v[132:133], s[30:31], v[126:127] op_sel:[0,0,1] op_sel_hi:[1,0,0]
	s_nop 0
	v_mul_f32_e32 v126, 0x3f3504f3, v131
	v_mov_b32_e32 v129, v127
	v_pk_fma_f32 v[126:127], v[130:131], s[18:19], v[126:127] op_sel_hi:[0,1,0] neg_lo:[0,0,1] neg_hi:[0,0,1]
	v_pk_mul_f32 v[130:131], v[110:111], s[88:89]
	v_pk_add_f32 v[132:133], v[178:179], v[128:129]
	v_pk_fma_f32 v[110:111], v[110:111], s[22:23], v[130:131] op_sel:[0,0,1] op_sel_hi:[1,0,0] neg_lo:[1,0,0] neg_hi:[1,0,0]
	v_pk_add_f32 v[130:131], v[116:117], v[120:121]
	v_pk_add_f32 v[116:117], v[116:117], v[120:121] neg_lo:[0,1] neg_hi:[0,1]
	v_pk_add_f32 v[120:121], v[118:119], v[122:123]
	v_pk_add_f32 v[118:119], v[118:119], v[122:123] neg_lo:[0,1] neg_hi:[0,1]
	v_pk_add_f32 v[128:129], v[178:179], v[128:129] neg_lo:[0,1] neg_hi:[0,1]
	v_xor_b32_e32 v122, 0x80000000, v119
	v_mov_b32_e32 v123, v118
	v_pk_add_f32 v[118:119], v[130:131], v[120:121]
	v_pk_add_f32 v[120:121], v[130:131], v[120:121] neg_lo:[0,1] neg_hi:[0,1]
	v_pk_add_f32 v[130:131], v[116:117], v[122:123]
	v_pk_add_f32 v[116:117], v[116:117], v[122:123] neg_lo:[0,1] neg_hi:[0,1]
	v_pk_add_f32 v[122:123], v[176:177], v[114:115]
	v_pk_add_f32 v[114:115], v[176:177], v[114:115] neg_lo:[0,1] neg_hi:[0,1]
	v_xor_b32_e32 v176, 0x80000000, v129
	v_mov_b32_e32 v177, v128
	v_pk_add_f32 v[128:129], v[122:123], v[132:133]
	v_pk_add_f32 v[122:123], v[122:123], v[132:133] neg_lo:[0,1] neg_hi:[0,1]
	v_pk_add_f32 v[132:133], v[114:115], v[176:177]
	v_pk_add_f32 v[114:115], v[114:115], v[176:177] neg_lo:[0,1] neg_hi:[0,1]
	v_pk_add_f32 v[176:177], v[112:113], v[106:107]
	v_pk_add_f32 v[106:107], v[112:113], v[106:107] neg_lo:[0,1] neg_hi:[0,1]
	v_pk_add_f32 v[112:113], v[134:135], v[126:127]
	v_pk_add_f32 v[126:127], v[134:135], v[126:127] neg_lo:[0,1] neg_hi:[0,1]
	s_nop 0
	v_xor_b32_e32 v134, 0x80000000, v127
	v_mov_b32_e32 v135, v126
	v_pk_add_f32 v[126:127], v[176:177], v[112:113]
	v_pk_add_f32 v[112:113], v[176:177], v[112:113] neg_lo:[0,1] neg_hi:[0,1]
	v_pk_add_f32 v[176:177], v[106:107], v[134:135]
	v_pk_add_f32 v[106:107], v[106:107], v[134:135] neg_lo:[0,1] neg_hi:[0,1]
	v_pk_add_f32 v[134:135], v[104:105], v[108:109]
	v_pk_add_f32 v[104:105], v[104:105], v[108:109] neg_lo:[0,1] neg_hi:[0,1]
	v_pk_add_f32 v[108:109], v[124:125], v[110:111]
	v_pk_add_f32 v[110:111], v[124:125], v[110:111] neg_lo:[0,1] neg_hi:[0,1]
	s_nop 0
	v_xor_b32_e32 v124, 0x80000000, v111
	v_mov_b32_e32 v125, v110
	v_pk_add_f32 v[110:111], v[134:135], v[108:109]
	v_pk_add_f32 v[108:109], v[134:135], v[108:109] neg_lo:[0,1] neg_hi:[0,1]
	v_pk_add_f32 v[134:135], v[104:105], v[124:125]
	v_pk_add_f32 v[104:105], v[104:105], v[124:125] neg_lo:[0,1] neg_hi:[0,1]
	ds_write2_b64 v180, v[118:119], v[128:129] offset1:1
	ds_write2_b64 v180, v[126:127], v[110:111] offset0:2 offset1:3
	ds_write2_b64 v180, v[130:131], v[132:133] offset0:4 offset1:5
	ds_write2_b64 v180, v[176:177], v[134:135] offset0:6 offset1:7
	ds_write2_b64 v180, v[120:121], v[122:123] offset0:8 offset1:9
	ds_write2_b64 v180, v[112:113], v[108:109] offset0:10 offset1:11
	ds_write2_b64 v180, v[116:117], v[114:115] offset0:12 offset1:13
	ds_write2_b64 v180, v[106:107], v[104:105] offset0:14 offset1:15
	v_mov_b32_e32 v104, v208
	s_waitcnt lgkmcnt(0)
	s_nop 0
	v_and_b32_e32 v128, 15, v104
	v_lshlrev_b32_e32 v106, 3, v128
	v_cvt_f32_ubyte0_e32 v128, v128
	v_mul_f32_e32 v205, 0x3b800000, v128
	v_mul_f32_e32 v128, 0x41400000, v205
	v_sin_f32_e32 v176, v128
	v_sin_f32_e32 v178, v205
	v_cos_f32_e32 v177, v128
	v_cos_f32_e32 v180, v205
	v_lshlrev_b32_e32 v104, 4, v104
	v_and_b32_e32 v104, 0xffffff00, v104
	v_pk_mul_f32 v[182:183], v[178:179], v[176:177] op_sel_hi:[0,1]
	v_ashrrev_i32_e32 v105, 1, v104
	v_pk_fma_f32 v[184:185], v[180:181], v[176:177], v[182:183] op_sel:[0,0,1] op_sel_hi:[0,1,0]
	v_pk_fma_f32 v[182:183], v[180:181], v[176:177], v[182:183] op_sel:[0,0,1] op_sel_hi:[0,1,0] neg_lo:[0,0,1] neg_hi:[0,0,1]
	v_add_u32_e32 v105, s35, v105
	v_lshlrev_b32_e32 v104, 3, v104
	v_pk_mov_b32 v[188:189], v[182:183], v[184:185] op_sel:[1,0]
	v_add3_u32 v204, v105, v104, v106
	v_pk_mov_b32 v[186:187], v[184:185], v[182:183] op_sel:[0,1]
	v_pk_mul_f32 v[188:189], v[178:179], v[188:189] op_sel_hi:[0,1]
	v_mov_b32_e32 v179, v180
	ds_read_b64 v[104:105], v204
	ds_read_b64 v[106:107], v204 offset:136
	ds_read_b64 v[108:109], v204 offset:272
	ds_read_b64 v[110:111], v204 offset:408
	ds_read_b64 v[112:113], v204 offset:544
	ds_read_b64 v[114:115], v204 offset:680
	ds_read_b64 v[116:117], v204 offset:816
	ds_read_b64 v[118:119], v204 offset:952
	ds_read_b64 v[120:121], v204 offset:1088
	ds_read_b64 v[122:123], v204 offset:1224
	ds_read_b64 v[124:125], v204 offset:1360
	ds_read_b64 v[126:127], v204 offset:1496
	v_pk_fma_f32 v[190:191], v[180:181], v[186:187], v[188:189] op_sel_hi:[0,1,1]
	v_pk_fma_f32 v[186:187], v[180:181], v[186:187], v[188:189] op_sel_hi:[0,1,1] neg_lo:[0,0,1] neg_hi:[0,0,1]
	v_mov_b32_e32 v181, v178
	s_waitcnt lgkmcnt(10)
	v_pk_mul_f32 v[194:195], v[106:107], v[178:179] op_sel_hi:[1,0]
	ds_read_b64 v[128:129], v204 offset:1632
	ds_read_b64 v[130:131], v204 offset:1768
	ds_read_b64 v[132:133], v204 offset:1904
	ds_read_b64 v[134:135], v204 offset:2040
	v_pk_fma_f32 v[196:197], v[106:107], v[180:181], v[194:195] op_sel:[0,0,1] op_sel_hi:[1,1,0] neg_lo:[0,0,1] neg_hi:[0,0,1]
	v_pk_fma_f32 v[106:107], v[106:107], v[180:181], v[194:195] op_sel:[0,0,1] op_sel_hi:[1,0,0]
	v_mov_b32_e32 v188, v190
	v_mov_b32_e32 v197, v107
	v_pk_mul_f32 v[106:107], v[178:179], v[178:179] op_sel:[0,1] op_sel_hi:[0,0]
	v_pk_fma_f32 v[194:195], v[180:181], v[178:179], v[106:107] op_sel_hi:[0,1,1]
	v_pk_fma_f32 v[106:107], v[180:181], v[178:179], v[106:107] op_sel_hi:[0,1,1] neg_lo:[0,0,1] neg_hi:[0,0,1]
	v_pk_mov_b32 v[198:199], v[194:195], v[106:107] op_sel:[0,1]
	s_waitcnt lgkmcnt(12)
	v_pk_mul_f32 v[194:195], v[108:109], v[194:195] op_sel:[1,0] op_sel_hi:[0,0]
	v_pk_fma_f32 v[200:201], v[108:109], v[106:107], v[194:195] op_sel:[0,1,0] neg_lo:[0,0,1] neg_hi:[0,0,1]
	v_pk_fma_f32 v[106:107], v[108:109], v[106:107], v[194:195] op_sel:[0,1,0]
	v_pk_mul_f32 v[108:109], v[178:179], v[198:199] op_sel:[1,0] op_sel_hi:[0,1]
	v_mov_b32_e32 v201, v107
	v_pk_mul_f32 v[106:107], v[178:179], v[198:199]
	v_pk_add_f32 v[108:109], v[108:109], v[108:109] op_sel:[0,1] op_sel_hi:[0,1]
	v_pk_mul_f32 v[108:109], v[110:111], v[108:109] op_sel:[1,0] op_sel_hi:[0,1]
	v_pk_add_f32 v[106:107], v[106:107], v[106:107] op_sel:[1,0] op_sel_hi:[1,0] neg_lo:[0,1] neg_hi:[0,1]
	v_mov_b32_e32 v189, v187
	v_pk_fma_f32 v[194:195], v[110:111], v[106:107], v[108:109] neg_lo:[0,0,1] neg_hi:[0,0,1]
	v_pk_fma_f32 v[106:107], v[110:111], v[106:107], v[108:109]
	v_mul_f32_e32 v195, 4.0, v205
	v_sin_f32_e32 v198, v195
	v_cos_f32_e32 v202, v195
	v_mov_b32_e32 v195, v107
	v_pk_mul_f32 v[192:193], v[180:181], v[188:189]
	s_waitcnt lgkmcnt(10)
	v_pk_mul_f32 v[106:107], v[198:199], v[112:113] op_sel:[0,1] op_sel_hi:[0,0]
	v_pk_fma_f32 v[108:109], v[202:203], v[112:113], v[106:107] neg_lo:[0,0,1] neg_hi:[0,0,1]
	v_pk_fma_f32 v[106:107], v[202:203], v[112:113], v[106:107] op_sel_hi:[0,1,1]
	v_mov_b32_e32 v199, v202
	v_mov_b32_e32 v109, v107
	v_pk_mul_f32 v[106:107], v[178:179], v[198:199] op_sel_hi:[0,1]
	v_pk_fma_f32 v[110:111], v[180:181], v[198:199], v[106:107] op_sel:[0,0,1] op_sel_hi:[0,1,0]
	v_pk_fma_f32 v[106:107], v[180:181], v[198:199], v[106:107] op_sel:[0,0,1] op_sel_hi:[0,1,0] neg_lo:[0,0,1] neg_hi:[0,0,1]
	v_pk_mul_f32 v[198:199], v[110:111], v[114:115] op_sel:[0,1] op_sel_hi:[0,0]
	v_pk_mov_b32 v[112:113], v[110:111], v[106:107] op_sel:[0,1]
	v_pk_mov_b32 v[110:111], v[106:107], v[110:111] op_sel:[1,0]
	v_pk_fma_f32 v[202:203], v[106:107], v[114:115], v[198:199] op_sel:[1,0,0] neg_lo:[0,0,1] neg_hi:[0,0,1]
	v_pk_fma_f32 v[106:107], v[106:107], v[114:115], v[198:199] op_sel:[1,0,0]
	v_pk_mul_f32 v[188:189], v[178:179], v[188:189]
	v_mov_b32_e32 v203, v107
	v_pk_mul_f32 v[106:107], v[178:179], v[110:111] op_sel_hi:[0,1]
	v_pk_fma_f32 v[110:111], v[180:181], v[112:113], v[106:107] op_sel_hi:[0,1,1]
	v_pk_fma_f32 v[106:107], v[180:181], v[112:113], v[106:107] op_sel_hi:[0,1,1] neg_lo:[0,0,1] neg_hi:[0,0,1]
	v_pk_mov_b32 v[112:113], v[110:111], v[106:107] op_sel:[0,1]
	s_waitcnt lgkmcnt(8)
	v_pk_mul_f32 v[110:111], v[116:117], v[110:111] op_sel:[1,0] op_sel_hi:[0,0]
	v_pk_fma_f32 v[114:115], v[116:117], v[106:107], v[110:111] op_sel:[0,1,0] neg_lo:[0,0,1] neg_hi:[0,0,1]
	v_pk_fma_f32 v[106:107], v[116:117], v[106:107], v[110:111] op_sel:[0,1,0]
	v_pk_mul_f32 v[110:111], v[180:181], v[112:113]
	v_mov_b32_e32 v115, v107
	v_pk_mul_f32 v[106:107], v[178:179], v[112:113]
	v_pk_add_f32 v[110:111], v[110:111], v[110:111] op_sel:[0,1] op_sel_hi:[0,1]
	v_pk_mul_f32 v[110:111], v[118:119], v[110:111] op_sel:[1,0] op_sel_hi:[0,1]
	v_pk_add_f32 v[106:107], v[106:107], v[106:107] op_sel:[1,0] op_sel_hi:[1,0] neg_lo:[0,1] neg_hi:[0,1]
	s_nop 0
	v_pk_fma_f32 v[112:113], v[118:119], v[106:107], v[110:111] neg_lo:[0,0,1] neg_hi:[0,0,1]
	v_pk_fma_f32 v[106:107], v[118:119], v[106:107], v[110:111]
	v_mul_f32_e32 v113, 0x41000000, v205
	v_sin_f32_e32 v116, v113
	v_cos_f32_e32 v198, v113
	v_mov_b32_e32 v113, v107
	s_waitcnt lgkmcnt(6)
	v_pk_mul_f32 v[106:107], v[116:117], v[120:121] op_sel:[0,1] op_sel_hi:[0,0]
	v_pk_fma_f32 v[110:111], v[198:199], v[120:121], v[106:107] neg_lo:[0,0,1] neg_hi:[0,0,1]
	v_pk_fma_f32 v[106:107], v[198:199], v[120:121], v[106:107] op_sel_hi:[0,1,1]
	v_mov_b32_e32 v117, v198
	v_mov_b32_e32 v111, v107
	v_pk_mul_f32 v[106:107], v[178:179], v[116:117] op_sel_hi:[0,1]
	v_pk_fma_f32 v[118:119], v[180:181], v[116:117], v[106:107] op_sel:[0,0,1] op_sel_hi:[0,1,0]
	v_pk_fma_f32 v[106:107], v[180:181], v[116:117], v[106:107] op_sel:[0,0,1] op_sel_hi:[0,1,0] neg_lo:[0,0,1] neg_hi:[0,0,1]
	v_pk_mul_f32 v[120:121], v[118:119], v[122:123] op_sel:[0,1] op_sel_hi:[0,0]
	v_pk_mov_b32 v[116:117], v[118:119], v[106:107] op_sel:[0,1]
	v_pk_mov_b32 v[118:119], v[106:107], v[118:119] op_sel:[1,0]
	v_pk_fma_f32 v[198:199], v[106:107], v[122:123], v[120:121] op_sel:[1,0,0] neg_lo:[0,0,1] neg_hi:[0,0,1]
	v_pk_fma_f32 v[106:107], v[106:107], v[122:123], v[120:121] op_sel:[1,0,0]
	v_mov_b32_e32 v122, v177
	v_mov_b32_e32 v199, v107
	v_pk_mul_f32 v[106:107], v[178:179], v[118:119] op_sel_hi:[0,1]
	v_pk_fma_f32 v[118:119], v[180:181], v[116:117], v[106:107] op_sel_hi:[0,1,1]
	v_pk_fma_f32 v[106:107], v[180:181], v[116:117], v[106:107] op_sel_hi:[0,1,1] neg_lo:[0,0,1] neg_hi:[0,0,1]
	v_mov_b32_e32 v116, v118
	s_waitcnt lgkmcnt(4)
	v_pk_mul_f32 v[118:119], v[118:119], v[124:125] op_sel:[0,1] op_sel_hi:[0,0]
	v_mov_b32_e32 v117, v107
	v_pk_fma_f32 v[120:121], v[106:107], v[124:125], v[118:119] op_sel:[1,0,0] neg_lo:[0,0,1] neg_hi:[0,0,1]
	v_pk_fma_f32 v[106:107], v[106:107], v[124:125], v[118:119] op_sel:[1,0,0]
	s_nop 0
	v_mov_b32_e32 v121, v107
	v_pk_mul_f32 v[106:107], v[178:179], v[116:117]
	v_pk_mul_f32 v[116:117], v[180:181], v[116:117]
	v_pk_add_f32 v[106:107], v[106:107], v[106:107] op_sel:[1,0] op_sel_hi:[1,0] neg_lo:[0,1] neg_hi:[0,1]
	v_pk_add_f32 v[116:117], v[116:117], v[116:117] op_sel:[0,1] op_sel_hi:[0,1]
	v_pk_mul_f32 v[116:117], v[116:117], v[126:127] op_sel:[0,1] op_sel_hi:[1,0]
	s_nop 0
	v_pk_fma_f32 v[118:119], v[106:107], v[126:127], v[116:117] neg_lo:[0,0,1] neg_hi:[0,0,1]
	v_pk_fma_f32 v[106:107], v[106:107], v[126:127], v[116:117]
	v_mov_b32_e32 v116, v177
	v_mov_b32_e32 v119, v107
	s_waitcnt lgkmcnt(2)
	v_pk_mul_f32 v[106:107], v[176:177], v[128:129] op_sel:[0,1] op_sel_hi:[0,0]
	v_pk_fma_f32 v[116:117], v[116:117], v[128:129], v[106:107] neg_lo:[0,0,1] neg_hi:[0,0,1]
	v_pk_fma_f32 v[106:107], v[122:123], v[128:129], v[106:107] op_sel_hi:[0,1,1]
	v_mov_b32_e32 v117, v107
	v_pk_mul_f32 v[106:107], v[184:185], v[130:131] op_sel:[0,1] op_sel_hi:[0,0]
	v_pk_fma_f32 v[122:123], v[182:183], v[130:131], v[106:107] op_sel:[1,0,0] neg_lo:[0,0,1] neg_hi:[0,0,1]
	v_pk_fma_f32 v[106:107], v[182:183], v[130:131], v[106:107] op_sel:[1,0,0]
	v_pk_add_f32 v[126:127], v[192:193], v[192:193] op_sel:[0,1] op_sel_hi:[0,1]
	v_mov_b32_e32 v123, v107
	s_waitcnt lgkmcnt(0)
	v_pk_mul_f32 v[106:107], v[190:191], v[132:133] op_sel:[0,1] op_sel_hi:[0,0]
	v_pk_fma_f32 v[124:125], v[186:187], v[132:133], v[106:107] op_sel:[1,0,0] neg_lo:[0,0,1] neg_hi:[0,0,1]
	v_pk_fma_f32 v[106:107], v[186:187], v[132:133], v[106:107] op_sel:[1,0,0]
	v_pk_mul_f32 v[126:127], v[126:127], v[134:135] op_sel:[0,1] op_sel_hi:[1,0]
	v_mov_b32_e32 v125, v107
	v_pk_add_f32 v[106:107], v[188:189], v[188:189] op_sel:[1,0] op_sel_hi:[1,0] neg_lo:[0,1] neg_hi:[0,1]
	v_pk_add_f32 v[130:131], v[202:203], v[122:123]
	v_pk_fma_f32 v[128:129], v[106:107], v[134:135], v[126:127] neg_lo:[0,0,1] neg_hi:[0,0,1]
	v_pk_fma_f32 v[106:107], v[106:107], v[134:135], v[126:127]
	v_pk_add_f32 v[122:123], v[202:203], v[122:123] neg_lo:[0,1] neg_hi:[0,1]
	v_mov_b32_e32 v129, v107
	v_pk_add_f32 v[106:107], v[104:105], v[110:111]
	v_pk_add_f32 v[104:105], v[104:105], v[110:111] neg_lo:[0,1] neg_hi:[0,1]
	v_pk_add_f32 v[110:111], v[108:109], v[116:117]
	v_pk_add_f32 v[108:109], v[108:109], v[116:117] neg_lo:[0,1] neg_hi:[0,1]
	v_pk_add_f32 v[126:127], v[196:197], v[198:199] neg_lo:[0,1] neg_hi:[0,1]
	v_xor_b32_e32 v116, 0x80000000, v109
	v_mov_b32_e32 v117, v108
	v_pk_add_f32 v[108:109], v[106:107], v[110:111]
	v_pk_add_f32 v[106:107], v[106:107], v[110:111] neg_lo:[0,1] neg_hi:[0,1]
	v_pk_add_f32 v[110:111], v[104:105], v[116:117]
	v_pk_add_f32 v[104:105], v[104:105], v[116:117] neg_lo:[0,1] neg_hi:[0,1]
	v_pk_add_f32 v[116:117], v[196:197], v[198:199]
	v_xor_b32_e32 v132, 0x80000000, v123
	v_mov_b32_e32 v133, v122
	v_pk_add_f32 v[134:135], v[114:115], v[124:125]
	v_pk_add_f32 v[114:115], v[114:115], v[124:125] neg_lo:[0,1] neg_hi:[0,1]
	v_pk_add_f32 v[122:123], v[116:117], v[130:131]
	v_pk_add_f32 v[116:117], v[116:117], v[130:131] neg_lo:[0,1] neg_hi:[0,1]
	v_pk_add_f32 v[130:131], v[126:127], v[132:133]
	v_pk_add_f32 v[126:127], v[126:127], v[132:133] neg_lo:[0,1] neg_hi:[0,1]
	v_pk_add_f32 v[132:133], v[200:201], v[120:121]
	v_pk_add_f32 v[120:121], v[200:201], v[120:121] neg_lo:[0,1] neg_hi:[0,1]
	v_xor_b32_e32 v124, 0x80000000, v115
	v_mov_b32_e32 v125, v114
	v_pk_add_f32 v[176:177], v[112:113], v[128:129]
	v_pk_add_f32 v[112:113], v[112:113], v[128:129] neg_lo:[0,1] neg_hi:[0,1]
	v_pk_add_f32 v[114:115], v[132:133], v[134:135]
	v_pk_add_f32 v[132:133], v[132:133], v[134:135] neg_lo:[0,1] neg_hi:[0,1]
	v_pk_add_f32 v[134:135], v[120:121], v[124:125]
	v_pk_add_f32 v[120:121], v[120:121], v[124:125] neg_lo:[0,1] neg_hi:[0,1]
	v_pk_add_f32 v[124:125], v[194:195], v[118:119]
	v_pk_add_f32 v[118:119], v[194:195], v[118:119] neg_lo:[0,1] neg_hi:[0,1]
	v_xor_b32_e32 v128, 0x80000000, v113
	v_mov_b32_e32 v129, v112
	v_pk_add_f32 v[112:113], v[124:125], v[176:177]
	v_pk_add_f32 v[124:125], v[124:125], v[176:177] neg_lo:[0,1] neg_hi:[0,1]
	v_pk_add_f32 v[176:177], v[118:119], v[128:129]
	v_pk_add_f32 v[118:119], v[118:119], v[128:129] neg_lo:[0,1] neg_hi:[0,1]
	v_pk_mul_f32 v[128:129], v[130:131], s[30:31] op_sel_hi:[1,0]
	s_nop 0
	v_pk_fma_f32 v[178:179], v[130:131], s[22:23], v[128:129] op_sel:[0,0,1] op_sel_hi:[1,0,0] neg_lo:[0,0,1] neg_hi:[0,0,1]
	v_pk_fma_f32 v[128:129], v[130:131], s[22:23], v[128:129] op_sel:[0,0,1] op_sel_hi:[1,0,0]
	s_nop 0
	v_mov_b32_e32 v179, v129
	v_pk_mul_f32 v[128:129], v[116:117], s[24:25] op_sel_hi:[1,0]
	s_nop 0
	v_pk_fma_f32 v[130:131], v[116:117], s[24:25], v[128:129] op_sel:[0,0,1] op_sel_hi:[1,0,0] neg_lo:[0,0,1] neg_hi:[0,0,1]
	v_pk_fma_f32 v[116:117], v[116:117], s[24:25], v[128:129] op_sel_hi:[1,0,0]
	s_nop 0
	v_mov_b32_e32 v131, v117
	v_pk_mul_f32 v[116:117], v[126:127], s[22:23] op_sel_hi:[1,0]
	s_nop 0
	v_pk_fma_f32 v[128:129], v[126:127], s[30:31], v[116:117] op_sel:[0,0,1] op_sel_hi:[1,0,0] neg_lo:[0,0,1] neg_hi:[0,0,1]
	v_pk_fma_f32 v[116:117], v[126:127], s[30:31], v[116:117] op_sel:[0,0,1] op_sel_hi:[1,0,0]
	s_nop 0
	v_mov_b32_e32 v129, v117
	v_pk_mul_f32 v[116:117], v[134:135], s[24:25] op_sel_hi:[1,0]
	s_nop 0
	v_pk_fma_f32 v[126:127], v[134:135], s[24:25], v[116:117] op_sel:[0,0,1] op_sel_hi:[1,0,0] neg_lo:[0,0,1] neg_hi:[0,0,1]
	v_pk_fma_f32 v[116:117], v[134:135], s[24:25], v[116:117] op_sel_hi:[1,0,0]
	s_nop 0
	v_mov_b32_e32 v127, v117
	v_mov_b32_e32 v117, v132
	v_mul_f32_e32 v132, 0x3f3504f3, v121
	v_xor_b32_e32 v116, 0x80000000, v133
	v_pk_fma_f32 v[120:121], v[120:121], s[18:19], v[132:133] op_sel_hi:[0,1,0] neg_lo:[0,0,1] neg_hi:[0,0,1]
	v_pk_mul_f32 v[132:133], v[176:177], s[22:23] op_sel_hi:[1,0]
	s_nop 0
	v_pk_fma_f32 v[134:135], v[176:177], s[30:31], v[132:133] op_sel:[0,0,1] op_sel_hi:[1,0,0] neg_lo:[0,0,1] neg_hi:[0,0,1]
	v_pk_fma_f32 v[132:133], v[176:177], s[30:31], v[132:133] op_sel:[0,0,1] op_sel_hi:[1,0,0]
	s_nop 0
	v_mul_f32_e32 v132, 0x3f3504f3, v125
	v_mov_b32_e32 v135, v133
	v_pk_fma_f32 v[124:125], v[124:125], s[18:19], v[132:133] op_sel_hi:[0,1,0] neg_lo:[0,0,1] neg_hi:[0,0,1]
	v_pk_mul_f32 v[132:133], v[118:119], s[88:89]
	s_nop 0
	v_pk_fma_f32 v[118:119], v[118:119], s[22:23], v[132:133] op_sel:[0,0,1] op_sel_hi:[1,0,0] neg_lo:[1,0,0] neg_hi:[1,0,0]
	v_pk_add_f32 v[132:133], v[108:109], v[114:115]
	v_pk_add_f32 v[108:109], v[108:109], v[114:115] neg_lo:[0,1] neg_hi:[0,1]
	v_pk_add_f32 v[114:115], v[122:123], v[112:113]
	v_pk_add_f32 v[112:113], v[122:123], v[112:113] neg_lo:[0,1] neg_hi:[0,1]
	s_nop 0
	v_xor_b32_e32 v122, 0x80000000, v113
	v_mov_b32_e32 v123, v112
	v_pk_add_f32 v[112:113], v[132:133], v[114:115]
	v_pk_add_f32 v[114:115], v[132:133], v[114:115] neg_lo:[0,1] neg_hi:[0,1]
	v_pk_add_f32 v[132:133], v[108:109], v[122:123]
	v_pk_add_f32 v[108:109], v[108:109], v[122:123] neg_lo:[0,1] neg_hi:[0,1]
	v_pk_add_f32 v[122:123], v[110:111], v[126:127]
	v_pk_add_f32 v[110:111], v[110:111], v[126:127] neg_lo:[0,1] neg_hi:[0,1]
	v_pk_add_f32 v[126:127], v[178:179], v[134:135]
	v_pk_add_f32 v[134:135], v[178:179], v[134:135] neg_lo:[0,1] neg_hi:[0,1]
	s_nop 0
	v_xor_b32_e32 v176, 0x80000000, v135
	v_mov_b32_e32 v177, v134
	v_pk_add_f32 v[134:135], v[122:123], v[126:127]
	v_pk_add_f32 v[122:123], v[122:123], v[126:127] neg_lo:[0,1] neg_hi:[0,1]
	v_pk_add_f32 v[126:127], v[110:111], v[176:177]
	v_pk_add_f32 v[110:111], v[110:111], v[176:177] neg_lo:[0,1] neg_hi:[0,1]
	v_pk_add_f32 v[176:177], v[106:107], v[116:117]
	v_pk_add_f32 v[106:107], v[106:107], v[116:117] neg_lo:[0,1] neg_hi:[0,1]
	v_pk_add_f32 v[116:117], v[130:131], v[124:125]
	v_pk_add_f32 v[124:125], v[130:131], v[124:125] neg_lo:[0,1] neg_hi:[0,1]
	s_nop 0
	v_xor_b32_e32 v130, 0x80000000, v125
	v_mov_b32_e32 v131, v124
	v_pk_add_f32 v[124:125], v[176:177], v[116:117]
	v_pk_add_f32 v[116:117], v[176:177], v[116:117] neg_lo:[0,1] neg_hi:[0,1]
	v_pk_add_f32 v[176:177], v[106:107], v[130:131]
	v_pk_add_f32 v[106:107], v[106:107], v[130:131] neg_lo:[0,1] neg_hi:[0,1]
	v_pk_add_f32 v[130:131], v[104:105], v[120:121]
	v_pk_add_f32 v[104:105], v[104:105], v[120:121] neg_lo:[0,1] neg_hi:[0,1]
	v_pk_add_f32 v[120:121], v[128:129], v[118:119]
	v_pk_add_f32 v[118:119], v[128:129], v[118:119] neg_lo:[0,1] neg_hi:[0,1]
	s_nop 0
	v_xor_b32_e32 v128, 0x80000000, v119
	v_mov_b32_e32 v129, v118
	v_pk_add_f32 v[118:119], v[130:131], v[120:121]
	v_pk_add_f32 v[120:121], v[130:131], v[120:121] neg_lo:[0,1] neg_hi:[0,1]
	v_pk_add_f32 v[130:131], v[104:105], v[128:129]
	v_pk_add_f32 v[104:105], v[104:105], v[128:129] neg_lo:[0,1] neg_hi:[0,1]
	v_mov_b32_e32 v128, v208
	ds_write2_b64 v204, v[112:113], v[134:135] offset1:17
	ds_write2_b64 v204, v[124:125], v[118:119] offset0:34 offset1:51
	ds_write2_b64 v204, v[132:133], v[126:127] offset0:68 offset1:85
	ds_write2_b64 v204, v[176:177], v[130:131] offset0:102 offset1:119
	ds_write2_b64 v204, v[114:115], v[122:123] offset0:136 offset1:153
	ds_write2_b64 v204, v[116:117], v[120:121] offset0:170 offset1:187
	ds_write2_b64 v204, v[108:109], v[110:111] offset0:204 offset1:221
	ds_write2_b64 v204, v[106:107], v[104:105] offset0:238 offset1:255
	s_waitcnt lgkmcnt(0)
	s_barrier
	s_nop 0
	v_and_b32_e32 v104, 0xff, v128
	v_lshlrev_b32_e32 v105, 4, v128
	v_cvt_f32_ubyte0_e32 v128, v128
	v_mul_f32_e32 v205, 0x39800000, v128
	v_mul_f32_e32 v129, 0x41400000, v205
	v_sin_f32_e32 v130, v129
	v_sin_f32_e32 v132, v205
	v_cos_f32_e32 v131, v129
	v_cos_f32_e32 v128, v205
	v_and_or_b32 v104, v105, s93, v104
	v_ashrrev_i32_e32 v105, 4, v104
	v_pk_mul_f32 v[182:183], v[132:133], v[130:131] op_sel_hi:[0,1]
	v_pk_fma_f32 v[184:185], v[128:129], v[130:131], v[182:183] op_sel:[0,0,1] op_sel_hi:[0,1,0]
	v_pk_fma_f32 v[182:183], v[128:129], v[130:131], v[182:183] op_sel:[0,0,1] op_sel_hi:[0,1,0] neg_lo:[0,0,1] neg_hi:[0,0,1]
	v_lshlrev_b32_e32 v105, 3, v105
	v_lshlrev_b32_e32 v104, 3, v104
	v_pk_mov_b32 v[188:189], v[182:183], v[184:185] op_sel:[1,0]
	v_add3_u32 v204, s35, v105, v104
	v_pk_mov_b32 v[186:187], v[184:185], v[182:183] op_sel:[0,1]
	v_pk_mul_f32 v[188:189], v[132:133], v[188:189] op_sel_hi:[0,1]
	v_mov_b32_e32 v133, v128
	ds_read_b64 v[104:105], v204
	ds_read_b64 v[106:107], v204 offset:2176
	ds_read_b64 v[108:109], v204 offset:4352
	ds_read_b64 v[110:111], v204 offset:6528
	ds_read_b64 v[112:113], v204 offset:8704
	ds_read_b64 v[114:115], v204 offset:10880
	ds_read_b64 v[116:117], v204 offset:13056
	ds_read_b64 v[118:119], v204 offset:15232
	ds_read_b64 v[120:121], v204 offset:17408
	ds_read_b64 v[122:123], v204 offset:19584
	ds_read_b64 v[124:125], v204 offset:21760
	ds_read_b64 v[126:127], v204 offset:23936
	v_pk_fma_f32 v[190:191], v[128:129], v[186:187], v[188:189] op_sel_hi:[0,1,1]
	v_pk_fma_f32 v[186:187], v[128:129], v[186:187], v[188:189] op_sel_hi:[0,1,1] neg_lo:[0,0,1] neg_hi:[0,0,1]
	v_mov_b32_e32 v129, v132
	s_waitcnt lgkmcnt(10)
	v_pk_mul_f32 v[194:195], v[106:107], v[132:133] op_sel_hi:[1,0]
	ds_read_b64 v[134:135], v204 offset:26112
	ds_read_b64 v[176:177], v204 offset:28288
	ds_read_b64 v[178:179], v204 offset:30464
	ds_read_b64 v[180:181], v204 offset:32640
	v_pk_fma_f32 v[196:197], v[106:107], v[128:129], v[194:195] op_sel:[0,0,1] op_sel_hi:[1,1,0] neg_lo:[0,0,1] neg_hi:[0,0,1]
	v_pk_fma_f32 v[106:107], v[106:107], v[128:129], v[194:195] op_sel:[0,0,1] op_sel_hi:[1,0,0]
	v_mov_b32_e32 v188, v190
	v_mov_b32_e32 v197, v107
	v_pk_mul_f32 v[106:107], v[132:133], v[132:133] op_sel:[0,1] op_sel_hi:[0,0]
	v_pk_fma_f32 v[194:195], v[128:129], v[132:133], v[106:107] op_sel_hi:[0,1,1]
	v_pk_fma_f32 v[106:107], v[128:129], v[132:133], v[106:107] op_sel_hi:[0,1,1] neg_lo:[0,0,1] neg_hi:[0,0,1]
	v_pk_mov_b32 v[198:199], v[194:195], v[106:107] op_sel:[0,1]
	s_waitcnt lgkmcnt(13)
	v_pk_mul_f32 v[194:195], v[108:109], v[194:195] op_sel:[1,0] op_sel_hi:[0,0]
	v_pk_fma_f32 v[200:201], v[108:109], v[106:107], v[194:195] op_sel:[0,1,0] neg_lo:[0,0,1] neg_hi:[0,0,1]
	v_pk_fma_f32 v[106:107], v[108:109], v[106:107], v[194:195] op_sel:[0,1,0]
	v_pk_mul_f32 v[108:109], v[132:133], v[198:199] op_sel:[1,0] op_sel_hi:[0,1]
	v_mov_b32_e32 v201, v107
	v_pk_mul_f32 v[106:107], v[132:133], v[198:199]
	v_pk_add_f32 v[108:109], v[108:109], v[108:109] op_sel:[0,1] op_sel_hi:[0,1]
	s_waitcnt lgkmcnt(12)
	v_pk_mul_f32 v[108:109], v[110:111], v[108:109] op_sel:[1,0] op_sel_hi:[0,1]
	v_pk_add_f32 v[106:107], v[106:107], v[106:107] op_sel:[1,0] op_sel_hi:[1,0] neg_lo:[0,1] neg_hi:[0,1]
	v_mov_b32_e32 v189, v187
	v_pk_fma_f32 v[194:195], v[110:111], v[106:107], v[108:109] neg_lo:[0,0,1] neg_hi:[0,0,1]
	v_pk_fma_f32 v[106:107], v[110:111], v[106:107], v[108:109]
	v_mul_f32_e32 v195, 4.0, v205
	v_sin_f32_e32 v198, v195
	v_cos_f32_e32 v202, v195
	v_mov_b32_e32 v195, v107
	v_pk_mul_f32 v[192:193], v[128:129], v[188:189]
	s_waitcnt lgkmcnt(11)
	v_pk_mul_f32 v[106:107], v[198:199], v[112:113] op_sel:[0,1] op_sel_hi:[0,0]
	v_pk_fma_f32 v[108:109], v[202:203], v[112:113], v[106:107] neg_lo:[0,0,1] neg_hi:[0,0,1]
	v_pk_fma_f32 v[106:107], v[202:203], v[112:113], v[106:107] op_sel_hi:[0,1,1]
	v_mov_b32_e32 v199, v202
	v_mov_b32_e32 v109, v107
	v_pk_mul_f32 v[106:107], v[132:133], v[198:199] op_sel_hi:[0,1]
	v_pk_fma_f32 v[110:111], v[128:129], v[198:199], v[106:107] op_sel:[0,0,1] op_sel_hi:[0,1,0]
	v_pk_fma_f32 v[106:107], v[128:129], v[198:199], v[106:107] op_sel:[0,0,1] op_sel_hi:[0,1,0] neg_lo:[0,0,1] neg_hi:[0,0,1]
	s_waitcnt lgkmcnt(10)
	v_pk_mul_f32 v[198:199], v[110:111], v[114:115] op_sel:[0,1] op_sel_hi:[0,0]
	v_mov_b32_e32 v112, v110
	v_mov_b32_e32 v113, v107
	v_pk_mov_b32 v[110:111], v[106:107], v[110:111] op_sel:[1,0]
	v_pk_fma_f32 v[202:203], v[106:107], v[114:115], v[198:199] op_sel:[1,0,0] neg_lo:[0,0,1] neg_hi:[0,0,1]
	v_pk_fma_f32 v[106:107], v[106:107], v[114:115], v[198:199] op_sel:[1,0,0]
	v_pk_mul_f32 v[188:189], v[132:133], v[188:189]
	v_mov_b32_e32 v203, v107
	v_pk_mul_f32 v[106:107], v[132:133], v[110:111] op_sel_hi:[0,1]
	v_pk_fma_f32 v[110:111], v[128:129], v[112:113], v[106:107] op_sel_hi:[0,1,1]
	v_pk_fma_f32 v[106:107], v[128:129], v[112:113], v[106:107] op_sel_hi:[0,1,1] neg_lo:[0,0,1] neg_hi:[0,0,1]
	v_pk_mov_b32 v[112:113], v[110:111], v[106:107] op_sel:[0,1]
	s_waitcnt lgkmcnt(9)
	v_pk_mul_f32 v[110:111], v[116:117], v[110:111] op_sel:[1,0] op_sel_hi:[0,0]
	v_pk_fma_f32 v[114:115], v[116:117], v[106:107], v[110:111] op_sel:[0,1,0] neg_lo:[0,0,1] neg_hi:[0,0,1]
	v_pk_fma_f32 v[106:107], v[116:117], v[106:107], v[110:111] op_sel:[0,1,0]
	v_pk_mul_f32 v[110:111], v[128:129], v[112:113]
	v_mov_b32_e32 v115, v107
	v_pk_mul_f32 v[106:107], v[132:133], v[112:113]
	v_pk_add_f32 v[110:111], v[110:111], v[110:111] op_sel:[0,1] op_sel_hi:[0,1]
	s_waitcnt lgkmcnt(8)
	v_pk_mul_f32 v[110:111], v[118:119], v[110:111] op_sel:[1,0] op_sel_hi:[0,1]
	v_pk_add_f32 v[106:107], v[106:107], v[106:107] op_sel:[1,0] op_sel_hi:[1,0] neg_lo:[0,1] neg_hi:[0,1]
	s_nop 0
	v_pk_fma_f32 v[112:113], v[118:119], v[106:107], v[110:111] neg_lo:[0,0,1] neg_hi:[0,0,1]
	v_pk_fma_f32 v[106:107], v[118:119], v[106:107], v[110:111]
	v_mul_f32_e32 v113, 0x41000000, v205
	v_sin_f32_e32 v116, v113
	v_cos_f32_e32 v198, v113
	v_mov_b32_e32 v113, v107
	s_waitcnt lgkmcnt(7)
	v_pk_mul_f32 v[106:107], v[116:117], v[120:121] op_sel:[0,1] op_sel_hi:[0,0]
	v_pk_fma_f32 v[110:111], v[198:199], v[120:121], v[106:107] neg_lo:[0,0,1] neg_hi:[0,0,1]
	v_pk_fma_f32 v[106:107], v[198:199], v[120:121], v[106:107] op_sel_hi:[0,1,1]
	v_mov_b32_e32 v117, v198
	v_mov_b32_e32 v111, v107
	v_pk_mul_f32 v[106:107], v[132:133], v[116:117] op_sel_hi:[0,1]
	v_pk_fma_f32 v[118:119], v[128:129], v[116:117], v[106:107] op_sel:[0,0,1] op_sel_hi:[0,1,0]
	v_pk_fma_f32 v[106:107], v[128:129], v[116:117], v[106:107] op_sel:[0,0,1] op_sel_hi:[0,1,0] neg_lo:[0,0,1] neg_hi:[0,0,1]
	s_waitcnt lgkmcnt(6)
	v_pk_mul_f32 v[120:121], v[118:119], v[122:123] op_sel:[0,1] op_sel_hi:[0,0]
	v_mov_b32_e32 v116, v118
	v_mov_b32_e32 v117, v107
	v_pk_mov_b32 v[118:119], v[106:107], v[118:119] op_sel:[1,0]
	v_pk_fma_f32 v[198:199], v[106:107], v[122:123], v[120:121] op_sel:[1,0,0] neg_lo:[0,0,1] neg_hi:[0,0,1]
	v_pk_fma_f32 v[106:107], v[106:107], v[122:123], v[120:121] op_sel:[1,0,0]
	v_mov_b32_e32 v122, v131
	v_mov_b32_e32 v199, v107
	v_pk_mul_f32 v[106:107], v[132:133], v[118:119] op_sel_hi:[0,1]
	v_pk_fma_f32 v[118:119], v[128:129], v[116:117], v[106:107] op_sel_hi:[0,1,1]
	v_pk_fma_f32 v[106:107], v[128:129], v[116:117], v[106:107] op_sel_hi:[0,1,1] neg_lo:[0,0,1] neg_hi:[0,0,1]
	v_mov_b32_e32 v116, v118
	s_waitcnt lgkmcnt(5)
	v_pk_mul_f32 v[118:119], v[118:119], v[124:125] op_sel:[0,1] op_sel_hi:[0,0]
	v_mov_b32_e32 v117, v107
	v_pk_fma_f32 v[120:121], v[106:107], v[124:125], v[118:119] op_sel:[1,0,0] neg_lo:[0,0,1] neg_hi:[0,0,1]
	v_pk_fma_f32 v[106:107], v[106:107], v[124:125], v[118:119] op_sel:[1,0,0]
	s_nop 0
	v_mov_b32_e32 v121, v107
	v_pk_mul_f32 v[106:107], v[132:133], v[116:117]
	v_pk_mul_f32 v[116:117], v[128:129], v[116:117]
	v_pk_add_f32 v[106:107], v[106:107], v[106:107] op_sel:[1,0] op_sel_hi:[1,0] neg_lo:[0,1] neg_hi:[0,1]
	v_pk_add_f32 v[116:117], v[116:117], v[116:117] op_sel:[0,1] op_sel_hi:[0,1]
	s_waitcnt lgkmcnt(4)
	v_pk_mul_f32 v[116:117], v[116:117], v[126:127] op_sel:[0,1] op_sel_hi:[1,0]
	s_nop 0
	v_pk_fma_f32 v[118:119], v[106:107], v[126:127], v[116:117] neg_lo:[0,0,1] neg_hi:[0,0,1]
	v_pk_fma_f32 v[106:107], v[106:107], v[126:127], v[116:117]
	v_mov_b32_e32 v116, v131
	v_mov_b32_e32 v119, v107
	s_waitcnt lgkmcnt(3)
	v_pk_mul_f32 v[106:107], v[130:131], v[134:135] op_sel:[0,1] op_sel_hi:[0,0]
	v_pk_fma_f32 v[116:117], v[116:117], v[134:135], v[106:107] neg_lo:[0,0,1] neg_hi:[0,0,1]
	v_pk_fma_f32 v[106:107], v[122:123], v[134:135], v[106:107] op_sel_hi:[0,1,1]
	v_mov_b32_e32 v117, v107
	s_waitcnt lgkmcnt(2)
	v_pk_mul_f32 v[106:107], v[184:185], v[176:177] op_sel:[0,1] op_sel_hi:[0,0]
	v_pk_fma_f32 v[122:123], v[182:183], v[176:177], v[106:107] op_sel:[1,0,0] neg_lo:[0,0,1] neg_hi:[0,0,1]
	v_pk_fma_f32 v[106:107], v[182:183], v[176:177], v[106:107] op_sel:[1,0,0]
	v_pk_add_f32 v[126:127], v[192:193], v[192:193] op_sel:[0,1] op_sel_hi:[0,1]
	v_mov_b32_e32 v123, v107
	s_waitcnt lgkmcnt(1)
	v_pk_mul_f32 v[106:107], v[190:191], v[178:179] op_sel:[0,1] op_sel_hi:[0,0]
	v_pk_fma_f32 v[124:125], v[186:187], v[178:179], v[106:107] op_sel:[1,0,0] neg_lo:[0,0,1] neg_hi:[0,0,1]
	v_pk_fma_f32 v[106:107], v[186:187], v[178:179], v[106:107] op_sel:[1,0,0]
	s_waitcnt lgkmcnt(0)
	v_pk_mul_f32 v[126:127], v[126:127], v[180:181] op_sel:[0,1] op_sel_hi:[1,0]
	v_mov_b32_e32 v125, v107
	v_pk_add_f32 v[106:107], v[188:189], v[188:189] op_sel:[1,0] op_sel_hi:[1,0] neg_lo:[0,1] neg_hi:[0,1]
	v_pk_add_f32 v[130:131], v[202:203], v[122:123]
	v_pk_fma_f32 v[128:129], v[106:107], v[180:181], v[126:127] neg_lo:[0,0,1] neg_hi:[0,0,1]
	v_pk_fma_f32 v[106:107], v[106:107], v[180:181], v[126:127]
	v_pk_add_f32 v[122:123], v[202:203], v[122:123] neg_lo:[0,1] neg_hi:[0,1]
	v_mov_b32_e32 v129, v107
	v_pk_add_f32 v[106:107], v[104:105], v[110:111]
	v_pk_add_f32 v[104:105], v[104:105], v[110:111] neg_lo:[0,1] neg_hi:[0,1]
	v_pk_add_f32 v[110:111], v[108:109], v[116:117]
	v_pk_add_f32 v[108:109], v[108:109], v[116:117] neg_lo:[0,1] neg_hi:[0,1]
	v_pk_add_f32 v[126:127], v[196:197], v[198:199] neg_lo:[0,1] neg_hi:[0,1]
	v_xor_b32_e32 v116, 0x80000000, v109
	v_mov_b32_e32 v117, v108
	v_pk_add_f32 v[108:109], v[106:107], v[110:111]
	v_pk_add_f32 v[106:107], v[106:107], v[110:111] neg_lo:[0,1] neg_hi:[0,1]
	v_pk_add_f32 v[110:111], v[104:105], v[116:117]
	v_pk_add_f32 v[104:105], v[104:105], v[116:117] neg_lo:[0,1] neg_hi:[0,1]
	v_pk_add_f32 v[116:117], v[196:197], v[198:199]
	v_xor_b32_e32 v132, 0x80000000, v123
	v_mov_b32_e32 v133, v122
	v_pk_add_f32 v[134:135], v[114:115], v[124:125]
	v_pk_add_f32 v[114:115], v[114:115], v[124:125] neg_lo:[0,1] neg_hi:[0,1]
	v_pk_add_f32 v[122:123], v[116:117], v[130:131]
	v_pk_add_f32 v[116:117], v[116:117], v[130:131] neg_lo:[0,1] neg_hi:[0,1]
	v_pk_add_f32 v[130:131], v[126:127], v[132:133]
	v_pk_add_f32 v[126:127], v[126:127], v[132:133] neg_lo:[0,1] neg_hi:[0,1]
	v_pk_add_f32 v[132:133], v[200:201], v[120:121]
	v_pk_add_f32 v[120:121], v[200:201], v[120:121] neg_lo:[0,1] neg_hi:[0,1]
	v_xor_b32_e32 v124, 0x80000000, v115
	v_mov_b32_e32 v125, v114
	v_pk_add_f32 v[176:177], v[112:113], v[128:129]
	v_pk_add_f32 v[112:113], v[112:113], v[128:129] neg_lo:[0,1] neg_hi:[0,1]
	v_pk_add_f32 v[114:115], v[132:133], v[134:135]
	v_pk_add_f32 v[132:133], v[132:133], v[134:135] neg_lo:[0,1] neg_hi:[0,1]
	v_pk_add_f32 v[134:135], v[120:121], v[124:125]
	v_pk_add_f32 v[120:121], v[120:121], v[124:125] neg_lo:[0,1] neg_hi:[0,1]
	v_pk_add_f32 v[124:125], v[194:195], v[118:119]
	v_pk_add_f32 v[118:119], v[194:195], v[118:119] neg_lo:[0,1] neg_hi:[0,1]
	v_xor_b32_e32 v128, 0x80000000, v113
	v_mov_b32_e32 v129, v112
	v_pk_add_f32 v[112:113], v[124:125], v[176:177]
	v_pk_add_f32 v[124:125], v[124:125], v[176:177] neg_lo:[0,1] neg_hi:[0,1]
	v_pk_add_f32 v[176:177], v[118:119], v[128:129]
	v_pk_add_f32 v[118:119], v[118:119], v[128:129] neg_lo:[0,1] neg_hi:[0,1]
	v_pk_mul_f32 v[128:129], v[130:131], s[30:31] op_sel_hi:[1,0]
	s_nop 0
	v_pk_fma_f32 v[178:179], v[130:131], s[22:23], v[128:129] op_sel:[0,0,1] op_sel_hi:[1,0,0] neg_lo:[0,0,1] neg_hi:[0,0,1]
	v_pk_fma_f32 v[128:129], v[130:131], s[22:23], v[128:129] op_sel:[0,0,1] op_sel_hi:[1,0,0]
	s_nop 0
	v_mov_b32_e32 v179, v129
	v_pk_mul_f32 v[128:129], v[116:117], s[24:25] op_sel_hi:[1,0]
	s_nop 0
	v_pk_fma_f32 v[130:131], v[116:117], s[24:25], v[128:129] op_sel:[0,0,1] op_sel_hi:[1,0,0] neg_lo:[0,0,1] neg_hi:[0,0,1]
	v_pk_fma_f32 v[116:117], v[116:117], s[24:25], v[128:129] op_sel_hi:[1,0,0]
	s_nop 0
	v_mov_b32_e32 v131, v117
	v_pk_mul_f32 v[116:117], v[126:127], s[22:23] op_sel_hi:[1,0]
	s_nop 0
	v_pk_fma_f32 v[128:129], v[126:127], s[30:31], v[116:117] op_sel:[0,0,1] op_sel_hi:[1,0,0] neg_lo:[0,0,1] neg_hi:[0,0,1]
	v_pk_fma_f32 v[116:117], v[126:127], s[30:31], v[116:117] op_sel:[0,0,1] op_sel_hi:[1,0,0]
	s_nop 0
	v_mov_b32_e32 v129, v117
	v_pk_mul_f32 v[116:117], v[134:135], s[24:25] op_sel_hi:[1,0]
	s_nop 0
	v_pk_fma_f32 v[126:127], v[134:135], s[24:25], v[116:117] op_sel:[0,0,1] op_sel_hi:[1,0,0] neg_lo:[0,0,1] neg_hi:[0,0,1]
	v_pk_fma_f32 v[116:117], v[134:135], s[24:25], v[116:117] op_sel_hi:[1,0,0]
	s_nop 0
	v_mov_b32_e32 v127, v117
	v_mov_b32_e32 v117, v132
	v_mul_f32_e32 v132, 0x3f3504f3, v121
	v_xor_b32_e32 v116, 0x80000000, v133
	v_pk_fma_f32 v[120:121], v[120:121], s[18:19], v[132:133] op_sel_hi:[0,1,0] neg_lo:[0,0,1] neg_hi:[0,0,1]
	v_pk_mul_f32 v[132:133], v[176:177], s[22:23] op_sel_hi:[1,0]
	s_nop 0
	v_pk_fma_f32 v[134:135], v[176:177], s[30:31], v[132:133] op_sel:[0,0,1] op_sel_hi:[1,0,0] neg_lo:[0,0,1] neg_hi:[0,0,1]
	v_pk_fma_f32 v[132:133], v[176:177], s[30:31], v[132:133] op_sel:[0,0,1] op_sel_hi:[1,0,0]
	s_nop 0
	v_mul_f32_e32 v132, 0x3f3504f3, v125
	v_mov_b32_e32 v135, v133
	v_pk_fma_f32 v[124:125], v[124:125], s[18:19], v[132:133] op_sel_hi:[0,1,0] neg_lo:[0,0,1] neg_hi:[0,0,1]
	v_pk_mul_f32 v[132:133], v[118:119], s[88:89]
	s_nop 0
	v_pk_fma_f32 v[118:119], v[118:119], s[22:23], v[132:133] op_sel:[0,0,1] op_sel_hi:[1,0,0] neg_lo:[1,0,0] neg_hi:[1,0,0]
	v_pk_add_f32 v[132:133], v[108:109], v[114:115]
	v_pk_add_f32 v[108:109], v[108:109], v[114:115] neg_lo:[0,1] neg_hi:[0,1]
	v_pk_add_f32 v[114:115], v[122:123], v[112:113]
	v_pk_add_f32 v[112:113], v[122:123], v[112:113] neg_lo:[0,1] neg_hi:[0,1]
	s_nop 0
	v_xor_b32_e32 v122, 0x80000000, v113
	v_mov_b32_e32 v123, v112
	v_pk_add_f32 v[112:113], v[132:133], v[114:115]
	v_pk_add_f32 v[114:115], v[132:133], v[114:115] neg_lo:[0,1] neg_hi:[0,1]
	v_pk_add_f32 v[132:133], v[108:109], v[122:123]
	v_pk_add_f32 v[108:109], v[108:109], v[122:123] neg_lo:[0,1] neg_hi:[0,1]
	v_pk_add_f32 v[122:123], v[110:111], v[126:127]
	v_pk_add_f32 v[110:111], v[110:111], v[126:127] neg_lo:[0,1] neg_hi:[0,1]
	v_pk_add_f32 v[126:127], v[178:179], v[134:135]
	v_pk_add_f32 v[134:135], v[178:179], v[134:135] neg_lo:[0,1] neg_hi:[0,1]
	s_nop 0
	v_xor_b32_e32 v176, 0x80000000, v135
	v_mov_b32_e32 v177, v134
	v_pk_add_f32 v[134:135], v[122:123], v[126:127]
	v_pk_add_f32 v[122:123], v[122:123], v[126:127] neg_lo:[0,1] neg_hi:[0,1]
	v_pk_add_f32 v[126:127], v[110:111], v[176:177]
	v_pk_add_f32 v[110:111], v[110:111], v[176:177] neg_lo:[0,1] neg_hi:[0,1]
	v_pk_add_f32 v[176:177], v[106:107], v[116:117]
	v_pk_add_f32 v[106:107], v[106:107], v[116:117] neg_lo:[0,1] neg_hi:[0,1]
	v_pk_add_f32 v[116:117], v[130:131], v[124:125]
	v_pk_add_f32 v[124:125], v[130:131], v[124:125] neg_lo:[0,1] neg_hi:[0,1]
	s_nop 0
	v_xor_b32_e32 v130, 0x80000000, v125
	v_mov_b32_e32 v131, v124
	v_pk_add_f32 v[124:125], v[176:177], v[116:117]
	v_pk_add_f32 v[116:117], v[176:177], v[116:117] neg_lo:[0,1] neg_hi:[0,1]
	v_pk_add_f32 v[176:177], v[106:107], v[130:131]
	v_pk_add_f32 v[106:107], v[106:107], v[130:131] neg_lo:[0,1] neg_hi:[0,1]
	v_pk_add_f32 v[130:131], v[104:105], v[120:121]
	v_pk_add_f32 v[104:105], v[104:105], v[120:121] neg_lo:[0,1] neg_hi:[0,1]
	v_pk_add_f32 v[120:121], v[128:129], v[118:119]
	v_pk_add_f32 v[118:119], v[128:129], v[118:119] neg_lo:[0,1] neg_hi:[0,1]
	s_nop 0
	v_xor_b32_e32 v128, 0x80000000, v119
	v_mov_b32_e32 v129, v118
	v_pk_add_f32 v[118:119], v[130:131], v[120:121]
	v_pk_add_f32 v[120:121], v[130:131], v[120:121] neg_lo:[0,1] neg_hi:[0,1]
	v_pk_add_f32 v[130:131], v[104:105], v[128:129]
	v_pk_add_f32 v[104:105], v[104:105], v[128:129] neg_lo:[0,1] neg_hi:[0,1]
	ds_write_b64 v204, v[112:113]
	ds_write_b64 v204, v[134:135] offset:2176
	ds_write_b64 v204, v[124:125] offset:4352
	ds_write_b64 v204, v[118:119] offset:6528
	ds_write_b64 v204, v[132:133] offset:8704
	ds_write_b64 v204, v[126:127] offset:10880
	ds_write_b64 v204, v[176:177] offset:13056
	ds_write_b64 v204, v[130:131] offset:15232
	ds_write_b64 v204, v[114:115] offset:17408
	ds_write_b64 v204, v[122:123] offset:19584
	ds_write_b64 v204, v[116:117] offset:21760
	ds_write_b64 v204, v[120:121] offset:23936
	ds_write_b64 v204, v[108:109] offset:26112
	ds_write_b64 v204, v[110:111] offset:28288
	ds_write_b64 v204, v[106:107] offset:30464
	ds_write_b64 v204, v[104:105] offset:32640
	s_waitcnt lgkmcnt(0)
	s_barrier
	s_and_saveexec_b64 s[18:19], s[48:49]
	s_cbranch_execz .LBB0_276
	ds_read_b64 v[110:111], v154
	ds_read_b64 v[112:113], v154 offset:8
	ds_read_b64 v[106:107], v0
	ds_read_b64 v[114:115], v165 offset:8
	s_waitcnt vmcnt(1)
	v_lshlrev_b32_e32 v105, 16, v2
	v_lshlrev_b32_e32 v104, 16, v162
	v_and_b32_e32 v109, 16, v3
	v_and_b32_e32 v108, 0xffff0000, v2
	s_waitcnt lgkmcnt(0)
	v_mov_b32_e32 v127, v114
	v_mov_b32_e32 v114, v107
	v_mov_b32_e32 v116, v108
	v_pk_mov_b32 v[108:109], v[104:105], v[108:109] op_sel:[1,0]
	v_pk_fma_f32 v[104:105], v[54:55], v[104:105], v[60:61]
	v_mov_b32_e32 v126, v106
	v_pk_mul_f32 v[106:107], v[32:33], v[114:115]
	v_pk_fma_f32 v[104:105], v[56:57], v[108:109], v[104:105]
	v_pk_fma_f32 v[106:107], v[30:31], v[126:127], v[106:107] neg_lo:[0,0,1] neg_hi:[0,0,1]
	v_pk_mov_b32 v[108:109], v[110:111], v[112:113] op_sel:[0,0]
	ds_read_b64 v[118:119], v166 offset:16
	ds_read_b64 v[124:125], v167 offset:24
	v_pk_add_f32 v[108:109], v[108:109], v[106:107]
	s_waitcnt vmcnt(0)
	v_lshlrev_b32_e32 v107, 16, v24
	v_lshlrev_b32_e32 v106, 16, v164
	v_and_b32_e32 v129, 16, v25
	v_and_b32_e32 v128, 0xffff0000, v24
	v_mov_b32_e32 v130, v128
	v_pk_mov_b32 v[128:129], v[106:107], v[128:129] op_sel:[1,0]
	v_pk_fma_f32 v[106:107], v[54:55], v[106:107], v[60:61]
	v_pk_mul_f32 v[126:127], v[32:33], v[126:127]
	ds_read_b64 v[120:121], v154 offset:16
	ds_read_b64 v[122:123], v154 offset:24
	v_pk_fma_f32 v[106:107], v[56:57], v[128:129], v[106:107]
	v_pk_fma_f32 v[114:115], v[30:31], v[114:115], v[126:127]
	ds_read_b64 v[126:127], v154 offset:32
	ds_read_b64 v[128:129], v154 offset:40
	ds_read_b64 v[132:133], v168 offset:32
	ds_read_b64 v[134:135], v169 offset:40
	v_mov_b32_e32 v112, v111
	v_pk_add_f32 v[110:111], v[112:113], v[114:115]
	v_and_b32_e32 v114, 0xffff0000, v3
	v_lshlrev_b32_e32 v177, 16, v4
	v_mov_b32_e32 v176, v114
	v_and_b32_e32 v113, 16, v5
	v_and_b32_e32 v112, 0xffff0000, v4
	s_waitcnt lgkmcnt(6)
	v_mov_b32_e32 v185, v124
	v_mov_b32_e32 v124, v119
	v_mov_b32_e32 v180, v112
	v_pk_mov_b32 v[178:179], v[176:177], v[112:113] op_sel:[1,0]
	v_mov_b32_e32 v184, v118
	v_pk_mul_f32 v[112:113], v[62:63], v[124:125]
	s_waitcnt lgkmcnt(4)
	v_mov_b32_e32 v118, v120
	v_pk_fma_f32 v[112:113], v[34:35], v[184:185], v[112:113] neg_lo:[0,0,1] neg_hi:[0,0,1]
	v_mov_b32_e32 v119, v122
	s_waitcnt lgkmcnt(0)
	v_mov_b32_e32 v189, v134
	v_mov_b32_e32 v134, v133
	v_lshlrev_b32_e32 v117, 16, v3
	v_and_b32_e32 v115, 16, v4
	v_pk_add_f32 v[112:113], v[118:119], v[112:113]
	v_mov_b32_e32 v188, v132
	v_pk_mul_f32 v[118:119], v[66:67], v[134:135]
	v_pk_fma_f32 v[182:183], v[54:55], v[116:117], v[60:61]
	v_pk_mov_b32 v[114:115], v[116:117], v[114:115] op_sel:[1,0]
	v_pk_fma_f32 v[118:119], v[64:65], v[188:189], v[118:119] neg_lo:[0,0,1] neg_hi:[0,0,1]
	v_pk_mov_b32 v[132:133], v[126:127], v[128:129] op_sel:[0,0]
	v_pk_mul_f32 v[184:185], v[62:63], v[184:185]
	v_lshlrev_b32_e32 v131, 16, v25
	v_pk_fma_f32 v[114:115], v[56:57], v[114:115], v[182:183]
	ds_read_b64 v[182:183], v174 offset:48
	ds_read_b64 v[186:187], v175 offset:56
	v_pk_add_f32 v[118:119], v[132:133], v[118:119]
	v_and_b32_e32 v133, 16, v26
	v_and_b32_e32 v132, 0xffff0000, v25
	v_pk_fma_f32 v[124:125], v[34:35], v[124:125], v[184:185]
	v_mov_b32_e32 v122, v121
	v_pk_fma_f32 v[104:105], v[58:59], v[116:117], v[104:105]
	v_pk_fma_f32 v[106:107], v[58:59], v[130:131], v[106:107]
	v_pk_fma_f32 v[116:117], v[58:59], v[176:177], v[114:115]
	v_pk_fma_f32 v[114:115], v[54:55], v[176:177], v[60:61]
	v_pk_fma_f32 v[196:197], v[54:55], v[130:131], v[60:61]
	v_pk_add_f32 v[120:121], v[122:123], v[124:125]
	v_pk_mov_b32 v[122:123], v[130:131], v[132:133] op_sel:[1,0]
	v_pk_mul_f32 v[130:131], v[66:67], v[188:189]
	v_pk_fma_f32 v[114:115], v[56:57], v[178:179], v[114:115]
	ds_read_b64 v[176:177], v154 offset:48
	ds_read_b64 v[178:179], v154 offset:56
	v_pk_fma_f32 v[130:131], v[64:65], v[134:135], v[130:131]
	v_mov_b32_e32 v128, v127
	v_lshlrev_b32_e32 v181, 16, v5
	v_pk_add_f32 v[126:127], v[128:129], v[130:131]
	v_and_b32_e32 v129, 16, v161
	v_and_b32_e32 v128, 0xffff0000, v5
	v_mov_b32_e32 v190, v132
	v_mov_b32_e32 v130, v128
	v_pk_mov_b32 v[128:129], v[180:181], v[128:129] op_sel:[1,0]
	v_pk_fma_f32 v[132:133], v[54:55], v[180:181], v[60:61]
	v_lshlrev_b32_e32 v131, 16, v161
	v_pk_fma_f32 v[128:129], v[56:57], v[128:129], v[132:133]
	s_waitcnt lgkmcnt(2)
	v_mov_b32_e32 v135, v186
	v_mov_b32_e32 v186, v183
	v_pk_fma_f32 v[128:129], v[58:59], v[130:131], v[128:129]
	v_mov_b32_e32 v134, v182
	v_pk_mul_f32 v[130:131], v[70:71], v[186:187]
	v_and_b32_e32 v192, 0xffff0000, v26
	v_pk_fma_f32 v[130:131], v[68:69], v[134:135], v[130:131] neg_lo:[0,0,1] neg_hi:[0,0,1]
	s_waitcnt lgkmcnt(0)
	v_mov_b32_e32 v132, v176
	v_mov_b32_e32 v133, v178
	v_lshlrev_b32_e32 v191, 16, v26
	v_and_b32_e32 v193, 16, v27
	v_lshlrev_b32_e32 v195, 16, v27
	v_mov_b32_e32 v194, v192
	v_pk_fma_f32 v[122:123], v[56:57], v[122:123], v[196:197]
	v_pk_add_f32 v[132:133], v[132:133], v[130:131]
	v_and_b32_e32 v131, 16, v163
	v_and_b32_e32 v130, 0xffff0000, v27
	v_pk_fma_f32 v[114:115], v[58:59], v[180:181], v[114:115]
	v_pk_mov_b32 v[192:193], v[190:191], v[192:193] op_sel:[1,0]
	v_pk_fma_f32 v[124:125], v[58:59], v[190:191], v[122:123]
	v_pk_fma_f32 v[122:123], v[54:55], v[190:191], v[60:61]
	v_mov_b32_e32 v180, v130
	v_pk_mov_b32 v[130:131], v[194:195], v[130:131] op_sel:[1,0]
	v_pk_fma_f32 v[182:183], v[54:55], v[194:195], v[60:61]
	v_pk_mul_f32 v[134:135], v[70:71], v[134:135]
	v_pk_fma_f32 v[122:123], v[56:57], v[192:193], v[122:123]
	v_lshlrev_b32_e32 v181, 16, v163
	v_pk_fma_f32 v[130:131], v[56:57], v[130:131], v[182:183]
	v_pk_fma_f32 v[134:135], v[68:69], v[186:187], v[134:135]
	v_mov_b32_e32 v178, v177
	v_pk_fma_f32 v[122:123], v[58:59], v[194:195], v[122:123]
	v_pk_fma_f32 v[130:131], v[58:59], v[180:181], v[130:131]
	v_pk_add_f32 v[134:135], v[178:179], v[134:135]
	s_andn2_b64 vcc, exec, s[8:9]
	s_mov_b64 s[88:89], -1
	s_cbranch_vccnz .LBB0_302
	s_mov_b64 s[88:89], 0
	v_fma_f32 v108, v6, v8, v108
	v_fma_f32 v109, v6, v9, v109
	v_fma_f32 v112, v6, v10, v112
	v_fma_f32 v113, v6, v11, v113
	v_fma_f32 v118, v6, v12, v118
	v_fma_f32 v119, v6, v13, v119
	v_fma_f32 v132, v6, v14, v132
	v_fma_f32 v133, v6, v15, v133
	v_fma_f32 v110, v6, v16, v110
	v_fma_f32 v111, v6, v17, v111
	v_fma_f32 v120, v6, v18, v120
	v_fma_f32 v121, v6, v19, v121
	v_fma_f32 v126, v6, v20, v126
	v_fma_f32 v127, v6, v21, v127
	v_fma_f32 v134, v6, v22, v134
	v_fma_f32 v135, v6, v23, v135
	v_mul_f32_e32 v108, v104, v108
	v_mul_f32_e32 v109, v105, v109
	v_mul_f32_e32 v112, v116, v112
	v_mul_f32_e32 v113, v117, v113
	v_mul_f32_e32 v118, v114, v118
	v_mul_f32_e32 v119, v115, v119
	v_mul_f32_e32 v132, v128, v132
	v_mul_f32_e32 v133, v129, v133
	v_mul_f32_e32 v110, v106, v110
	v_mul_f32_e32 v111, v107, v111
	v_mul_f32_e32 v120, v124, v120
	v_mul_f32_e32 v121, v125, v121
	v_mul_f32_e32 v126, v122, v126
	v_mul_f32_e32 v127, v123, v127
	v_mul_f32_e32 v134, v130, v134
	v_mul_f32_e32 v135, v131, v135
	v_cvt_pk_bf16_f32 v8, v108, v109
	v_cvt_pk_bf16_f32 v9, v112, v113
	v_cvt_pk_bf16_f32 v10, v118, v119
	v_cvt_pk_bf16_f32 v11, v132, v133
	v_cvt_pk_bf16_f32 v12, v110, v111
	v_cvt_pk_bf16_f32 v13, v120, v121
	v_cvt_pk_bf16_f32 v14, v126, v127
	v_cvt_pk_bf16_f32 v15, v134, v135
	s_mul_i32 s36, s2, 0x11000
	s_add_u32 s36, s36, 0x6d00000
	s_add_u32 s36, s64, s36
	s_addc_u32 s37, s65, 0
	v_add_u32_e32 v176, s14, v44
	v_lshlrev_b32_e32 v176, 1, v176
	v_add_u32_e32 v177, 0x2000, v176
	global_store_dwordx4 v176, v[8:11], s[36:37]
	global_store_dwordx4 v177, v[12:15], s[36:37]

.LBB0_350:
	s_or_b64 exec, exec, s[10:11]
	v_cmp_gt_i32_e32 vcc, 8, v50
	s_and_saveexec_b64 s[10:11], vcc
	v_add_u32_e32 v50, 0x18800, v51
	ds_write_b32 v50, v1
	s_or_b64 exec, exec, s[10:11]
	s_bfe_i32 s10, s18, 0x10000
	s_and_b32 s12, s10, 40
	s_mul_i32 s10, s14, 0x1900
	v_add_u32_e32 v50, s12, v236
	s_add_i32 s13, s10, 0
	s_mul_i32 s10, s14, 0x300
	v_mul_u32_u24_e32 v50, 0xc0, v50
	s_add_i32 s10, s10, 0
	s_lshl_b32 s18, s12, 2
	v_add3_u32 v118, 0, v50, v0
	s_add_i32 s19, s10, s18
	s_waitcnt lgkmcnt(0)
	s_barrier
	ds_read_b128 v[50:53], v118
	ds_read_b128 v[54:57], v118 offset:64
	ds_read_b128 v[58:61], v118 offset:18496
	ds_read_b128 v[62:65], v118 offset:18560
	ds_read_b128 v[66:69], v118 offset:128
	ds_read_b128 v[70:73], v118 offset:3072
	ds_read_b128 v[74:77], v118 offset:21504
	ds_read_b128 v[78:81], v118 offset:21568
	ds_read_b128 v[82:85], v118 offset:3136
	ds_read_b128 v[86:89], v118 offset:3200
	ds_read_b128 v[90:93], v118 offset:21632
	ds_read_b128 v[94:97], v118 offset:24576
	ds_read_b128 v[98:101], v118 offset:6144
	ds_read_b128 v[102:105], v118 offset:6208
	ds_read_b128 v[106:109], v118 offset:18432
	ds_read_b128 v[110:113], v118 offset:6272
	ds_read_b128 v[114:117], v118 offset:24640
	ds_read_b128 v[118:121], v118 offset:24704
	s_and_b64 s[10:11], s[44:45], exec
	s_cselect_b32 s10, s59, 0x11c00000
	s_add_u32 s36, s64, s10
	s_addc_u32 s37, s65, 0
	s_lshl_b32 s40, s17, 12
	s_add_i32 s17, s14, -1
	v_mov_b32_e32 v124, s13
	s_movk_i32 s10, 0x190
	s_cmp_lt_u32 s16, 64
	v_mad_u32_u24 v124, v236, s10, v124
	s_cselect_b64 s[10:11], -1, 0
	v_lshl_add_u32 v125, v122, 2, s12
	s_and_b64 s[12:13], s[10:11], exec
	s_cselect_b32 s12, 7, s17
	s_lshl_b32 s13, s12, 2
	s_add_i32 s89, 0, 0x18800
	s_add_i32 s41, s89, s13
	s_mulk_i32 s12, 0x180
	v_readlane_b32 s13, v254, 60
	s_add_i32 s12, s13, s12
	s_add_i32 s12, s12, s18
	v_add_u32_e32 v238, s12, v0
	s_mul_i32 s12, s14, 0x180
	s_add_i32 s12, s13, s12
	s_add_i32 s12, s12, s18
	v_add_u32_e32 v240, s12, v0
	s_lshl_b32 s12, s14, 2
	s_add_i32 s19, s19, 0x18900
	s_add_i32 s89, s89, s12
	v_lshlrev_b32_e32 v0, 2, v237
	s_add_u32 s12, s36, s15
	v_add_u32_e32 v241, 0, v0
	v_add_u32_e32 v242, v124, v0
	v_lshlrev_b32_e32 v0, 2, v125
	s_addc_u32 s13, s37, 0
	v_add_u32_e32 v243, 0, v0
	v_add_u32_e32 v244, v124, v0
	v_lshlrev_b32_e32 v0, 1, v125
	v_mov_b32_e32 v178, 0
	v_lshl_add_u32 v239, v122, 4, s19
	v_cmp_eq_u32_e64 s[46:47], 15, v236
	v_cmp_eq_u32_e64 s[48:49], 0, v123
	v_cmp_ne_u32_e64 s[50:51], 3, v122
	v_lshl_add_u64 v[176:177], s[12:13], 0, v[0:1]
	v_mov_b32_e32 v245, 0
	s_mov_b32 s94, 0
	v_mov_b32_e32 v179, v178
	v_mov_b32_e32 v180, v178
	v_mov_b32_e32 v181, v178
	v_pk_mov_b32 v[182:183], v[178:179], v[178:179] op_sel:[0,0]
	v_pk_mov_b32 v[184:185], v[178:179], v[178:179] op_sel:[0,0]
	v_pk_mov_b32 v[186:187], v[178:179], v[178:179] op_sel:[0,0]
	v_pk_mov_b32 v[188:189], v[178:179], v[178:179] op_sel:[0,0]
	v_pk_mov_b32 v[190:191], v[178:179], v[178:179] op_sel:[0,0]
	v_pk_mov_b32 v[192:193], v[178:179], v[178:179] op_sel:[0,0]
	v_pk_mov_b32 v[194:195], v[178:179], v[178:179] op_sel:[0,0]
	v_pk_mov_b32 v[196:197], v[178:179], v[178:179] op_sel:[0,0]
	v_pk_mov_b32 v[198:199], v[178:179], v[178:179] op_sel:[0,0]
	v_pk_mov_b32 v[200:201], v[178:179], v[178:179] op_sel:[0,0]
	s_branch .LBB0_355
.LBB0_353:
	s_or_b64 exec, exec, s[12:13]
	v_mov_b32_e32 v245, v246
	v_mov_b32_e32 v178, v122
	v_mov_b32_e32 v179, v123
	v_pk_mov_b32 v[180:181], v[124:125], v[124:125] op_sel:[0,1]
	v_pk_mov_b32 v[182:183], v[138:139], v[138:139] op_sel:[0,1]
	v_pk_mov_b32 v[184:185], v[140:141], v[140:141] op_sel:[0,1]
	v_pk_mov_b32 v[186:187], v[134:135], v[134:135] op_sel:[0,1]
	v_pk_mov_b32 v[188:189], v[136:137], v[136:137] op_sel:[0,1]
	v_pk_mov_b32 v[190:191], v[126:127], v[126:127] op_sel:[0,1]
	v_pk_mov_b32 v[192:193], v[128:129], v[128:129] op_sel:[0,1]
	v_pk_mov_b32 v[194:195], v[142:143], v[142:143] op_sel:[0,1]
	v_pk_mov_b32 v[196:197], v[144:145], v[144:145] op_sel:[0,1]
	v_pk_mov_b32 v[198:199], v[130:131], v[130:131] op_sel:[0,1]
	v_pk_mov_b32 v[200:201], v[132:133], v[132:133] op_sel:[0,1]

.LBB0_405:
	v_mov_b32_e32 v157, 0
	v_mov_b32_e32 v156, v157
	v_pk_mov_b32 v[154:155], v[156:157], v[156:157] op_sel:[1,1]
	v_pk_mov_b32 v[152:153], v[156:157], v[156:157] op_sel:[1,1]
	v_pk_mov_b32 v[150:151], v[156:157], v[156:157] op_sel:[1,1]
	v_pk_mov_b32 v[148:149], v[156:157], v[156:157] op_sel:[1,1]
	v_pk_mov_b32 v[146:147], v[156:157], v[156:157] op_sel:[1,1]
